# v083 + back-edge rotation (asm guide 7.11, SALU part): loop counter / pointer bumps / exit compare moved in front of the loop-back s_barrier in all ten K-loops
# baseline (speedup 1.0000x reference)
.LBB0_241:
	s_add_u32 s94, s26, s92
	s_addc_u32 s95, s27, s93
	s_add_u32 s94, s94, 0x100
	s_addc_u32 s95, s95, 0
	s_add_u32 vcc_lo, s41, s92
	s_addc_u32 vcc_hi, s44, s93
	s_add_i32 s43, 0, 0x10000
	v_add_u32_e32 v152, s43, v171
	ds_read_b128 v[132:135], v152
	ds_read_b128 v[136:139], v152 offset:1024
	ds_read_b128 v[140:143], v152 offset:2048
	ds_read_b128 v[166:169], v152 offset:3072
	v_add_u32_e32 v152, s8, v171
	ds_read_b128 v[178:181], v152
	ds_read_b128 v[182:185], v152 offset:1024
	ds_read_b128 v[186:189], v152 offset:2048
	ds_read_b128 v[190:193], v152 offset:3072
	s_cmpk_eq_i32 s92, 0xf00
	s_cselect_b32 s97, s45, s95
	s_cselect_b32 s96, s50, s94
	s_cselect_b32 s95, s51, vcc_hi
	s_cselect_b32 s94, s81, vcc_lo
	v_lshl_add_u64 v[226:227], v[128:129], 0, s[92:93]
	s_add_i32 m0, s21, 0xc000
	ds_read_b128 v[194:197], v173
	ds_read_b128 v[198:201], v173 offset:1024
	ds_read_b128 v[202:205], v173 offset:2048
	ds_read_b128 v[206:209], v173 offset:3072
	ds_read_b128 v[210:213], v173 offset:4096
	ds_read_b128 v[214:217], v173 offset:5120
	ds_read_b128 v[218:221], v173 offset:6144
	ds_read_b128 v[222:225], v173 offset:7168
	global_load_lds_dwordx4 v[226:227], off
	v_lshl_add_u64 v[226:227], v[130:131], 0, s[92:93]
	s_add_i32 m0, s21, 0xe000
	s_nop 0
	global_load_lds_dwordx4 v[226:227], off
	s_waitcnt vmcnt(8)
	s_waitcnt lgkmcnt(0)
	s_barrier
	s_setprio 1
	s_waitcnt lgkmcnt(0)
	v_mfma_f32_16x16x32_bf16 v[124:127], v[132:135], v[194:197], v[124:127]
	v_mfma_f32_16x16x32_bf16 v[124:127], v[136:139], v[198:201], v[124:127]
	v_mfma_f32_16x16x32_bf16 v[120:123], v[140:143], v[194:197], v[120:123]
	v_mfma_f32_16x16x32_bf16 v[120:123], v[166:169], v[198:201], v[120:123]
	v_mfma_f32_16x16x32_bf16 v[116:119], v[132:135], v[202:205], v[116:119]
	v_mfma_f32_16x16x32_bf16 v[116:119], v[136:139], v[206:209], v[116:119]
	v_mfma_f32_16x16x32_bf16 v[112:115], v[140:143], v[202:205], v[112:115]
	v_mfma_f32_16x16x32_bf16 v[112:115], v[166:169], v[206:209], v[112:115]
	v_mfma_f32_16x16x32_bf16 v[108:111], v[132:135], v[210:213], v[108:111]
	v_mfma_f32_16x16x32_bf16 v[108:111], v[136:139], v[214:217], v[108:111]
	v_mfma_f32_16x16x32_bf16 v[104:107], v[140:143], v[210:213], v[104:107]
	v_mfma_f32_16x16x32_bf16 v[104:107], v[166:169], v[214:217], v[104:107]
	v_mfma_f32_16x16x32_bf16 v[100:103], v[132:135], v[218:221], v[100:103]
	v_mfma_f32_16x16x32_bf16 v[100:103], v[136:139], v[222:225], v[100:103]
	v_mfma_f32_16x16x32_bf16 v[96:99], v[140:143], v[218:221], v[96:99]
	v_mfma_f32_16x16x32_bf16 v[96:99], v[166:169], v[222:225], v[96:99]
	s_setprio 0
	s_setprio 1
	v_mfma_f32_16x16x32_bf16 v[92:95], v[178:181], v[194:197], v[92:95]
	v_mfma_f32_16x16x32_bf16 v[92:95], v[182:185], v[198:201], v[92:95]
	v_mfma_f32_16x16x32_bf16 v[88:91], v[186:189], v[194:197], v[88:91]
	v_mfma_f32_16x16x32_bf16 v[88:91], v[190:193], v[198:201], v[88:91]
	v_mfma_f32_16x16x32_bf16 v[84:87], v[178:181], v[202:205], v[84:87]
	v_mfma_f32_16x16x32_bf16 v[84:87], v[182:185], v[206:209], v[84:87]
	v_mfma_f32_16x16x32_bf16 v[80:83], v[186:189], v[202:205], v[80:83]
	v_mfma_f32_16x16x32_bf16 v[80:83], v[190:193], v[206:209], v[80:83]
	v_mfma_f32_16x16x32_bf16 v[76:79], v[178:181], v[210:213], v[76:79]
	v_mfma_f32_16x16x32_bf16 v[76:79], v[182:185], v[214:217], v[76:79]
	v_mfma_f32_16x16x32_bf16 v[72:75], v[186:189], v[210:213], v[72:75]
	v_mfma_f32_16x16x32_bf16 v[72:75], v[190:193], v[214:217], v[72:75]
	v_mfma_f32_16x16x32_bf16 v[68:71], v[178:181], v[218:221], v[68:71]
	v_mfma_f32_16x16x32_bf16 v[68:71], v[182:185], v[222:225], v[68:71]
	v_mfma_f32_16x16x32_bf16 v[64:67], v[186:189], v[218:221], v[64:67]
	v_mfma_f32_16x16x32_bf16 v[64:67], v[190:193], v[222:225], v[64:67]
	s_setprio 0
	s_barrier
	s_add_i32 s43, s43, s17
	s_add_u32 s98, s94, s70
	s_addc_u32 s99, s95, s71
	s_mov_b32 m0, s43
	ds_read_b128 v[194:197], v173 offset:16384
	ds_read_b128 v[198:201], v173 offset:17408
	ds_read_b128 v[202:205], v173 offset:18432
	ds_read_b128 v[206:209], v173 offset:19456
	ds_read_b128 v[210:213], v173 offset:20480
	ds_read_b128 v[214:217], v173 offset:21504
	ds_read_b128 v[218:221], v173 offset:22528
	ds_read_b128 v[222:225], v173 offset:23552
	global_load_lds_dwordx4 v146, s[94:95]
	s_add_i32 m0, s43, 0x2000
	s_add_u32 vcc_lo, s94, 0x80000
	s_addc_u32 vcc_hi, s95, 0
	s_add_i32 s43, s8, s17
	global_load_lds_dwordx4 v150, s[94:95]
	s_mov_b32 m0, s43
	s_nop 0
	global_load_lds_dwordx4 v146, vcc
	s_add_i32 m0, s43, 0x2000
	s_nop 0
	global_load_lds_dwordx4 v150, vcc
	s_add_u32 s100, s96, s70
	s_addc_u32 s101, s97, s71
	s_mov_b32 m0, s21
	s_nop 0
	global_load_lds_dwordx4 v144, s[96:97]
	s_mov_b32 m0, s39
	s_nop 0
	global_load_lds_dwordx4 v148, s[96:97]
	s_waitcnt vmcnt(8)
	s_waitcnt lgkmcnt(0)
	s_barrier
	s_setprio 1
	s_waitcnt lgkmcnt(0)
	v_mfma_f32_16x16x32_bf16 v[60:63], v[132:135], v[194:197], v[60:63]
	v_mfma_f32_16x16x32_bf16 v[60:63], v[136:139], v[198:201], v[60:63]
	v_mfma_f32_16x16x32_bf16 v[56:59], v[140:143], v[194:197], v[56:59]
	v_mfma_f32_16x16x32_bf16 v[56:59], v[166:169], v[198:201], v[56:59]
	v_mfma_f32_16x16x32_bf16 v[52:55], v[132:135], v[202:205], v[52:55]
	v_mfma_f32_16x16x32_bf16 v[52:55], v[136:139], v[206:209], v[52:55]
	v_mfma_f32_16x16x32_bf16 v[48:51], v[140:143], v[202:205], v[48:51]
	v_mfma_f32_16x16x32_bf16 v[48:51], v[166:169], v[206:209], v[48:51]
	v_mfma_f32_16x16x32_bf16 v[44:47], v[132:135], v[210:213], v[44:47]
	v_mfma_f32_16x16x32_bf16 v[44:47], v[136:139], v[214:217], v[44:47]
	v_mfma_f32_16x16x32_bf16 v[40:43], v[140:143], v[210:213], v[40:43]
	v_mfma_f32_16x16x32_bf16 v[40:43], v[166:169], v[214:217], v[40:43]
	v_mfma_f32_16x16x32_bf16 v[36:39], v[132:135], v[218:221], v[36:39]
	v_mfma_f32_16x16x32_bf16 v[36:39], v[136:139], v[222:225], v[36:39]
	v_mfma_f32_16x16x32_bf16 v[32:35], v[140:143], v[218:221], v[32:35]
	v_mfma_f32_16x16x32_bf16 v[32:35], v[166:169], v[222:225], v[32:35]
	s_setprio 0
	s_setprio 1
	v_mfma_f32_16x16x32_bf16 v[28:31], v[178:181], v[194:197], v[28:31]
	v_mfma_f32_16x16x32_bf16 v[28:31], v[182:185], v[198:201], v[28:31]
	v_mfma_f32_16x16x32_bf16 v[24:27], v[186:189], v[194:197], v[24:27]
	v_mfma_f32_16x16x32_bf16 v[24:27], v[190:193], v[198:201], v[24:27]
	v_mfma_f32_16x16x32_bf16 v[20:23], v[178:181], v[202:205], v[20:23]
	v_mfma_f32_16x16x32_bf16 v[20:23], v[182:185], v[206:209], v[20:23]
	v_mfma_f32_16x16x32_bf16 v[16:19], v[186:189], v[202:205], v[16:19]
	v_mfma_f32_16x16x32_bf16 v[16:19], v[190:193], v[206:209], v[16:19]
	v_mfma_f32_16x16x32_bf16 v[12:15], v[178:181], v[210:213], v[12:15]
	v_mfma_f32_16x16x32_bf16 v[12:15], v[182:185], v[214:217], v[12:15]
	v_mfma_f32_16x16x32_bf16 v[8:11], v[186:189], v[210:213], v[8:11]
	v_mfma_f32_16x16x32_bf16 v[8:11], v[190:193], v[214:217], v[8:11]
	v_mfma_f32_16x16x32_bf16 v[4:7], v[178:181], v[218:221], v[4:7]
	v_mfma_f32_16x16x32_bf16 v[4:7], v[182:185], v[222:225], v[4:7]
	v_mfma_f32_16x16x32_bf16 v[0:3], v[186:189], v[218:221], v[0:3]
	v_mfma_f32_16x16x32_bf16 v[0:3], v[190:193], v[222:225], v[0:3]
	s_setprio 0
	s_barrier
	s_add_i32 s43, 0, 0x18000
	v_add_u32_e32 v152, s43, v171
	s_add_i32 vcc_lo, 0, 0x1c000
	ds_read_b128 v[132:135], v152
	ds_read_b128 v[136:139], v152 offset:1024
	ds_read_b128 v[140:143], v152 offset:2048
	ds_read_b128 v[166:169], v152 offset:3072
	v_add_u32_e32 v152, vcc_lo, v171
	ds_read_b128 v[178:181], v152
	ds_read_b128 v[182:185], v152 offset:1024
	ds_read_b128 v[186:189], v152 offset:2048
	ds_read_b128 v[190:193], v152 offset:3072
	s_add_u32 s96, s96, 0x80000
	s_addc_u32 s97, s97, 0
	s_mov_b32 m0, s6
	ds_read_b128 v[194:197], v173 offset:32768
	ds_read_b128 v[198:201], v173 offset:33792
	ds_read_b128 v[202:205], v173 offset:34816
	ds_read_b128 v[206:209], v173 offset:35840
	ds_read_b128 v[210:213], v173 offset:36864
	ds_read_b128 v[214:217], v173 offset:37888
	ds_read_b128 v[218:221], v173 offset:38912
	ds_read_b128 v[222:225], v173 offset:39936
	global_load_lds_dwordx4 v144, s[96:97]
	s_mov_b32 m0, s10
	s_nop 0
	global_load_lds_dwordx4 v148, s[96:97]
	s_waitcnt vmcnt(8)
	s_waitcnt lgkmcnt(0)
	s_barrier
	s_setprio 1
	s_waitcnt lgkmcnt(0)
	v_mfma_f32_16x16x32_bf16 v[124:127], v[132:135], v[194:197], v[124:127]
	v_mfma_f32_16x16x32_bf16 v[124:127], v[136:139], v[198:201], v[124:127]
	v_mfma_f32_16x16x32_bf16 v[120:123], v[140:143], v[194:197], v[120:123]
	v_mfma_f32_16x16x32_bf16 v[120:123], v[166:169], v[198:201], v[120:123]
	v_mfma_f32_16x16x32_bf16 v[116:119], v[132:135], v[202:205], v[116:119]
	v_mfma_f32_16x16x32_bf16 v[116:119], v[136:139], v[206:209], v[116:119]
	v_mfma_f32_16x16x32_bf16 v[112:115], v[140:143], v[202:205], v[112:115]
	v_mfma_f32_16x16x32_bf16 v[112:115], v[166:169], v[206:209], v[112:115]
	v_mfma_f32_16x16x32_bf16 v[108:111], v[132:135], v[210:213], v[108:111]
	v_mfma_f32_16x16x32_bf16 v[108:111], v[136:139], v[214:217], v[108:111]
	v_mfma_f32_16x16x32_bf16 v[104:107], v[140:143], v[210:213], v[104:107]
	v_mfma_f32_16x16x32_bf16 v[104:107], v[166:169], v[214:217], v[104:107]
	v_mfma_f32_16x16x32_bf16 v[100:103], v[132:135], v[218:221], v[100:103]
	v_mfma_f32_16x16x32_bf16 v[100:103], v[136:139], v[222:225], v[100:103]
	v_mfma_f32_16x16x32_bf16 v[96:99], v[140:143], v[218:221], v[96:99]
	v_mfma_f32_16x16x32_bf16 v[96:99], v[166:169], v[222:225], v[96:99]
	s_setprio 0
	s_setprio 1
	v_mfma_f32_16x16x32_bf16 v[92:95], v[178:181], v[194:197], v[92:95]
	v_mfma_f32_16x16x32_bf16 v[92:95], v[182:185], v[198:201], v[92:95]
	v_mfma_f32_16x16x32_bf16 v[88:91], v[186:189], v[194:197], v[88:91]
	v_mfma_f32_16x16x32_bf16 v[88:91], v[190:193], v[198:201], v[88:91]
	v_mfma_f32_16x16x32_bf16 v[84:87], v[178:181], v[202:205], v[84:87]
	v_mfma_f32_16x16x32_bf16 v[84:87], v[182:185], v[206:209], v[84:87]
	v_mfma_f32_16x16x32_bf16 v[80:83], v[186:189], v[202:205], v[80:83]
	v_mfma_f32_16x16x32_bf16 v[80:83], v[190:193], v[206:209], v[80:83]
	v_mfma_f32_16x16x32_bf16 v[76:79], v[178:181], v[210:213], v[76:79]
	v_mfma_f32_16x16x32_bf16 v[76:79], v[182:185], v[214:217], v[76:79]
	v_mfma_f32_16x16x32_bf16 v[72:75], v[186:189], v[210:213], v[72:75]
	v_mfma_f32_16x16x32_bf16 v[72:75], v[190:193], v[214:217], v[72:75]
	v_mfma_f32_16x16x32_bf16 v[68:71], v[178:181], v[218:221], v[68:71]
	v_mfma_f32_16x16x32_bf16 v[68:71], v[182:185], v[222:225], v[68:71]
	v_mfma_f32_16x16x32_bf16 v[64:67], v[186:189], v[218:221], v[64:67]
	v_mfma_f32_16x16x32_bf16 v[64:67], v[190:193], v[222:225], v[64:67]
	s_setprio 0
	s_barrier
	s_add_i32 s43, s43, s17
	s_mov_b32 m0, s43
	ds_read_b128 v[194:197], v173 offset:49152
	ds_read_b128 v[198:201], v173 offset:50176
	ds_read_b128 v[202:205], v173 offset:51200
	ds_read_b128 v[206:209], v173 offset:52224
	ds_read_b128 v[210:213], v173 offset:53248
	ds_read_b128 v[214:217], v173 offset:54272
	ds_read_b128 v[218:221], v173 offset:55296
	ds_read_b128 v[222:225], v173 offset:56320
	global_load_lds_dwordx4 v146, s[98:99]
	s_add_i32 m0, s43, 0x2000
	s_add_u32 s94, s94, 0x80080
	s_addc_u32 s95, s95, 0
	s_add_i32 s43, vcc_lo, s17
	global_load_lds_dwordx4 v150, s[98:99]
	s_mov_b32 m0, s43
	s_nop 0
	global_load_lds_dwordx4 v146, s[94:95]
	s_add_i32 m0, s43, 0x2000
	s_nop 0
	global_load_lds_dwordx4 v150, s[94:95]
	s_mov_b32 m0, s33
	s_nop 0
	global_load_lds_dwordx4 v144, s[100:101]
	s_mov_b32 m0, s7
	s_nop 0
	global_load_lds_dwordx4 v148, s[100:101]
	s_waitcnt vmcnt(8)
	s_waitcnt lgkmcnt(0)
	s_barrier
	s_setprio 1
	s_waitcnt lgkmcnt(0)
	v_mfma_f32_16x16x32_bf16 v[60:63], v[132:135], v[194:197], v[60:63]
	v_mfma_f32_16x16x32_bf16 v[60:63], v[136:139], v[198:201], v[60:63]
	v_mfma_f32_16x16x32_bf16 v[56:59], v[140:143], v[194:197], v[56:59]
	v_mfma_f32_16x16x32_bf16 v[56:59], v[166:169], v[198:201], v[56:59]
	v_mfma_f32_16x16x32_bf16 v[52:55], v[132:135], v[202:205], v[52:55]
	v_mfma_f32_16x16x32_bf16 v[52:55], v[136:139], v[206:209], v[52:55]
	v_mfma_f32_16x16x32_bf16 v[48:51], v[140:143], v[202:205], v[48:51]
	v_mfma_f32_16x16x32_bf16 v[48:51], v[166:169], v[206:209], v[48:51]
	v_mfma_f32_16x16x32_bf16 v[44:47], v[132:135], v[210:213], v[44:47]
	v_mfma_f32_16x16x32_bf16 v[44:47], v[136:139], v[214:217], v[44:47]
	v_mfma_f32_16x16x32_bf16 v[40:43], v[140:143], v[210:213], v[40:43]
	v_mfma_f32_16x16x32_bf16 v[40:43], v[166:169], v[214:217], v[40:43]
	v_mfma_f32_16x16x32_bf16 v[36:39], v[132:135], v[218:221], v[36:39]
	v_mfma_f32_16x16x32_bf16 v[36:39], v[136:139], v[222:225], v[36:39]
	v_mfma_f32_16x16x32_bf16 v[32:35], v[140:143], v[218:221], v[32:35]
	v_mfma_f32_16x16x32_bf16 v[32:35], v[166:169], v[222:225], v[32:35]
	s_setprio 0
	s_setprio 1
	v_mfma_f32_16x16x32_bf16 v[28:31], v[178:181], v[194:197], v[28:31]
	v_mfma_f32_16x16x32_bf16 v[28:31], v[182:185], v[198:201], v[28:31]
	v_mfma_f32_16x16x32_bf16 v[24:27], v[186:189], v[194:197], v[24:27]
	v_mfma_f32_16x16x32_bf16 v[24:27], v[190:193], v[198:201], v[24:27]
	v_mfma_f32_16x16x32_bf16 v[20:23], v[178:181], v[202:205], v[20:23]
	v_mfma_f32_16x16x32_bf16 v[20:23], v[182:185], v[206:209], v[20:23]
	v_mfma_f32_16x16x32_bf16 v[16:19], v[186:189], v[202:205], v[16:19]
	v_mfma_f32_16x16x32_bf16 v[16:19], v[190:193], v[206:209], v[16:19]
	v_mfma_f32_16x16x32_bf16 v[12:15], v[178:181], v[210:213], v[12:15]
	v_mfma_f32_16x16x32_bf16 v[12:15], v[182:185], v[214:217], v[12:15]
	v_mfma_f32_16x16x32_bf16 v[8:11], v[186:189], v[210:213], v[8:11]
	v_mfma_f32_16x16x32_bf16 v[8:11], v[190:193], v[214:217], v[8:11]
	v_mfma_f32_16x16x32_bf16 v[4:7], v[178:181], v[218:221], v[4:7]
	v_mfma_f32_16x16x32_bf16 v[4:7], v[182:185], v[222:225], v[4:7]
	v_mfma_f32_16x16x32_bf16 v[0:3], v[186:189], v[218:221], v[0:3]
	v_mfma_f32_16x16x32_bf16 v[0:3], v[190:193], v[222:225], v[0:3]
	s_setprio 0
	s_add_i32 s83, s83, 2
	s_add_u32 s92, s92, 0x100
	s_addc_u32 s93, s93, 0
	s_cmp_gt_u32 s83, 29
	s_barrier
	s_cbranch_scc0 .LBB0_241
	s_and_b64 vcc, exec, s[72:73]
	s_cbranch_vccz .LBB0_244
	s_barrier

.LBB0_273:
	ds_read_b128 v[146:149], v141
	ds_read_b128 v[150:153], v141 offset:1024
	ds_read_b128 v[154:157], v141 offset:2048
	ds_read_b128 v[158:161], v141 offset:3072
	ds_read_b128 v[162:165], v142
	ds_read_b128 v[166:169], v142 offset:1024
	ds_read_b128 v[170:173], v142 offset:2048
	ds_read_b128 v[176:179], v142 offset:3072
	s_add_u32 s48, s46, 0xfff80080
	s_addc_u32 s49, s47, -1
	s_cmp_eq_u32 s80, 4
	s_cselect_b32 s69, s39, s49
	s_cselect_b32 s68, s38, s48
	s_cselect_b32 s49, s43, s79
	s_cselect_b32 s48, s42, s27
	s_add_i32 m0, s10, 0xc000
	ds_read_b128 v[180:183], v143
	ds_read_b128 v[184:187], v143 offset:1024
	ds_read_b128 v[188:191], v143 offset:2048
	ds_read_b128 v[192:195], v143 offset:3072
	ds_read_b128 v[196:199], v143 offset:4096
	ds_read_b128 v[200:203], v143 offset:5120
	ds_read_b128 v[204:207], v143 offset:6144
	ds_read_b128 v[208:211], v143 offset:7168
	global_load_lds_dwordx4 v136, s[46:47]
	s_add_i32 m0, s10, 0xe000
	s_nop 0
	global_load_lds_dwordx4 v138, s[46:47]
	s_waitcnt vmcnt(8)
	s_waitcnt lgkmcnt(0)
	s_barrier
	s_setprio 1
	s_waitcnt lgkmcnt(0)
	v_mfma_f32_16x16x32_bf16 v[124:127], v[146:149], v[180:183], v[124:127]
	v_mfma_f32_16x16x32_bf16 v[124:127], v[150:153], v[184:187], v[124:127]
	v_mfma_f32_16x16x32_bf16 v[120:123], v[154:157], v[180:183], v[120:123]
	v_mfma_f32_16x16x32_bf16 v[120:123], v[158:161], v[184:187], v[120:123]
	v_mfma_f32_16x16x32_bf16 v[116:119], v[146:149], v[188:191], v[116:119]
	v_mfma_f32_16x16x32_bf16 v[116:119], v[150:153], v[192:195], v[116:119]
	v_mfma_f32_16x16x32_bf16 v[112:115], v[154:157], v[188:191], v[112:115]
	v_mfma_f32_16x16x32_bf16 v[112:115], v[158:161], v[192:195], v[112:115]
	v_mfma_f32_16x16x32_bf16 v[100:103], v[146:149], v[196:199], v[100:103]
	v_mfma_f32_16x16x32_bf16 v[100:103], v[150:153], v[200:203], v[100:103]
	v_mfma_f32_16x16x32_bf16 v[96:99], v[154:157], v[196:199], v[96:99]
	v_mfma_f32_16x16x32_bf16 v[96:99], v[158:161], v[200:203], v[96:99]
	v_mfma_f32_16x16x32_bf16 v[84:87], v[146:149], v[204:207], v[84:87]
	v_mfma_f32_16x16x32_bf16 v[84:87], v[150:153], v[208:211], v[84:87]
	v_mfma_f32_16x16x32_bf16 v[80:83], v[154:157], v[204:207], v[80:83]
	v_mfma_f32_16x16x32_bf16 v[80:83], v[158:161], v[208:211], v[80:83]
	s_setprio 0
	s_setprio 1
	v_mfma_f32_16x16x32_bf16 v[108:111], v[162:165], v[180:183], v[108:111]
	v_mfma_f32_16x16x32_bf16 v[108:111], v[166:169], v[184:187], v[108:111]
	v_mfma_f32_16x16x32_bf16 v[104:107], v[170:173], v[180:183], v[104:107]
	v_mfma_f32_16x16x32_bf16 v[104:107], v[176:179], v[184:187], v[104:107]
	v_mfma_f32_16x16x32_bf16 v[92:95], v[162:165], v[188:191], v[92:95]
	v_mfma_f32_16x16x32_bf16 v[92:95], v[166:169], v[192:195], v[92:95]
	v_mfma_f32_16x16x32_bf16 v[88:91], v[170:173], v[188:191], v[88:91]
	v_mfma_f32_16x16x32_bf16 v[88:91], v[176:179], v[192:195], v[88:91]
	v_mfma_f32_16x16x32_bf16 v[76:79], v[162:165], v[196:199], v[76:79]
	v_mfma_f32_16x16x32_bf16 v[76:79], v[166:169], v[200:203], v[76:79]
	v_mfma_f32_16x16x32_bf16 v[72:75], v[170:173], v[196:199], v[72:75]
	v_mfma_f32_16x16x32_bf16 v[72:75], v[176:179], v[200:203], v[72:75]
	v_mfma_f32_16x16x32_bf16 v[68:71], v[162:165], v[204:207], v[68:71]
	v_mfma_f32_16x16x32_bf16 v[68:71], v[166:169], v[208:211], v[68:71]
	v_mfma_f32_16x16x32_bf16 v[64:67], v[170:173], v[204:207], v[64:67]
	v_mfma_f32_16x16x32_bf16 v[64:67], v[176:179], v[208:211], v[64:67]
	s_setprio 0
	s_barrier
	s_add_i32 s81, s45, s6
	s_add_u32 s98, s48, s16
	s_addc_u32 s99, s49, s17
	s_mov_b32 m0, s81
	ds_read_b128 v[180:183], v143 offset:16384
	ds_read_b128 v[184:187], v143 offset:17408
	ds_read_b128 v[188:191], v143 offset:18432
	ds_read_b128 v[192:195], v143 offset:19456
	ds_read_b128 v[196:199], v143 offset:20480
	ds_read_b128 v[200:203], v143 offset:21504
	ds_read_b128 v[204:207], v143 offset:22528
	ds_read_b128 v[208:211], v143 offset:23552
	global_load_lds_dwordx4 v132, s[48:49]
	s_add_i32 m0, s81, 0x2000
	s_add_u32 s82, s48, 0x80000
	s_addc_u32 s83, s49, 0
	s_add_i32 s81, s50, s6
	global_load_lds_dwordx4 v128, s[48:49]
	s_mov_b32 m0, s81
	s_nop 0
	global_load_lds_dwordx4 v132, s[82:83]
	s_add_i32 m0, s81, 0x2000
	s_nop 0
	global_load_lds_dwordx4 v128, s[82:83]
	s_add_u32 s100, s68, s16
	s_addc_u32 s101, s69, s17
	s_mov_b32 m0, s10
	s_nop 0
	global_load_lds_dwordx4 v134, s[68:69]
	s_mov_b32 m0, s22
	s_nop 0
	global_load_lds_dwordx4 v130, s[68:69]
	s_waitcnt vmcnt(8)
	s_waitcnt lgkmcnt(0)
	s_barrier
	s_setprio 1
	s_waitcnt lgkmcnt(0)
	v_mfma_f32_16x16x32_bf16 v[60:63], v[146:149], v[180:183], v[60:63]
	v_mfma_f32_16x16x32_bf16 v[60:63], v[150:153], v[184:187], v[60:63]
	v_mfma_f32_16x16x32_bf16 v[56:59], v[154:157], v[180:183], v[56:59]
	v_mfma_f32_16x16x32_bf16 v[56:59], v[158:161], v[184:187], v[56:59]
	v_mfma_f32_16x16x32_bf16 v[52:55], v[146:149], v[188:191], v[52:55]
	v_mfma_f32_16x16x32_bf16 v[52:55], v[150:153], v[192:195], v[52:55]
	v_mfma_f32_16x16x32_bf16 v[48:51], v[154:157], v[188:191], v[48:51]
	v_mfma_f32_16x16x32_bf16 v[48:51], v[158:161], v[192:195], v[48:51]
	v_mfma_f32_16x16x32_bf16 v[36:39], v[146:149], v[196:199], v[36:39]
	v_mfma_f32_16x16x32_bf16 v[36:39], v[150:153], v[200:203], v[36:39]
	v_mfma_f32_16x16x32_bf16 v[32:35], v[154:157], v[196:199], v[32:35]
	v_mfma_f32_16x16x32_bf16 v[32:35], v[158:161], v[200:203], v[32:35]
	v_mfma_f32_16x16x32_bf16 v[20:23], v[146:149], v[204:207], v[20:23]
	v_mfma_f32_16x16x32_bf16 v[20:23], v[150:153], v[208:211], v[20:23]
	v_mfma_f32_16x16x32_bf16 v[16:19], v[154:157], v[204:207], v[16:19]
	v_mfma_f32_16x16x32_bf16 v[16:19], v[158:161], v[208:211], v[16:19]
	s_setprio 0
	s_setprio 1
	v_mfma_f32_16x16x32_bf16 v[44:47], v[162:165], v[180:183], v[44:47]
	v_mfma_f32_16x16x32_bf16 v[44:47], v[166:169], v[184:187], v[44:47]
	v_mfma_f32_16x16x32_bf16 v[40:43], v[170:173], v[180:183], v[40:43]
	v_mfma_f32_16x16x32_bf16 v[40:43], v[176:179], v[184:187], v[40:43]
	v_mfma_f32_16x16x32_bf16 v[28:31], v[162:165], v[188:191], v[28:31]
	v_mfma_f32_16x16x32_bf16 v[28:31], v[166:169], v[192:195], v[28:31]
	v_mfma_f32_16x16x32_bf16 v[24:27], v[170:173], v[188:191], v[24:27]
	v_mfma_f32_16x16x32_bf16 v[24:27], v[176:179], v[192:195], v[24:27]
	v_mfma_f32_16x16x32_bf16 v[12:15], v[162:165], v[196:199], v[12:15]
	v_mfma_f32_16x16x32_bf16 v[12:15], v[166:169], v[200:203], v[12:15]
	v_mfma_f32_16x16x32_bf16 v[8:11], v[170:173], v[196:199], v[8:11]
	v_mfma_f32_16x16x32_bf16 v[8:11], v[176:179], v[200:203], v[8:11]
	v_mfma_f32_16x16x32_bf16 v[4:7], v[162:165], v[204:207], v[4:7]
	v_mfma_f32_16x16x32_bf16 v[4:7], v[166:169], v[208:211], v[4:7]
	v_mfma_f32_16x16x32_bf16 v[0:3], v[170:173], v[204:207], v[0:3]
	v_mfma_f32_16x16x32_bf16 v[0:3], v[176:179], v[208:211], v[0:3]
	s_setprio 0
	s_barrier
	s_add_i32 s81, 0, 0x18000
	v_add_u32_e32 v145, s81, v140
	s_add_i32 s82, 0, 0x1c000
	ds_read_b128 v[146:149], v145
	ds_read_b128 v[150:153], v145 offset:1024
	ds_read_b128 v[154:157], v145 offset:2048
	ds_read_b128 v[158:161], v145 offset:3072
	v_add_u32_e32 v145, s82, v140
	ds_read_b128 v[162:165], v145
	ds_read_b128 v[166:169], v145 offset:1024
	ds_read_b128 v[170:173], v145 offset:2048
	ds_read_b128 v[176:179], v145 offset:3072
	s_add_u32 s68, s68, 0x80000
	s_addc_u32 s69, s69, 0
	s_mov_b32 m0, s23
	ds_read_b128 v[180:183], v143 offset:32768
	ds_read_b128 v[184:187], v143 offset:33792
	ds_read_b128 v[188:191], v143 offset:34816
	ds_read_b128 v[192:195], v143 offset:35840
	ds_read_b128 v[196:199], v143 offset:36864
	ds_read_b128 v[200:203], v143 offset:37888
	ds_read_b128 v[204:207], v143 offset:38912
	ds_read_b128 v[208:211], v143 offset:39936
	global_load_lds_dwordx4 v134, s[68:69]
	s_mov_b32 m0, s33
	s_nop 0
	global_load_lds_dwordx4 v130, s[68:69]
	s_waitcnt vmcnt(8)
	s_waitcnt lgkmcnt(0)
	s_barrier
	s_setprio 1
	s_waitcnt lgkmcnt(0)
	v_mfma_f32_16x16x32_bf16 v[124:127], v[146:149], v[180:183], v[124:127]
	v_mfma_f32_16x16x32_bf16 v[124:127], v[150:153], v[184:187], v[124:127]
	v_mfma_f32_16x16x32_bf16 v[120:123], v[154:157], v[180:183], v[120:123]
	v_mfma_f32_16x16x32_bf16 v[120:123], v[158:161], v[184:187], v[120:123]
	v_mfma_f32_16x16x32_bf16 v[116:119], v[146:149], v[188:191], v[116:119]
	v_mfma_f32_16x16x32_bf16 v[116:119], v[150:153], v[192:195], v[116:119]
	v_mfma_f32_16x16x32_bf16 v[112:115], v[154:157], v[188:191], v[112:115]
	v_mfma_f32_16x16x32_bf16 v[112:115], v[158:161], v[192:195], v[112:115]
	v_mfma_f32_16x16x32_bf16 v[100:103], v[146:149], v[196:199], v[100:103]
	v_mfma_f32_16x16x32_bf16 v[100:103], v[150:153], v[200:203], v[100:103]
	v_mfma_f32_16x16x32_bf16 v[96:99], v[154:157], v[196:199], v[96:99]
	v_mfma_f32_16x16x32_bf16 v[96:99], v[158:161], v[200:203], v[96:99]
	v_mfma_f32_16x16x32_bf16 v[84:87], v[146:149], v[204:207], v[84:87]
	v_mfma_f32_16x16x32_bf16 v[84:87], v[150:153], v[208:211], v[84:87]
	v_mfma_f32_16x16x32_bf16 v[80:83], v[154:157], v[204:207], v[80:83]
	v_mfma_f32_16x16x32_bf16 v[80:83], v[158:161], v[208:211], v[80:83]
	s_setprio 0
	s_setprio 1
	v_mfma_f32_16x16x32_bf16 v[108:111], v[162:165], v[180:183], v[108:111]
	v_mfma_f32_16x16x32_bf16 v[108:111], v[166:169], v[184:187], v[108:111]
	v_mfma_f32_16x16x32_bf16 v[104:107], v[170:173], v[180:183], v[104:107]
	v_mfma_f32_16x16x32_bf16 v[104:107], v[176:179], v[184:187], v[104:107]
	v_mfma_f32_16x16x32_bf16 v[92:95], v[162:165], v[188:191], v[92:95]
	v_mfma_f32_16x16x32_bf16 v[92:95], v[166:169], v[192:195], v[92:95]
	v_mfma_f32_16x16x32_bf16 v[88:91], v[170:173], v[188:191], v[88:91]
	v_mfma_f32_16x16x32_bf16 v[88:91], v[176:179], v[192:195], v[88:91]
	v_mfma_f32_16x16x32_bf16 v[76:79], v[162:165], v[196:199], v[76:79]
	v_mfma_f32_16x16x32_bf16 v[76:79], v[166:169], v[200:203], v[76:79]
	v_mfma_f32_16x16x32_bf16 v[72:75], v[170:173], v[196:199], v[72:75]
	v_mfma_f32_16x16x32_bf16 v[72:75], v[176:179], v[200:203], v[72:75]
	v_mfma_f32_16x16x32_bf16 v[68:71], v[162:165], v[204:207], v[68:71]
	v_mfma_f32_16x16x32_bf16 v[68:71], v[166:169], v[208:211], v[68:71]
	v_mfma_f32_16x16x32_bf16 v[64:67], v[170:173], v[204:207], v[64:67]
	v_mfma_f32_16x16x32_bf16 v[64:67], v[176:179], v[208:211], v[64:67]
	s_setprio 0
	s_barrier
	s_add_i32 s68, s81, s6
	s_mov_b32 m0, s68
	ds_read_b128 v[180:183], v143 offset:49152
	ds_read_b128 v[184:187], v143 offset:50176
	ds_read_b128 v[188:191], v143 offset:51200
	ds_read_b128 v[192:195], v143 offset:52224
	ds_read_b128 v[196:199], v143 offset:53248
	ds_read_b128 v[200:203], v143 offset:54272
	ds_read_b128 v[204:207], v143 offset:55296
	ds_read_b128 v[208:211], v143 offset:56320
	global_load_lds_dwordx4 v132, s[98:99]
	s_add_i32 m0, s68, 0x2000
	s_add_u32 s48, s48, 0x80080
	s_addc_u32 s49, s49, 0
	s_add_i32 s68, s82, s6
	global_load_lds_dwordx4 v128, s[98:99]
	s_mov_b32 m0, s68
	s_nop 0
	global_load_lds_dwordx4 v132, s[48:49]
	s_add_i32 m0, s68, 0x2000
	s_nop 0
	global_load_lds_dwordx4 v128, s[48:49]
	s_mov_b32 m0, s41
	s_nop 0
	global_load_lds_dwordx4 v134, s[100:101]
	s_mov_b32 m0, s44
	s_nop 0
	global_load_lds_dwordx4 v130, s[100:101]
	s_waitcnt vmcnt(8)
	s_waitcnt lgkmcnt(0)
	s_barrier
	s_setprio 1
	s_waitcnt lgkmcnt(0)
	v_mfma_f32_16x16x32_bf16 v[60:63], v[146:149], v[180:183], v[60:63]
	v_mfma_f32_16x16x32_bf16 v[60:63], v[150:153], v[184:187], v[60:63]
	v_mfma_f32_16x16x32_bf16 v[56:59], v[154:157], v[180:183], v[56:59]
	v_mfma_f32_16x16x32_bf16 v[56:59], v[158:161], v[184:187], v[56:59]
	v_mfma_f32_16x16x32_bf16 v[52:55], v[146:149], v[188:191], v[52:55]
	v_mfma_f32_16x16x32_bf16 v[52:55], v[150:153], v[192:195], v[52:55]
	v_mfma_f32_16x16x32_bf16 v[48:51], v[154:157], v[188:191], v[48:51]
	v_mfma_f32_16x16x32_bf16 v[48:51], v[158:161], v[192:195], v[48:51]
	v_mfma_f32_16x16x32_bf16 v[36:39], v[146:149], v[196:199], v[36:39]
	v_mfma_f32_16x16x32_bf16 v[36:39], v[150:153], v[200:203], v[36:39]
	v_mfma_f32_16x16x32_bf16 v[32:35], v[154:157], v[196:199], v[32:35]
	v_mfma_f32_16x16x32_bf16 v[32:35], v[158:161], v[200:203], v[32:35]
	v_mfma_f32_16x16x32_bf16 v[20:23], v[146:149], v[204:207], v[20:23]
	v_mfma_f32_16x16x32_bf16 v[20:23], v[150:153], v[208:211], v[20:23]
	v_mfma_f32_16x16x32_bf16 v[16:19], v[154:157], v[204:207], v[16:19]
	v_mfma_f32_16x16x32_bf16 v[16:19], v[158:161], v[208:211], v[16:19]
	s_setprio 0
	s_setprio 1
	v_mfma_f32_16x16x32_bf16 v[44:47], v[162:165], v[180:183], v[44:47]
	v_mfma_f32_16x16x32_bf16 v[44:47], v[166:169], v[184:187], v[44:47]
	v_mfma_f32_16x16x32_bf16 v[40:43], v[170:173], v[180:183], v[40:43]
	v_mfma_f32_16x16x32_bf16 v[40:43], v[176:179], v[184:187], v[40:43]
	v_mfma_f32_16x16x32_bf16 v[28:31], v[162:165], v[188:191], v[28:31]
	v_mfma_f32_16x16x32_bf16 v[28:31], v[166:169], v[192:195], v[28:31]
	v_mfma_f32_16x16x32_bf16 v[24:27], v[170:173], v[188:191], v[24:27]
	v_mfma_f32_16x16x32_bf16 v[24:27], v[176:179], v[192:195], v[24:27]
	v_mfma_f32_16x16x32_bf16 v[12:15], v[162:165], v[196:199], v[12:15]
	v_mfma_f32_16x16x32_bf16 v[12:15], v[166:169], v[200:203], v[12:15]
	v_mfma_f32_16x16x32_bf16 v[8:11], v[170:173], v[196:199], v[8:11]
	v_mfma_f32_16x16x32_bf16 v[8:11], v[176:179], v[200:203], v[8:11]
	v_mfma_f32_16x16x32_bf16 v[4:7], v[162:165], v[204:207], v[4:7]
	v_mfma_f32_16x16x32_bf16 v[4:7], v[166:169], v[208:211], v[4:7]
	v_mfma_f32_16x16x32_bf16 v[0:3], v[170:173], v[204:207], v[0:3]
	v_mfma_f32_16x16x32_bf16 v[0:3], v[176:179], v[208:211], v[0:3]
	s_setprio 0
	s_add_i32 s80, s80, 2
	s_add_u32 s46, s46, 0x100
	s_addc_u32 s47, s47, 0
	s_add_u32 s27, s27, 0x100
	s_addc_u32 s79, s79, 0
	s_cmp_gt_u32 s80, 5
	s_barrier
	s_cbranch_scc0 .LBB0_273
	s_and_b64 vcc, exec, s[20:21]
	s_cbranch_vccz .LBB0_276
	s_barrier

.LBB0_414:
	ds_read_b128 v[146:149], v141
	ds_read_b128 v[150:153], v141 offset:1024
	ds_read_b128 v[154:157], v141 offset:2048
	ds_read_b128 v[158:161], v141 offset:3072
	ds_read_b128 v[162:165], v142
	ds_read_b128 v[166:169], v142 offset:1024
	ds_read_b128 v[170:173], v142 offset:2048
	ds_read_b128 v[176:179], v142 offset:3072
	s_add_u32 s46, s44, 0xfff80080
	s_addc_u32 s47, s45, -1
	s_cmp_eq_u32 s82, 4
	s_cselect_b32 s49, s41, s47
	s_cselect_b32 s48, s40, s46
	s_cselect_b32 s47, s43, s81
	s_cselect_b32 s46, s42, s39
	s_mov_b32 m0, s64
	ds_read_b128 v[180:183], v143
	ds_read_b128 v[184:187], v143 offset:1024
	ds_read_b128 v[188:191], v143 offset:2048
	ds_read_b128 v[192:195], v143 offset:3072
	ds_read_b128 v[196:199], v143 offset:4096
	ds_read_b128 v[200:203], v143 offset:5120
	ds_read_b128 v[204:207], v143 offset:6144
	ds_read_b128 v[208:211], v143 offset:7168
	global_load_lds_dwordx4 v136, s[44:45]
	s_mov_b32 m0, s65
	s_nop 0
	global_load_lds_dwordx4 v138, s[44:45]
	s_waitcnt vmcnt(8)
	s_waitcnt lgkmcnt(0)
	s_barrier
	s_setprio 1
	s_waitcnt lgkmcnt(0)
	v_mfma_f32_16x16x32_bf16 v[124:127], v[146:149], v[180:183], v[124:127]
	v_mfma_f32_16x16x32_bf16 v[124:127], v[150:153], v[184:187], v[124:127]
	v_mfma_f32_16x16x32_bf16 v[120:123], v[154:157], v[180:183], v[120:123]
	v_mfma_f32_16x16x32_bf16 v[120:123], v[158:161], v[184:187], v[120:123]
	v_mfma_f32_16x16x32_bf16 v[116:119], v[146:149], v[188:191], v[116:119]
	v_mfma_f32_16x16x32_bf16 v[116:119], v[150:153], v[192:195], v[116:119]
	v_mfma_f32_16x16x32_bf16 v[112:115], v[154:157], v[188:191], v[112:115]
	v_mfma_f32_16x16x32_bf16 v[112:115], v[158:161], v[192:195], v[112:115]
	v_mfma_f32_16x16x32_bf16 v[100:103], v[146:149], v[196:199], v[100:103]
	v_mfma_f32_16x16x32_bf16 v[100:103], v[150:153], v[200:203], v[100:103]
	v_mfma_f32_16x16x32_bf16 v[96:99], v[154:157], v[196:199], v[96:99]
	v_mfma_f32_16x16x32_bf16 v[96:99], v[158:161], v[200:203], v[96:99]
	v_mfma_f32_16x16x32_bf16 v[84:87], v[146:149], v[204:207], v[84:87]
	v_mfma_f32_16x16x32_bf16 v[84:87], v[150:153], v[208:211], v[84:87]
	v_mfma_f32_16x16x32_bf16 v[80:83], v[154:157], v[204:207], v[80:83]
	v_mfma_f32_16x16x32_bf16 v[80:83], v[158:161], v[208:211], v[80:83]
	s_setprio 0
	s_setprio 1
	v_mfma_f32_16x16x32_bf16 v[108:111], v[162:165], v[180:183], v[108:111]
	v_mfma_f32_16x16x32_bf16 v[108:111], v[166:169], v[184:187], v[108:111]
	v_mfma_f32_16x16x32_bf16 v[104:107], v[170:173], v[180:183], v[104:107]
	v_mfma_f32_16x16x32_bf16 v[104:107], v[176:179], v[184:187], v[104:107]
	v_mfma_f32_16x16x32_bf16 v[92:95], v[162:165], v[188:191], v[92:95]
	v_mfma_f32_16x16x32_bf16 v[92:95], v[166:169], v[192:195], v[92:95]
	v_mfma_f32_16x16x32_bf16 v[88:91], v[170:173], v[188:191], v[88:91]
	v_mfma_f32_16x16x32_bf16 v[88:91], v[176:179], v[192:195], v[88:91]
	v_mfma_f32_16x16x32_bf16 v[76:79], v[162:165], v[196:199], v[76:79]
	v_mfma_f32_16x16x32_bf16 v[76:79], v[166:169], v[200:203], v[76:79]
	v_mfma_f32_16x16x32_bf16 v[72:75], v[170:173], v[196:199], v[72:75]
	v_mfma_f32_16x16x32_bf16 v[72:75], v[176:179], v[200:203], v[72:75]
	v_mfma_f32_16x16x32_bf16 v[68:71], v[162:165], v[204:207], v[68:71]
	v_mfma_f32_16x16x32_bf16 v[68:71], v[166:169], v[208:211], v[68:71]
	v_mfma_f32_16x16x32_bf16 v[64:67], v[170:173], v[204:207], v[64:67]
	v_mfma_f32_16x16x32_bf16 v[64:67], v[176:179], v[208:211], v[64:67]
	s_setprio 0
	s_barrier
	s_mov_b32 m0, s68
	s_add_u32 s98, s46, s24
	s_addc_u32 s99, s47, s25
	s_add_u32 s84, s46, 0x80000
	ds_read_b128 v[180:183], v143 offset:16384
	ds_read_b128 v[184:187], v143 offset:17408
	ds_read_b128 v[188:191], v143 offset:18432
	ds_read_b128 v[192:195], v143 offset:19456
	ds_read_b128 v[196:199], v143 offset:20480
	ds_read_b128 v[200:203], v143 offset:21504
	ds_read_b128 v[204:207], v143 offset:22528
	ds_read_b128 v[208:211], v143 offset:23552
	global_load_lds_dwordx4 v132, s[46:47]
	s_mov_b32 m0, s69
	s_addc_u32 s85, s47, 0
	global_load_lds_dwordx4 v128, s[46:47]
	s_mov_b32 m0, s77
	s_nop 0
	global_load_lds_dwordx4 v132, s[84:85]
	s_add_i32 m0, s77, 0x2000
	s_nop 0
	global_load_lds_dwordx4 v128, s[84:85]
	s_add_u32 s100, s48, s24
	s_addc_u32 s101, s49, s25
	s_mov_b32 m0, s22
	s_nop 0
	global_load_lds_dwordx4 v134, s[48:49]
	s_mov_b32 m0, s23
	s_nop 0
	global_load_lds_dwordx4 v130, s[48:49]
	s_waitcnt vmcnt(8)
	s_waitcnt lgkmcnt(0)
	s_barrier
	s_setprio 1
	s_waitcnt lgkmcnt(0)
	v_mfma_f32_16x16x32_bf16 v[60:63], v[146:149], v[180:183], v[60:63]
	v_mfma_f32_16x16x32_bf16 v[60:63], v[150:153], v[184:187], v[60:63]
	v_mfma_f32_16x16x32_bf16 v[56:59], v[154:157], v[180:183], v[56:59]
	v_mfma_f32_16x16x32_bf16 v[56:59], v[158:161], v[184:187], v[56:59]
	v_mfma_f32_16x16x32_bf16 v[52:55], v[146:149], v[188:191], v[52:55]
	v_mfma_f32_16x16x32_bf16 v[52:55], v[150:153], v[192:195], v[52:55]
	v_mfma_f32_16x16x32_bf16 v[48:51], v[154:157], v[188:191], v[48:51]
	v_mfma_f32_16x16x32_bf16 v[48:51], v[158:161], v[192:195], v[48:51]
	v_mfma_f32_16x16x32_bf16 v[36:39], v[146:149], v[196:199], v[36:39]
	v_mfma_f32_16x16x32_bf16 v[36:39], v[150:153], v[200:203], v[36:39]
	v_mfma_f32_16x16x32_bf16 v[32:35], v[154:157], v[196:199], v[32:35]
	v_mfma_f32_16x16x32_bf16 v[32:35], v[158:161], v[200:203], v[32:35]
	v_mfma_f32_16x16x32_bf16 v[20:23], v[146:149], v[204:207], v[20:23]
	v_mfma_f32_16x16x32_bf16 v[20:23], v[150:153], v[208:211], v[20:23]
	v_mfma_f32_16x16x32_bf16 v[16:19], v[154:157], v[204:207], v[16:19]
	v_mfma_f32_16x16x32_bf16 v[16:19], v[158:161], v[208:211], v[16:19]
	s_setprio 0
	s_setprio 1
	v_mfma_f32_16x16x32_bf16 v[44:47], v[162:165], v[180:183], v[44:47]
	v_mfma_f32_16x16x32_bf16 v[44:47], v[166:169], v[184:187], v[44:47]
	v_mfma_f32_16x16x32_bf16 v[40:43], v[170:173], v[180:183], v[40:43]
	v_mfma_f32_16x16x32_bf16 v[40:43], v[176:179], v[184:187], v[40:43]
	v_mfma_f32_16x16x32_bf16 v[28:31], v[162:165], v[188:191], v[28:31]
	v_mfma_f32_16x16x32_bf16 v[28:31], v[166:169], v[192:195], v[28:31]
	v_mfma_f32_16x16x32_bf16 v[24:27], v[170:173], v[188:191], v[24:27]
	v_mfma_f32_16x16x32_bf16 v[24:27], v[176:179], v[192:195], v[24:27]
	v_mfma_f32_16x16x32_bf16 v[12:15], v[162:165], v[196:199], v[12:15]
	v_mfma_f32_16x16x32_bf16 v[12:15], v[166:169], v[200:203], v[12:15]
	v_mfma_f32_16x16x32_bf16 v[8:11], v[170:173], v[196:199], v[8:11]
	v_mfma_f32_16x16x32_bf16 v[8:11], v[176:179], v[200:203], v[8:11]
	v_mfma_f32_16x16x32_bf16 v[4:7], v[162:165], v[204:207], v[4:7]
	v_mfma_f32_16x16x32_bf16 v[4:7], v[166:169], v[208:211], v[4:7]
	v_mfma_f32_16x16x32_bf16 v[0:3], v[170:173], v[204:207], v[0:3]
	v_mfma_f32_16x16x32_bf16 v[0:3], v[176:179], v[208:211], v[0:3]
	s_setprio 0
	s_barrier
	s_add_i32 s83, 0, 0x18000
	v_add_u32_e32 v145, s83, v140
	s_add_i32 s84, 0, 0x1c000
	ds_read_b128 v[146:149], v145
	ds_read_b128 v[150:153], v145 offset:1024
	ds_read_b128 v[154:157], v145 offset:2048
	ds_read_b128 v[158:161], v145 offset:3072
	v_add_u32_e32 v145, s84, v140
	ds_read_b128 v[162:165], v145
	ds_read_b128 v[166:169], v145 offset:1024
	ds_read_b128 v[170:173], v145 offset:2048
	ds_read_b128 v[176:179], v145 offset:3072
	s_add_u32 s48, s48, 0x80000
	s_addc_u32 s49, s49, 0
	s_mov_b32 m0, s33
	ds_read_b128 v[180:183], v143 offset:32768
	ds_read_b128 v[184:187], v143 offset:33792
	ds_read_b128 v[188:191], v143 offset:34816
	ds_read_b128 v[192:195], v143 offset:35840
	ds_read_b128 v[196:199], v143 offset:36864
	ds_read_b128 v[200:203], v143 offset:37888
	ds_read_b128 v[204:207], v143 offset:38912
	ds_read_b128 v[208:211], v143 offset:39936
	global_load_lds_dwordx4 v134, s[48:49]
	s_mov_b32 m0, s50
	s_nop 0
	global_load_lds_dwordx4 v130, s[48:49]
	s_waitcnt vmcnt(8)
	s_waitcnt lgkmcnt(0)
	s_barrier
	s_setprio 1
	s_waitcnt lgkmcnt(0)
	v_mfma_f32_16x16x32_bf16 v[124:127], v[146:149], v[180:183], v[124:127]
	v_mfma_f32_16x16x32_bf16 v[124:127], v[150:153], v[184:187], v[124:127]
	v_mfma_f32_16x16x32_bf16 v[120:123], v[154:157], v[180:183], v[120:123]
	v_mfma_f32_16x16x32_bf16 v[120:123], v[158:161], v[184:187], v[120:123]
	v_mfma_f32_16x16x32_bf16 v[116:119], v[146:149], v[188:191], v[116:119]
	v_mfma_f32_16x16x32_bf16 v[116:119], v[150:153], v[192:195], v[116:119]
	v_mfma_f32_16x16x32_bf16 v[112:115], v[154:157], v[188:191], v[112:115]
	v_mfma_f32_16x16x32_bf16 v[112:115], v[158:161], v[192:195], v[112:115]
	v_mfma_f32_16x16x32_bf16 v[100:103], v[146:149], v[196:199], v[100:103]
	v_mfma_f32_16x16x32_bf16 v[100:103], v[150:153], v[200:203], v[100:103]
	v_mfma_f32_16x16x32_bf16 v[96:99], v[154:157], v[196:199], v[96:99]
	v_mfma_f32_16x16x32_bf16 v[96:99], v[158:161], v[200:203], v[96:99]
	v_mfma_f32_16x16x32_bf16 v[84:87], v[146:149], v[204:207], v[84:87]
	v_mfma_f32_16x16x32_bf16 v[84:87], v[150:153], v[208:211], v[84:87]
	v_mfma_f32_16x16x32_bf16 v[80:83], v[154:157], v[204:207], v[80:83]
	v_mfma_f32_16x16x32_bf16 v[80:83], v[158:161], v[208:211], v[80:83]
	s_setprio 0
	s_setprio 1
	v_mfma_f32_16x16x32_bf16 v[108:111], v[162:165], v[180:183], v[108:111]
	v_mfma_f32_16x16x32_bf16 v[108:111], v[166:169], v[184:187], v[108:111]
	v_mfma_f32_16x16x32_bf16 v[104:107], v[170:173], v[180:183], v[104:107]
	v_mfma_f32_16x16x32_bf16 v[104:107], v[176:179], v[184:187], v[104:107]
	v_mfma_f32_16x16x32_bf16 v[92:95], v[162:165], v[188:191], v[92:95]
	v_mfma_f32_16x16x32_bf16 v[92:95], v[166:169], v[192:195], v[92:95]
	v_mfma_f32_16x16x32_bf16 v[88:91], v[170:173], v[188:191], v[88:91]
	v_mfma_f32_16x16x32_bf16 v[88:91], v[176:179], v[192:195], v[88:91]
	v_mfma_f32_16x16x32_bf16 v[76:79], v[162:165], v[196:199], v[76:79]
	v_mfma_f32_16x16x32_bf16 v[76:79], v[166:169], v[200:203], v[76:79]
	v_mfma_f32_16x16x32_bf16 v[72:75], v[170:173], v[196:199], v[72:75]
	v_mfma_f32_16x16x32_bf16 v[72:75], v[176:179], v[200:203], v[72:75]
	v_mfma_f32_16x16x32_bf16 v[68:71], v[162:165], v[204:207], v[68:71]
	v_mfma_f32_16x16x32_bf16 v[68:71], v[166:169], v[208:211], v[68:71]
	v_mfma_f32_16x16x32_bf16 v[64:67], v[170:173], v[204:207], v[64:67]
	v_mfma_f32_16x16x32_bf16 v[64:67], v[176:179], v[208:211], v[64:67]
	s_setprio 0
	s_barrier
	s_add_i32 s48, s83, s10
	s_mov_b32 m0, s48
	ds_read_b128 v[180:183], v143 offset:49152
	ds_read_b128 v[184:187], v143 offset:50176
	ds_read_b128 v[188:191], v143 offset:51200
	ds_read_b128 v[192:195], v143 offset:52224
	ds_read_b128 v[196:199], v143 offset:53248
	ds_read_b128 v[200:203], v143 offset:54272
	ds_read_b128 v[204:207], v143 offset:55296
	ds_read_b128 v[208:211], v143 offset:56320
	global_load_lds_dwordx4 v132, s[98:99]
	s_add_i32 m0, s48, 0x2000
	s_add_u32 s46, s46, 0x80080
	s_addc_u32 s47, s47, 0
	s_add_i32 s48, s84, s10
	global_load_lds_dwordx4 v128, s[98:99]
	s_mov_b32 m0, s48
	s_nop 0
	global_load_lds_dwordx4 v132, s[46:47]
	s_add_i32 m0, s48, 0x2000
	s_nop 0
	global_load_lds_dwordx4 v128, s[46:47]
	s_mov_b32 m0, s62
	s_nop 0
	global_load_lds_dwordx4 v134, s[100:101]
	s_mov_b32 m0, s63
	s_nop 0
	global_load_lds_dwordx4 v130, s[100:101]
	s_waitcnt vmcnt(8)
	s_waitcnt lgkmcnt(0)
	s_barrier
	s_setprio 1
	s_waitcnt lgkmcnt(0)
	v_mfma_f32_16x16x32_bf16 v[60:63], v[146:149], v[180:183], v[60:63]
	v_mfma_f32_16x16x32_bf16 v[60:63], v[150:153], v[184:187], v[60:63]
	v_mfma_f32_16x16x32_bf16 v[56:59], v[154:157], v[180:183], v[56:59]
	v_mfma_f32_16x16x32_bf16 v[56:59], v[158:161], v[184:187], v[56:59]
	v_mfma_f32_16x16x32_bf16 v[52:55], v[146:149], v[188:191], v[52:55]
	v_mfma_f32_16x16x32_bf16 v[52:55], v[150:153], v[192:195], v[52:55]
	v_mfma_f32_16x16x32_bf16 v[48:51], v[154:157], v[188:191], v[48:51]
	v_mfma_f32_16x16x32_bf16 v[48:51], v[158:161], v[192:195], v[48:51]
	v_mfma_f32_16x16x32_bf16 v[36:39], v[146:149], v[196:199], v[36:39]
	v_mfma_f32_16x16x32_bf16 v[36:39], v[150:153], v[200:203], v[36:39]
	v_mfma_f32_16x16x32_bf16 v[32:35], v[154:157], v[196:199], v[32:35]
	v_mfma_f32_16x16x32_bf16 v[32:35], v[158:161], v[200:203], v[32:35]
	v_mfma_f32_16x16x32_bf16 v[20:23], v[146:149], v[204:207], v[20:23]
	v_mfma_f32_16x16x32_bf16 v[20:23], v[150:153], v[208:211], v[20:23]
	v_mfma_f32_16x16x32_bf16 v[16:19], v[154:157], v[204:207], v[16:19]
	v_mfma_f32_16x16x32_bf16 v[16:19], v[158:161], v[208:211], v[16:19]
	s_setprio 0
	s_setprio 1
	v_mfma_f32_16x16x32_bf16 v[44:47], v[162:165], v[180:183], v[44:47]
	v_mfma_f32_16x16x32_bf16 v[44:47], v[166:169], v[184:187], v[44:47]
	v_mfma_f32_16x16x32_bf16 v[40:43], v[170:173], v[180:183], v[40:43]
	v_mfma_f32_16x16x32_bf16 v[40:43], v[176:179], v[184:187], v[40:43]
	v_mfma_f32_16x16x32_bf16 v[28:31], v[162:165], v[188:191], v[28:31]
	v_mfma_f32_16x16x32_bf16 v[28:31], v[166:169], v[192:195], v[28:31]
	v_mfma_f32_16x16x32_bf16 v[24:27], v[170:173], v[188:191], v[24:27]
	v_mfma_f32_16x16x32_bf16 v[24:27], v[176:179], v[192:195], v[24:27]
	v_mfma_f32_16x16x32_bf16 v[12:15], v[162:165], v[196:199], v[12:15]
	v_mfma_f32_16x16x32_bf16 v[12:15], v[166:169], v[200:203], v[12:15]
	v_mfma_f32_16x16x32_bf16 v[8:11], v[170:173], v[196:199], v[8:11]
	v_mfma_f32_16x16x32_bf16 v[8:11], v[176:179], v[200:203], v[8:11]
	v_mfma_f32_16x16x32_bf16 v[4:7], v[162:165], v[204:207], v[4:7]
	v_mfma_f32_16x16x32_bf16 v[4:7], v[166:169], v[208:211], v[4:7]
	v_mfma_f32_16x16x32_bf16 v[0:3], v[170:173], v[204:207], v[0:3]
	v_mfma_f32_16x16x32_bf16 v[0:3], v[176:179], v[208:211], v[0:3]
	s_setprio 0
	s_add_i32 s82, s82, 2
	s_add_u32 s44, s44, 0x100
	s_addc_u32 s45, s45, 0
	s_add_u32 s39, s39, 0x100
	s_addc_u32 s81, s81, 0
	s_cmp_gt_u32 s82, 5
	s_barrier
	s_cbranch_scc0 .LBB0_414
	s_and_b64 vcc, exec, s[36:37]
	s_cbranch_vccz .LBB0_417
	s_barrier

.LBB0_428:
	ds_read_b128 v[148:151], v143
	ds_read_b128 v[152:155], v143 offset:1024
	ds_read_b128 v[156:159], v143 offset:2048
	ds_read_b128 v[160:163], v143 offset:3072
	ds_read_b128 v[164:167], v144
	ds_read_b128 v[168:171], v144 offset:1024
	ds_read_b128 v[176:179], v144 offset:2048
	ds_read_b128 v[180:183], v144 offset:3072
	s_add_u32 s48, s46, 0xfff80080
	s_addc_u32 s49, s47, -1
	s_cmp_eq_u32 s83, 4
	s_cselect_b32 s51, s77, s49
	s_cselect_b32 s50, s78, s48
	s_cselect_b32 s49, s79, s82
	s_cselect_b32 s48, s80, s81
	s_add_i32 m0, s15, 0xc000
	ds_read_b128 v[184:187], v145
	ds_read_b128 v[188:191], v145 offset:1024
	ds_read_b128 v[192:195], v145 offset:2048
	ds_read_b128 v[196:199], v145 offset:3072
	ds_read_b128 v[200:203], v145 offset:4096
	ds_read_b128 v[204:207], v145 offset:5120
	ds_read_b128 v[208:211], v145 offset:6144
	ds_read_b128 v[212:215], v145 offset:7168
	global_load_lds_dwordx4 v138, s[46:47]
	s_add_i32 m0, s15, 0xe000
	s_nop 0
	global_load_lds_dwordx4 v140, s[46:47]
	s_waitcnt vmcnt(8)
	s_waitcnt lgkmcnt(0)
	s_barrier
	s_setprio 1
	s_waitcnt lgkmcnt(0)
	v_mfma_f32_16x16x32_bf16 v[124:127], v[148:151], v[184:187], v[124:127]
	v_mfma_f32_16x16x32_bf16 v[124:127], v[152:155], v[188:191], v[124:127]
	v_mfma_f32_16x16x32_bf16 v[120:123], v[156:159], v[184:187], v[120:123]
	v_mfma_f32_16x16x32_bf16 v[120:123], v[160:163], v[188:191], v[120:123]
	v_mfma_f32_16x16x32_bf16 v[116:119], v[148:151], v[192:195], v[116:119]
	v_mfma_f32_16x16x32_bf16 v[116:119], v[152:155], v[196:199], v[116:119]
	v_mfma_f32_16x16x32_bf16 v[112:115], v[156:159], v[192:195], v[112:115]
	v_mfma_f32_16x16x32_bf16 v[112:115], v[160:163], v[196:199], v[112:115]
	v_mfma_f32_16x16x32_bf16 v[100:103], v[148:151], v[200:203], v[100:103]
	v_mfma_f32_16x16x32_bf16 v[100:103], v[152:155], v[204:207], v[100:103]
	v_mfma_f32_16x16x32_bf16 v[96:99], v[156:159], v[200:203], v[96:99]
	v_mfma_f32_16x16x32_bf16 v[96:99], v[160:163], v[204:207], v[96:99]
	v_mfma_f32_16x16x32_bf16 v[84:87], v[148:151], v[208:211], v[84:87]
	v_mfma_f32_16x16x32_bf16 v[84:87], v[152:155], v[212:215], v[84:87]
	v_mfma_f32_16x16x32_bf16 v[80:83], v[156:159], v[208:211], v[80:83]
	v_mfma_f32_16x16x32_bf16 v[80:83], v[160:163], v[212:215], v[80:83]
	s_setprio 0
	s_setprio 1
	v_mfma_f32_16x16x32_bf16 v[108:111], v[164:167], v[184:187], v[108:111]
	v_mfma_f32_16x16x32_bf16 v[108:111], v[168:171], v[188:191], v[108:111]
	v_mfma_f32_16x16x32_bf16 v[104:107], v[176:179], v[184:187], v[104:107]
	v_mfma_f32_16x16x32_bf16 v[104:107], v[180:183], v[188:191], v[104:107]
	v_mfma_f32_16x16x32_bf16 v[92:95], v[164:167], v[192:195], v[92:95]
	v_mfma_f32_16x16x32_bf16 v[92:95], v[168:171], v[196:199], v[92:95]
	v_mfma_f32_16x16x32_bf16 v[88:91], v[176:179], v[192:195], v[88:91]
	v_mfma_f32_16x16x32_bf16 v[88:91], v[180:183], v[196:199], v[88:91]
	v_mfma_f32_16x16x32_bf16 v[76:79], v[164:167], v[200:203], v[76:79]
	v_mfma_f32_16x16x32_bf16 v[76:79], v[168:171], v[204:207], v[76:79]
	v_mfma_f32_16x16x32_bf16 v[72:75], v[176:179], v[200:203], v[72:75]
	v_mfma_f32_16x16x32_bf16 v[72:75], v[180:183], v[204:207], v[72:75]
	v_mfma_f32_16x16x32_bf16 v[68:71], v[164:167], v[208:211], v[68:71]
	v_mfma_f32_16x16x32_bf16 v[68:71], v[168:171], v[212:215], v[68:71]
	v_mfma_f32_16x16x32_bf16 v[64:67], v[176:179], v[208:211], v[64:67]
	v_mfma_f32_16x16x32_bf16 v[64:67], v[180:183], v[212:215], v[64:67]
	s_setprio 0
	s_barrier
	s_add_i32 s84, s68, s10
	s_add_u32 s98, s48, s38
	s_addc_u32 s99, s49, s39
	s_mov_b32 m0, s84
	ds_read_b128 v[184:187], v145 offset:16384
	ds_read_b128 v[188:191], v145 offset:17408
	ds_read_b128 v[192:195], v145 offset:18432
	ds_read_b128 v[196:199], v145 offset:19456
	ds_read_b128 v[200:203], v145 offset:20480
	ds_read_b128 v[204:207], v145 offset:21504
	ds_read_b128 v[208:211], v145 offset:22528
	ds_read_b128 v[212:215], v145 offset:23552
	global_load_lds_dwordx4 v132, s[48:49]
	s_add_i32 m0, s84, 0x2000
	s_add_u32 s84, s48, 0x80000
	s_addc_u32 s85, s49, 0
	s_add_i32 s86, s69, s10
	global_load_lds_dwordx4 v128, s[48:49]
	s_mov_b32 m0, s86
	s_nop 0
	global_load_lds_dwordx4 v132, s[84:85]
	s_add_i32 m0, s86, 0x2000
	s_nop 0
	global_load_lds_dwordx4 v128, s[84:85]
	s_add_u32 s100, s50, s38
	s_addc_u32 s101, s51, s39
	s_mov_b32 m0, s15
	s_nop 0
	global_load_lds_dwordx4 v134, s[50:51]
	s_mov_b32 m0, s22
	s_nop 0
	global_load_lds_dwordx4 v130, s[50:51]
	s_waitcnt vmcnt(8)
	s_waitcnt lgkmcnt(0)
	s_barrier
	s_setprio 1
	s_waitcnt lgkmcnt(0)
	v_mfma_f32_16x16x32_bf16 v[60:63], v[148:151], v[184:187], v[60:63]
	v_mfma_f32_16x16x32_bf16 v[60:63], v[152:155], v[188:191], v[60:63]
	v_mfma_f32_16x16x32_bf16 v[56:59], v[156:159], v[184:187], v[56:59]
	v_mfma_f32_16x16x32_bf16 v[56:59], v[160:163], v[188:191], v[56:59]
	v_mfma_f32_16x16x32_bf16 v[52:55], v[148:151], v[192:195], v[52:55]
	v_mfma_f32_16x16x32_bf16 v[52:55], v[152:155], v[196:199], v[52:55]
	v_mfma_f32_16x16x32_bf16 v[48:51], v[156:159], v[192:195], v[48:51]
	v_mfma_f32_16x16x32_bf16 v[48:51], v[160:163], v[196:199], v[48:51]
	v_mfma_f32_16x16x32_bf16 v[36:39], v[148:151], v[200:203], v[36:39]
	v_mfma_f32_16x16x32_bf16 v[36:39], v[152:155], v[204:207], v[36:39]
	v_mfma_f32_16x16x32_bf16 v[32:35], v[156:159], v[200:203], v[32:35]
	v_mfma_f32_16x16x32_bf16 v[32:35], v[160:163], v[204:207], v[32:35]
	v_mfma_f32_16x16x32_bf16 v[20:23], v[148:151], v[208:211], v[20:23]
	v_mfma_f32_16x16x32_bf16 v[20:23], v[152:155], v[212:215], v[20:23]
	v_mfma_f32_16x16x32_bf16 v[16:19], v[156:159], v[208:211], v[16:19]
	v_mfma_f32_16x16x32_bf16 v[16:19], v[160:163], v[212:215], v[16:19]
	s_setprio 0
	s_setprio 1
	v_mfma_f32_16x16x32_bf16 v[44:47], v[164:167], v[184:187], v[44:47]
	v_mfma_f32_16x16x32_bf16 v[44:47], v[168:171], v[188:191], v[44:47]
	v_mfma_f32_16x16x32_bf16 v[40:43], v[176:179], v[184:187], v[40:43]
	v_mfma_f32_16x16x32_bf16 v[40:43], v[180:183], v[188:191], v[40:43]
	v_mfma_f32_16x16x32_bf16 v[28:31], v[164:167], v[192:195], v[28:31]
	v_mfma_f32_16x16x32_bf16 v[28:31], v[168:171], v[196:199], v[28:31]
	v_mfma_f32_16x16x32_bf16 v[24:27], v[176:179], v[192:195], v[24:27]
	v_mfma_f32_16x16x32_bf16 v[24:27], v[180:183], v[196:199], v[24:27]
	v_mfma_f32_16x16x32_bf16 v[12:15], v[164:167], v[200:203], v[12:15]
	v_mfma_f32_16x16x32_bf16 v[12:15], v[168:171], v[204:207], v[12:15]
	v_mfma_f32_16x16x32_bf16 v[8:11], v[176:179], v[200:203], v[8:11]
	v_mfma_f32_16x16x32_bf16 v[8:11], v[180:183], v[204:207], v[8:11]
	v_mfma_f32_16x16x32_bf16 v[4:7], v[164:167], v[208:211], v[4:7]
	v_mfma_f32_16x16x32_bf16 v[4:7], v[168:171], v[212:215], v[4:7]
	v_mfma_f32_16x16x32_bf16 v[0:3], v[176:179], v[208:211], v[0:3]
	v_mfma_f32_16x16x32_bf16 v[0:3], v[180:183], v[212:215], v[0:3]
	s_setprio 0
	s_barrier
	s_add_i32 s84, 0, 0x18000
	v_add_u32_e32 v136, s84, v142
	s_add_i32 s85, 0, 0x1c000
	ds_read_b128 v[148:151], v136
	ds_read_b128 v[152:155], v136 offset:1024
	ds_read_b128 v[156:159], v136 offset:2048
	ds_read_b128 v[160:163], v136 offset:3072
	v_add_u32_e32 v136, s85, v142
	ds_read_b128 v[164:167], v136
	ds_read_b128 v[168:171], v136 offset:1024
	ds_read_b128 v[176:179], v136 offset:2048
	ds_read_b128 v[180:183], v136 offset:3072
	s_add_u32 s50, s50, 0x80000
	s_addc_u32 s51, s51, 0
	s_mov_b32 m0, s23
	ds_read_b128 v[184:187], v145 offset:32768
	ds_read_b128 v[188:191], v145 offset:33792
	ds_read_b128 v[192:195], v145 offset:34816
	ds_read_b128 v[196:199], v145 offset:35840
	ds_read_b128 v[200:203], v145 offset:36864
	ds_read_b128 v[204:207], v145 offset:37888
	ds_read_b128 v[208:211], v145 offset:38912
	ds_read_b128 v[212:215], v145 offset:39936
	global_load_lds_dwordx4 v134, s[50:51]
	s_mov_b32 m0, s33
	s_nop 0
	global_load_lds_dwordx4 v130, s[50:51]
	s_waitcnt vmcnt(8)
	s_waitcnt lgkmcnt(0)
	s_barrier
	s_setprio 1
	s_waitcnt lgkmcnt(0)
	v_mfma_f32_16x16x32_bf16 v[124:127], v[148:151], v[184:187], v[124:127]
	v_mfma_f32_16x16x32_bf16 v[124:127], v[152:155], v[188:191], v[124:127]
	v_mfma_f32_16x16x32_bf16 v[120:123], v[156:159], v[184:187], v[120:123]
	v_mfma_f32_16x16x32_bf16 v[120:123], v[160:163], v[188:191], v[120:123]
	v_mfma_f32_16x16x32_bf16 v[116:119], v[148:151], v[192:195], v[116:119]
	v_mfma_f32_16x16x32_bf16 v[116:119], v[152:155], v[196:199], v[116:119]
	v_mfma_f32_16x16x32_bf16 v[112:115], v[156:159], v[192:195], v[112:115]
	v_mfma_f32_16x16x32_bf16 v[112:115], v[160:163], v[196:199], v[112:115]
	v_mfma_f32_16x16x32_bf16 v[100:103], v[148:151], v[200:203], v[100:103]
	v_mfma_f32_16x16x32_bf16 v[100:103], v[152:155], v[204:207], v[100:103]
	v_mfma_f32_16x16x32_bf16 v[96:99], v[156:159], v[200:203], v[96:99]
	v_mfma_f32_16x16x32_bf16 v[96:99], v[160:163], v[204:207], v[96:99]
	v_mfma_f32_16x16x32_bf16 v[84:87], v[148:151], v[208:211], v[84:87]
	v_mfma_f32_16x16x32_bf16 v[84:87], v[152:155], v[212:215], v[84:87]
	v_mfma_f32_16x16x32_bf16 v[80:83], v[156:159], v[208:211], v[80:83]
	v_mfma_f32_16x16x32_bf16 v[80:83], v[160:163], v[212:215], v[80:83]
	s_setprio 0
	s_setprio 1
	v_mfma_f32_16x16x32_bf16 v[108:111], v[164:167], v[184:187], v[108:111]
	v_mfma_f32_16x16x32_bf16 v[108:111], v[168:171], v[188:191], v[108:111]
	v_mfma_f32_16x16x32_bf16 v[104:107], v[176:179], v[184:187], v[104:107]
	v_mfma_f32_16x16x32_bf16 v[104:107], v[180:183], v[188:191], v[104:107]
	v_mfma_f32_16x16x32_bf16 v[92:95], v[164:167], v[192:195], v[92:95]
	v_mfma_f32_16x16x32_bf16 v[92:95], v[168:171], v[196:199], v[92:95]
	v_mfma_f32_16x16x32_bf16 v[88:91], v[176:179], v[192:195], v[88:91]
	v_mfma_f32_16x16x32_bf16 v[88:91], v[180:183], v[196:199], v[88:91]
	v_mfma_f32_16x16x32_bf16 v[76:79], v[164:167], v[200:203], v[76:79]
	v_mfma_f32_16x16x32_bf16 v[76:79], v[168:171], v[204:207], v[76:79]
	v_mfma_f32_16x16x32_bf16 v[72:75], v[176:179], v[200:203], v[72:75]
	v_mfma_f32_16x16x32_bf16 v[72:75], v[180:183], v[204:207], v[72:75]
	v_mfma_f32_16x16x32_bf16 v[68:71], v[164:167], v[208:211], v[68:71]
	v_mfma_f32_16x16x32_bf16 v[68:71], v[168:171], v[212:215], v[68:71]
	v_mfma_f32_16x16x32_bf16 v[64:67], v[176:179], v[208:211], v[64:67]
	v_mfma_f32_16x16x32_bf16 v[64:67], v[180:183], v[212:215], v[64:67]
	s_setprio 0
	s_barrier
	s_add_i32 s50, s84, s10
	s_mov_b32 m0, s50
	ds_read_b128 v[184:187], v145 offset:49152
	ds_read_b128 v[188:191], v145 offset:50176
	ds_read_b128 v[192:195], v145 offset:51200
	ds_read_b128 v[196:199], v145 offset:52224
	ds_read_b128 v[200:203], v145 offset:53248
	ds_read_b128 v[204:207], v145 offset:54272
	ds_read_b128 v[208:211], v145 offset:55296
	ds_read_b128 v[212:215], v145 offset:56320
	global_load_lds_dwordx4 v132, s[98:99]
	s_add_i32 m0, s50, 0x2000
	s_add_u32 s48, s48, 0x80080
	s_addc_u32 s49, s49, 0
	s_add_i32 s50, s85, s10
	global_load_lds_dwordx4 v128, s[98:99]
	s_mov_b32 m0, s50
	s_nop 0
	global_load_lds_dwordx4 v132, s[48:49]
	s_add_i32 m0, s50, 0x2000
	s_nop 0
	global_load_lds_dwordx4 v128, s[48:49]
	s_mov_b32 m0, s64
	s_nop 0
	global_load_lds_dwordx4 v134, s[100:101]
	s_mov_b32 m0, s65
	s_nop 0
	global_load_lds_dwordx4 v130, s[100:101]
	s_waitcnt vmcnt(8)
	s_waitcnt lgkmcnt(0)
	s_barrier
	s_setprio 1
	s_waitcnt lgkmcnt(0)
	v_mfma_f32_16x16x32_bf16 v[60:63], v[148:151], v[184:187], v[60:63]
	v_mfma_f32_16x16x32_bf16 v[60:63], v[152:155], v[188:191], v[60:63]
	v_mfma_f32_16x16x32_bf16 v[56:59], v[156:159], v[184:187], v[56:59]
	v_mfma_f32_16x16x32_bf16 v[56:59], v[160:163], v[188:191], v[56:59]
	v_mfma_f32_16x16x32_bf16 v[52:55], v[148:151], v[192:195], v[52:55]
	v_mfma_f32_16x16x32_bf16 v[52:55], v[152:155], v[196:199], v[52:55]
	v_mfma_f32_16x16x32_bf16 v[48:51], v[156:159], v[192:195], v[48:51]
	v_mfma_f32_16x16x32_bf16 v[48:51], v[160:163], v[196:199], v[48:51]
	v_mfma_f32_16x16x32_bf16 v[36:39], v[148:151], v[200:203], v[36:39]
	v_mfma_f32_16x16x32_bf16 v[36:39], v[152:155], v[204:207], v[36:39]
	v_mfma_f32_16x16x32_bf16 v[32:35], v[156:159], v[200:203], v[32:35]
	v_mfma_f32_16x16x32_bf16 v[32:35], v[160:163], v[204:207], v[32:35]
	v_mfma_f32_16x16x32_bf16 v[20:23], v[148:151], v[208:211], v[20:23]
	v_mfma_f32_16x16x32_bf16 v[20:23], v[152:155], v[212:215], v[20:23]
	v_mfma_f32_16x16x32_bf16 v[16:19], v[156:159], v[208:211], v[16:19]
	v_mfma_f32_16x16x32_bf16 v[16:19], v[160:163], v[212:215], v[16:19]
	s_setprio 0
	s_setprio 1
	v_mfma_f32_16x16x32_bf16 v[44:47], v[164:167], v[184:187], v[44:47]
	v_mfma_f32_16x16x32_bf16 v[44:47], v[168:171], v[188:191], v[44:47]
	v_mfma_f32_16x16x32_bf16 v[40:43], v[176:179], v[184:187], v[40:43]
	v_mfma_f32_16x16x32_bf16 v[40:43], v[180:183], v[188:191], v[40:43]
	v_mfma_f32_16x16x32_bf16 v[28:31], v[164:167], v[192:195], v[28:31]
	v_mfma_f32_16x16x32_bf16 v[28:31], v[168:171], v[196:199], v[28:31]
	v_mfma_f32_16x16x32_bf16 v[24:27], v[176:179], v[192:195], v[24:27]
	v_mfma_f32_16x16x32_bf16 v[24:27], v[180:183], v[196:199], v[24:27]
	v_mfma_f32_16x16x32_bf16 v[12:15], v[164:167], v[200:203], v[12:15]
	v_mfma_f32_16x16x32_bf16 v[12:15], v[168:171], v[204:207], v[12:15]
	v_mfma_f32_16x16x32_bf16 v[8:11], v[176:179], v[200:203], v[8:11]
	v_mfma_f32_16x16x32_bf16 v[8:11], v[180:183], v[204:207], v[8:11]
	v_mfma_f32_16x16x32_bf16 v[4:7], v[164:167], v[208:211], v[4:7]
	v_mfma_f32_16x16x32_bf16 v[4:7], v[168:171], v[212:215], v[4:7]
	v_mfma_f32_16x16x32_bf16 v[0:3], v[176:179], v[208:211], v[0:3]
	v_mfma_f32_16x16x32_bf16 v[0:3], v[180:183], v[212:215], v[0:3]
	s_setprio 0
	s_add_i32 s83, s83, 2
	s_add_u32 s46, s46, 0x100
	s_addc_u32 s47, s47, 0
	s_add_u32 s81, s81, 0x100
	s_addc_u32 s82, s82, 0
	s_cmp_gt_u32 s83, 5
	s_barrier
	s_cbranch_scc0 .LBB0_428
	s_and_b64 vcc, exec, s[40:41]
	s_cbranch_vccz .LBB0_431
	s_barrier

.LBB0_502:
	ds_read_b128 v[128:131], v192
	ds_read_b128 v[132:135], v192 offset:1024
	ds_read_b128 v[136:139], v192 offset:2048
	ds_read_b128 v[140:143], v192 offset:3072
	ds_read_b128 v[144:147], v193
	ds_read_b128 v[148:151], v193 offset:1024
	ds_read_b128 v[168:171], v193 offset:2048
	ds_read_b128 v[196:199], v193 offset:3072
	s_add_u32 s62, s60, 0xfff80080
	s_addc_u32 s63, s61, -1
	s_cmp_eq_u32 s76, 28
	s_cselect_b32 s65, s27, s63
	s_cselect_b32 s64, s45, s62
	s_cselect_b32 s63, s43, s75
	s_cselect_b32 s62, s51, s74
	s_add_i32 m0, s1, 0xc000
	ds_read_b128 v[200:203], v194
	ds_read_b128 v[204:207], v194 offset:1024
	ds_read_b128 v[208:211], v194 offset:2048
	ds_read_b128 v[212:215], v194 offset:3072
	ds_read_b128 v[216:219], v194 offset:4096
	ds_read_b128 v[220:223], v194 offset:5120
	ds_read_b128 v[224:227], v194 offset:6144
	ds_read_b128 v[228:231], v194 offset:7168
	global_load_lds_dwordx4 v160, s[60:61]
	s_add_i32 m0, s1, 0xe000
	s_nop 0
	global_load_lds_dwordx4 v162, s[60:61]
	s_waitcnt vmcnt(8)
	s_waitcnt lgkmcnt(0)
	s_barrier
	s_setprio 1
	s_waitcnt lgkmcnt(0)
	v_mfma_f32_16x16x32_bf16 v[124:127], v[128:131], v[200:203], v[124:127]
	v_mfma_f32_16x16x32_bf16 v[124:127], v[132:135], v[204:207], v[124:127]
	v_mfma_f32_16x16x32_bf16 v[120:123], v[136:139], v[200:203], v[120:123]
	v_mfma_f32_16x16x32_bf16 v[120:123], v[140:143], v[204:207], v[120:123]
	v_mfma_f32_16x16x32_bf16 v[108:111], v[128:131], v[208:211], v[108:111]
	v_mfma_f32_16x16x32_bf16 v[108:111], v[132:135], v[212:215], v[108:111]
	v_mfma_f32_16x16x32_bf16 v[104:107], v[136:139], v[208:211], v[104:107]
	v_mfma_f32_16x16x32_bf16 v[104:107], v[140:143], v[212:215], v[104:107]
	v_mfma_f32_16x16x32_bf16 v[92:95], v[128:131], v[216:219], v[92:95]
	v_mfma_f32_16x16x32_bf16 v[92:95], v[132:135], v[220:223], v[92:95]
	v_mfma_f32_16x16x32_bf16 v[88:91], v[136:139], v[216:219], v[88:91]
	v_mfma_f32_16x16x32_bf16 v[88:91], v[140:143], v[220:223], v[88:91]
	v_mfma_f32_16x16x32_bf16 v[76:79], v[128:131], v[224:227], v[76:79]
	v_mfma_f32_16x16x32_bf16 v[76:79], v[132:135], v[228:231], v[76:79]
	v_mfma_f32_16x16x32_bf16 v[72:75], v[136:139], v[224:227], v[72:75]
	v_mfma_f32_16x16x32_bf16 v[72:75], v[140:143], v[228:231], v[72:75]
	s_setprio 0
	s_setprio 1
	v_mfma_f32_16x16x32_bf16 v[116:119], v[144:147], v[200:203], v[116:119]
	v_mfma_f32_16x16x32_bf16 v[116:119], v[148:151], v[204:207], v[116:119]
	v_mfma_f32_16x16x32_bf16 v[112:115], v[168:171], v[200:203], v[112:115]
	v_mfma_f32_16x16x32_bf16 v[112:115], v[196:199], v[204:207], v[112:115]
	v_mfma_f32_16x16x32_bf16 v[100:103], v[144:147], v[208:211], v[100:103]
	v_mfma_f32_16x16x32_bf16 v[100:103], v[148:151], v[212:215], v[100:103]
	v_mfma_f32_16x16x32_bf16 v[96:99], v[168:171], v[208:211], v[96:99]
	v_mfma_f32_16x16x32_bf16 v[96:99], v[196:199], v[212:215], v[96:99]
	v_mfma_f32_16x16x32_bf16 v[84:87], v[144:147], v[216:219], v[84:87]
	v_mfma_f32_16x16x32_bf16 v[84:87], v[148:151], v[220:223], v[84:87]
	v_mfma_f32_16x16x32_bf16 v[80:83], v[168:171], v[216:219], v[80:83]
	v_mfma_f32_16x16x32_bf16 v[80:83], v[196:199], v[220:223], v[80:83]
	v_mfma_f32_16x16x32_bf16 v[68:71], v[144:147], v[224:227], v[68:71]
	v_mfma_f32_16x16x32_bf16 v[68:71], v[148:151], v[228:231], v[68:71]
	v_mfma_f32_16x16x32_bf16 v[64:67], v[168:171], v[224:227], v[64:67]
	v_mfma_f32_16x16x32_bf16 v[64:67], v[196:199], v[228:231], v[64:67]
	s_setprio 0
	s_barrier
	s_add_i32 s77, s69, s0
	s_add_u32 s98, s62, s38
	s_addc_u32 s99, s63, s39
	s_mov_b32 m0, s77
	ds_read_b128 v[200:203], v194 offset:16384
	ds_read_b128 v[204:207], v194 offset:17408
	ds_read_b128 v[208:211], v194 offset:18432
	ds_read_b128 v[212:215], v194 offset:19456
	ds_read_b128 v[216:219], v194 offset:20480
	ds_read_b128 v[220:223], v194 offset:21504
	ds_read_b128 v[224:227], v194 offset:22528
	ds_read_b128 v[228:231], v194 offset:23552
	global_load_lds_dwordx4 v154, s[62:63]
	s_add_i32 m0, s77, 0x2000
	s_add_u32 s78, s62, 0x80000
	s_addc_u32 s79, s63, 0
	s_add_i32 s77, s73, s0
	global_load_lds_dwordx4 v158, s[62:63]
	s_mov_b32 m0, s77
	s_nop 0
	global_load_lds_dwordx4 v154, s[78:79]
	s_add_i32 m0, s77, 0x2000
	s_nop 0
	global_load_lds_dwordx4 v158, s[78:79]
	s_add_u32 s100, s64, s38
	s_addc_u32 s101, s65, s39
	s_mov_b32 m0, s1
	s_nop 0
	global_load_lds_dwordx4 v152, s[64:65]
	s_mov_b32 m0, s10
	s_nop 0
	global_load_lds_dwordx4 v156, s[64:65]
	s_waitcnt vmcnt(8)
	s_waitcnt lgkmcnt(0)
	s_barrier
	s_setprio 1
	s_waitcnt lgkmcnt(0)
	v_mfma_f32_16x16x32_bf16 v[60:63], v[128:131], v[200:203], v[60:63]
	v_mfma_f32_16x16x32_bf16 v[60:63], v[132:135], v[204:207], v[60:63]
	v_mfma_f32_16x16x32_bf16 v[56:59], v[136:139], v[200:203], v[56:59]
	v_mfma_f32_16x16x32_bf16 v[56:59], v[140:143], v[204:207], v[56:59]
	v_mfma_f32_16x16x32_bf16 v[44:47], v[128:131], v[208:211], v[44:47]
	v_mfma_f32_16x16x32_bf16 v[44:47], v[132:135], v[212:215], v[44:47]
	v_mfma_f32_16x16x32_bf16 v[40:43], v[136:139], v[208:211], v[40:43]
	v_mfma_f32_16x16x32_bf16 v[40:43], v[140:143], v[212:215], v[40:43]
	v_mfma_f32_16x16x32_bf16 v[28:31], v[128:131], v[216:219], v[28:31]
	v_mfma_f32_16x16x32_bf16 v[28:31], v[132:135], v[220:223], v[28:31]
	v_mfma_f32_16x16x32_bf16 v[24:27], v[136:139], v[216:219], v[24:27]
	v_mfma_f32_16x16x32_bf16 v[24:27], v[140:143], v[220:223], v[24:27]
	v_mfma_f32_16x16x32_bf16 v[12:15], v[128:131], v[224:227], v[12:15]
	v_mfma_f32_16x16x32_bf16 v[12:15], v[132:135], v[228:231], v[12:15]
	v_mfma_f32_16x16x32_bf16 v[8:11], v[136:139], v[224:227], v[8:11]
	v_mfma_f32_16x16x32_bf16 v[8:11], v[140:143], v[228:231], v[8:11]
	s_setprio 0
	s_setprio 1
	v_mfma_f32_16x16x32_bf16 v[52:55], v[144:147], v[200:203], v[52:55]
	v_mfma_f32_16x16x32_bf16 v[52:55], v[148:151], v[204:207], v[52:55]
	v_mfma_f32_16x16x32_bf16 v[48:51], v[168:171], v[200:203], v[48:51]
	v_mfma_f32_16x16x32_bf16 v[48:51], v[196:199], v[204:207], v[48:51]
	v_mfma_f32_16x16x32_bf16 v[36:39], v[144:147], v[208:211], v[36:39]
	v_mfma_f32_16x16x32_bf16 v[36:39], v[148:151], v[212:215], v[36:39]
	v_mfma_f32_16x16x32_bf16 v[32:35], v[168:171], v[208:211], v[32:35]
	v_mfma_f32_16x16x32_bf16 v[32:35], v[196:199], v[212:215], v[32:35]
	v_mfma_f32_16x16x32_bf16 v[20:23], v[144:147], v[216:219], v[20:23]
	v_mfma_f32_16x16x32_bf16 v[20:23], v[148:151], v[220:223], v[20:23]
	v_mfma_f32_16x16x32_bf16 v[16:19], v[168:171], v[216:219], v[16:19]
	v_mfma_f32_16x16x32_bf16 v[16:19], v[196:199], v[220:223], v[16:19]
	v_mfma_f32_16x16x32_bf16 v[4:7], v[144:147], v[224:227], v[4:7]
	v_mfma_f32_16x16x32_bf16 v[4:7], v[148:151], v[228:231], v[4:7]
	v_mfma_f32_16x16x32_bf16 v[0:3], v[168:171], v[224:227], v[0:3]
	v_mfma_f32_16x16x32_bf16 v[0:3], v[196:199], v[228:231], v[0:3]
	s_setprio 0
	s_barrier
	s_add_i32 s77, 0, 0x18000
	s_add_i32 s78, 0, 0x1c000
	v_add_u32_e32 v140, s77, v177
	v_add_u32_e32 v196, s78, v177
	ds_read_b128 v[128:131], v140
	ds_read_b128 v[132:135], v140 offset:1024
	ds_read_b128 v[136:139], v140 offset:2048
	ds_read_b128 v[140:143], v140 offset:3072
	ds_read_b128 v[144:147], v196
	ds_read_b128 v[148:151], v196 offset:1024
	ds_read_b128 v[168:171], v196 offset:2048
	ds_read_b128 v[196:199], v196 offset:3072
	s_add_u32 s64, s64, 0x80000
	s_addc_u32 s65, s65, 0
	s_mov_b32 m0, s11
	ds_read_b128 v[200:203], v194 offset:32768
	ds_read_b128 v[204:207], v194 offset:33792
	ds_read_b128 v[208:211], v194 offset:34816
	ds_read_b128 v[212:215], v194 offset:35840
	ds_read_b128 v[216:219], v194 offset:36864
	ds_read_b128 v[220:223], v194 offset:37888
	ds_read_b128 v[224:227], v194 offset:38912
	ds_read_b128 v[228:231], v194 offset:39936
	global_load_lds_dwordx4 v152, s[64:65]
	s_mov_b32 m0, s14
	s_nop 0
	global_load_lds_dwordx4 v156, s[64:65]
	s_waitcnt vmcnt(8)
	s_waitcnt lgkmcnt(0)
	s_barrier
	s_setprio 1
	s_waitcnt lgkmcnt(0)
	v_mfma_f32_16x16x32_bf16 v[124:127], v[128:131], v[200:203], v[124:127]
	v_mfma_f32_16x16x32_bf16 v[124:127], v[132:135], v[204:207], v[124:127]
	v_mfma_f32_16x16x32_bf16 v[120:123], v[136:139], v[200:203], v[120:123]
	v_mfma_f32_16x16x32_bf16 v[120:123], v[140:143], v[204:207], v[120:123]
	v_mfma_f32_16x16x32_bf16 v[108:111], v[128:131], v[208:211], v[108:111]
	v_mfma_f32_16x16x32_bf16 v[108:111], v[132:135], v[212:215], v[108:111]
	v_mfma_f32_16x16x32_bf16 v[104:107], v[136:139], v[208:211], v[104:107]
	v_mfma_f32_16x16x32_bf16 v[104:107], v[140:143], v[212:215], v[104:107]
	v_mfma_f32_16x16x32_bf16 v[92:95], v[128:131], v[216:219], v[92:95]
	v_mfma_f32_16x16x32_bf16 v[92:95], v[132:135], v[220:223], v[92:95]
	v_mfma_f32_16x16x32_bf16 v[88:91], v[136:139], v[216:219], v[88:91]
	v_mfma_f32_16x16x32_bf16 v[88:91], v[140:143], v[220:223], v[88:91]
	v_mfma_f32_16x16x32_bf16 v[76:79], v[128:131], v[224:227], v[76:79]
	v_mfma_f32_16x16x32_bf16 v[76:79], v[132:135], v[228:231], v[76:79]
	v_mfma_f32_16x16x32_bf16 v[72:75], v[136:139], v[224:227], v[72:75]
	v_mfma_f32_16x16x32_bf16 v[72:75], v[140:143], v[228:231], v[72:75]
	s_setprio 0
	s_setprio 1
	v_mfma_f32_16x16x32_bf16 v[116:119], v[144:147], v[200:203], v[116:119]
	v_mfma_f32_16x16x32_bf16 v[116:119], v[148:151], v[204:207], v[116:119]
	v_mfma_f32_16x16x32_bf16 v[112:115], v[168:171], v[200:203], v[112:115]
	v_mfma_f32_16x16x32_bf16 v[112:115], v[196:199], v[204:207], v[112:115]
	v_mfma_f32_16x16x32_bf16 v[100:103], v[144:147], v[208:211], v[100:103]
	v_mfma_f32_16x16x32_bf16 v[100:103], v[148:151], v[212:215], v[100:103]
	v_mfma_f32_16x16x32_bf16 v[96:99], v[168:171], v[208:211], v[96:99]
	v_mfma_f32_16x16x32_bf16 v[96:99], v[196:199], v[212:215], v[96:99]
	v_mfma_f32_16x16x32_bf16 v[84:87], v[144:147], v[216:219], v[84:87]
	v_mfma_f32_16x16x32_bf16 v[84:87], v[148:151], v[220:223], v[84:87]
	v_mfma_f32_16x16x32_bf16 v[80:83], v[168:171], v[216:219], v[80:83]
	v_mfma_f32_16x16x32_bf16 v[80:83], v[196:199], v[220:223], v[80:83]
	v_mfma_f32_16x16x32_bf16 v[68:71], v[144:147], v[224:227], v[68:71]
	v_mfma_f32_16x16x32_bf16 v[68:71], v[148:151], v[228:231], v[68:71]
	v_mfma_f32_16x16x32_bf16 v[64:67], v[168:171], v[224:227], v[64:67]
	v_mfma_f32_16x16x32_bf16 v[64:67], v[196:199], v[228:231], v[64:67]
	s_setprio 0
	s_barrier
	s_add_i32 s64, s77, s0
	s_mov_b32 m0, s64
	ds_read_b128 v[200:203], v194 offset:49152
	ds_read_b128 v[204:207], v194 offset:50176
	ds_read_b128 v[208:211], v194 offset:51200
	ds_read_b128 v[212:215], v194 offset:52224
	ds_read_b128 v[216:219], v194 offset:53248
	ds_read_b128 v[220:223], v194 offset:54272
	ds_read_b128 v[224:227], v194 offset:55296
	ds_read_b128 v[228:231], v194 offset:56320
	global_load_lds_dwordx4 v154, s[98:99]
	s_add_i32 m0, s64, 0x2000
	s_add_u32 s62, s62, 0x80080
	s_addc_u32 s63, s63, 0
	s_add_i32 s64, s78, s0
	global_load_lds_dwordx4 v158, s[98:99]
	s_mov_b32 m0, s64
	s_nop 0
	global_load_lds_dwordx4 v154, s[62:63]
	s_add_i32 m0, s64, 0x2000
	s_nop 0
	global_load_lds_dwordx4 v158, s[62:63]
	s_mov_b32 m0, s33
	s_nop 0
	global_load_lds_dwordx4 v152, s[100:101]
	s_mov_b32 m0, s68
	s_nop 0
	global_load_lds_dwordx4 v156, s[100:101]
	s_waitcnt vmcnt(8)
	s_waitcnt lgkmcnt(0)
	s_barrier
	s_setprio 1
	s_waitcnt lgkmcnt(0)
	v_mfma_f32_16x16x32_bf16 v[60:63], v[128:131], v[200:203], v[60:63]
	v_mfma_f32_16x16x32_bf16 v[60:63], v[132:135], v[204:207], v[60:63]
	v_mfma_f32_16x16x32_bf16 v[56:59], v[136:139], v[200:203], v[56:59]
	v_mfma_f32_16x16x32_bf16 v[56:59], v[140:143], v[204:207], v[56:59]
	v_mfma_f32_16x16x32_bf16 v[44:47], v[128:131], v[208:211], v[44:47]
	v_mfma_f32_16x16x32_bf16 v[44:47], v[132:135], v[212:215], v[44:47]
	v_mfma_f32_16x16x32_bf16 v[40:43], v[136:139], v[208:211], v[40:43]
	v_mfma_f32_16x16x32_bf16 v[40:43], v[140:143], v[212:215], v[40:43]
	v_mfma_f32_16x16x32_bf16 v[28:31], v[128:131], v[216:219], v[28:31]
	v_mfma_f32_16x16x32_bf16 v[28:31], v[132:135], v[220:223], v[28:31]
	v_mfma_f32_16x16x32_bf16 v[24:27], v[136:139], v[216:219], v[24:27]
	v_mfma_f32_16x16x32_bf16 v[24:27], v[140:143], v[220:223], v[24:27]
	v_mfma_f32_16x16x32_bf16 v[12:15], v[128:131], v[224:227], v[12:15]
	v_mfma_f32_16x16x32_bf16 v[12:15], v[132:135], v[228:231], v[12:15]
	v_mfma_f32_16x16x32_bf16 v[8:11], v[136:139], v[224:227], v[8:11]
	v_mfma_f32_16x16x32_bf16 v[8:11], v[140:143], v[228:231], v[8:11]
	s_setprio 0
	s_setprio 1
	v_mfma_f32_16x16x32_bf16 v[52:55], v[144:147], v[200:203], v[52:55]
	v_mfma_f32_16x16x32_bf16 v[52:55], v[148:151], v[204:207], v[52:55]
	v_mfma_f32_16x16x32_bf16 v[48:51], v[168:171], v[200:203], v[48:51]
	v_mfma_f32_16x16x32_bf16 v[48:51], v[196:199], v[204:207], v[48:51]
	v_mfma_f32_16x16x32_bf16 v[36:39], v[144:147], v[208:211], v[36:39]
	v_mfma_f32_16x16x32_bf16 v[36:39], v[148:151], v[212:215], v[36:39]
	v_mfma_f32_16x16x32_bf16 v[32:35], v[168:171], v[208:211], v[32:35]
	v_mfma_f32_16x16x32_bf16 v[32:35], v[196:199], v[212:215], v[32:35]
	v_mfma_f32_16x16x32_bf16 v[20:23], v[144:147], v[216:219], v[20:23]
	v_mfma_f32_16x16x32_bf16 v[20:23], v[148:151], v[220:223], v[20:23]
	v_mfma_f32_16x16x32_bf16 v[16:19], v[168:171], v[216:219], v[16:19]
	v_mfma_f32_16x16x32_bf16 v[16:19], v[196:199], v[220:223], v[16:19]
	v_mfma_f32_16x16x32_bf16 v[4:7], v[144:147], v[224:227], v[4:7]
	v_mfma_f32_16x16x32_bf16 v[4:7], v[148:151], v[228:231], v[4:7]
	v_mfma_f32_16x16x32_bf16 v[0:3], v[168:171], v[224:227], v[0:3]
	v_mfma_f32_16x16x32_bf16 v[0:3], v[196:199], v[228:231], v[0:3]
	s_setprio 0
	s_add_i32 s76, s76, 2
	s_add_u32 s60, s60, 0x100
	s_addc_u32 s61, s61, 0
	s_add_u32 s74, s74, 0x100
	s_addc_u32 s75, s75, 0
	s_cmp_gt_u32 s76, 29
	s_barrier
	s_cbranch_scc0 .LBB0_502
	s_and_b64 vcc, exec, s[40:41]
	s_cbranch_vccz .LBB0_505
	s_barrier

.LBB0_596:
	ds_read_b128 v[142:145], v159
	ds_read_b128 v[146:149], v159 offset:1024
	ds_read_b128 v[150:153], v159 offset:2048
	ds_read_b128 v[154:157], v159 offset:3072
	ds_read_b128 v[166:169], v160
	ds_read_b128 v[170:173], v160 offset:1024
	ds_read_b128 v[176:179], v160 offset:2048
	ds_read_b128 v[180:183], v160 offset:3072
	s_add_u32 s50, s48, 0xfff80080
	s_addc_u32 s51, s49, -1
	s_cmp_eq_u32 s76, 28
	s_cselect_b32 s61, s39, s51
	s_cselect_b32 s60, s47, s50
	s_cselect_b32 s51, s72, s75
	s_cselect_b32 s50, s73, s74
	s_add_i32 m0, s1, 0xc000
	ds_read_b128 v[184:187], v161
	ds_read_b128 v[188:191], v161 offset:1024
	ds_read_b128 v[192:195], v161 offset:2048
	ds_read_b128 v[196:199], v161 offset:3072
	ds_read_b128 v[200:203], v161 offset:4096
	ds_read_b128 v[204:207], v161 offset:5120
	ds_read_b128 v[208:211], v161 offset:6144
	ds_read_b128 v[212:215], v161 offset:7168
	global_load_lds_dwordx4 v138, s[48:49]
	s_add_i32 m0, s1, 0xe000
	s_nop 0
	global_load_lds_dwordx4 v140, s[48:49]
	s_waitcnt vmcnt(8)
	s_waitcnt lgkmcnt(0)
	s_barrier
	s_setprio 1
	s_waitcnt lgkmcnt(0)
	v_mfma_f32_16x16x32_bf16 v[124:127], v[142:145], v[184:187], v[124:127]
	v_mfma_f32_16x16x32_bf16 v[124:127], v[146:149], v[188:191], v[124:127]
	v_mfma_f32_16x16x32_bf16 v[120:123], v[150:153], v[184:187], v[120:123]
	v_mfma_f32_16x16x32_bf16 v[120:123], v[154:157], v[188:191], v[120:123]
	v_mfma_f32_16x16x32_bf16 v[108:111], v[142:145], v[192:195], v[108:111]
	v_mfma_f32_16x16x32_bf16 v[108:111], v[146:149], v[196:199], v[108:111]
	v_mfma_f32_16x16x32_bf16 v[104:107], v[150:153], v[192:195], v[104:107]
	v_mfma_f32_16x16x32_bf16 v[104:107], v[154:157], v[196:199], v[104:107]
	v_mfma_f32_16x16x32_bf16 v[92:95], v[142:145], v[200:203], v[92:95]
	v_mfma_f32_16x16x32_bf16 v[92:95], v[146:149], v[204:207], v[92:95]
	v_mfma_f32_16x16x32_bf16 v[88:91], v[150:153], v[200:203], v[88:91]
	v_mfma_f32_16x16x32_bf16 v[88:91], v[154:157], v[204:207], v[88:91]
	v_mfma_f32_16x16x32_bf16 v[76:79], v[142:145], v[208:211], v[76:79]
	v_mfma_f32_16x16x32_bf16 v[76:79], v[146:149], v[212:215], v[76:79]
	v_mfma_f32_16x16x32_bf16 v[72:75], v[150:153], v[208:211], v[72:75]
	v_mfma_f32_16x16x32_bf16 v[72:75], v[154:157], v[212:215], v[72:75]
	s_setprio 0
	s_setprio 1
	v_mfma_f32_16x16x32_bf16 v[116:119], v[166:169], v[184:187], v[116:119]
	v_mfma_f32_16x16x32_bf16 v[116:119], v[170:173], v[188:191], v[116:119]
	v_mfma_f32_16x16x32_bf16 v[112:115], v[176:179], v[184:187], v[112:115]
	v_mfma_f32_16x16x32_bf16 v[112:115], v[180:183], v[188:191], v[112:115]
	v_mfma_f32_16x16x32_bf16 v[100:103], v[166:169], v[192:195], v[100:103]
	v_mfma_f32_16x16x32_bf16 v[100:103], v[170:173], v[196:199], v[100:103]
	v_mfma_f32_16x16x32_bf16 v[96:99], v[176:179], v[192:195], v[96:99]
	v_mfma_f32_16x16x32_bf16 v[96:99], v[180:183], v[196:199], v[96:99]
	v_mfma_f32_16x16x32_bf16 v[84:87], v[166:169], v[200:203], v[84:87]
	v_mfma_f32_16x16x32_bf16 v[84:87], v[170:173], v[204:207], v[84:87]
	v_mfma_f32_16x16x32_bf16 v[80:83], v[176:179], v[200:203], v[80:83]
	v_mfma_f32_16x16x32_bf16 v[80:83], v[180:183], v[204:207], v[80:83]
	v_mfma_f32_16x16x32_bf16 v[68:71], v[166:169], v[208:211], v[68:71]
	v_mfma_f32_16x16x32_bf16 v[68:71], v[170:173], v[212:215], v[68:71]
	v_mfma_f32_16x16x32_bf16 v[64:67], v[176:179], v[208:211], v[64:67]
	v_mfma_f32_16x16x32_bf16 v[64:67], v[180:183], v[212:215], v[64:67]
	s_setprio 0
	s_barrier
	s_add_i32 s77, s64, s0
	s_add_u32 s98, s50, s34
	s_addc_u32 s99, s51, s35
	s_mov_b32 m0, s77
	ds_read_b128 v[184:187], v161 offset:16384
	ds_read_b128 v[188:191], v161 offset:17408
	ds_read_b128 v[192:195], v161 offset:18432
	ds_read_b128 v[196:199], v161 offset:19456
	ds_read_b128 v[200:203], v161 offset:20480
	ds_read_b128 v[204:207], v161 offset:21504
	ds_read_b128 v[208:211], v161 offset:22528
	ds_read_b128 v[212:215], v161 offset:23552
	global_load_lds_dwordx4 v130, s[50:51]
	s_add_i32 m0, s77, 0x2000
	s_add_u32 s78, s50, 0x80000
	s_addc_u32 s79, s51, 0
	s_add_i32 s77, s65, s0
	global_load_lds_dwordx4 v134, s[50:51]
	s_mov_b32 m0, s77
	s_nop 0
	global_load_lds_dwordx4 v130, s[78:79]
	s_add_i32 m0, s77, 0x2000
	s_nop 0
	global_load_lds_dwordx4 v134, s[78:79]
	s_add_u32 s100, s60, s34
	s_addc_u32 s101, s61, s35
	s_mov_b32 m0, s1
	s_nop 0
	global_load_lds_dwordx4 v128, s[60:61]
	s_mov_b32 m0, s10
	s_nop 0
	global_load_lds_dwordx4 v132, s[60:61]
	s_waitcnt vmcnt(8)
	s_waitcnt lgkmcnt(0)
	s_barrier
	s_setprio 1
	s_waitcnt lgkmcnt(0)
	v_mfma_f32_16x16x32_bf16 v[60:63], v[142:145], v[184:187], v[60:63]
	v_mfma_f32_16x16x32_bf16 v[60:63], v[146:149], v[188:191], v[60:63]
	v_mfma_f32_16x16x32_bf16 v[56:59], v[150:153], v[184:187], v[56:59]
	v_mfma_f32_16x16x32_bf16 v[56:59], v[154:157], v[188:191], v[56:59]
	v_mfma_f32_16x16x32_bf16 v[44:47], v[142:145], v[192:195], v[44:47]
	v_mfma_f32_16x16x32_bf16 v[44:47], v[146:149], v[196:199], v[44:47]
	v_mfma_f32_16x16x32_bf16 v[40:43], v[150:153], v[192:195], v[40:43]
	v_mfma_f32_16x16x32_bf16 v[40:43], v[154:157], v[196:199], v[40:43]
	v_mfma_f32_16x16x32_bf16 v[28:31], v[142:145], v[200:203], v[28:31]
	v_mfma_f32_16x16x32_bf16 v[28:31], v[146:149], v[204:207], v[28:31]
	v_mfma_f32_16x16x32_bf16 v[24:27], v[150:153], v[200:203], v[24:27]
	v_mfma_f32_16x16x32_bf16 v[24:27], v[154:157], v[204:207], v[24:27]
	v_mfma_f32_16x16x32_bf16 v[12:15], v[142:145], v[208:211], v[12:15]
	v_mfma_f32_16x16x32_bf16 v[12:15], v[146:149], v[212:215], v[12:15]
	v_mfma_f32_16x16x32_bf16 v[8:11], v[150:153], v[208:211], v[8:11]
	v_mfma_f32_16x16x32_bf16 v[8:11], v[154:157], v[212:215], v[8:11]
	s_setprio 0
	s_setprio 1
	v_mfma_f32_16x16x32_bf16 v[52:55], v[166:169], v[184:187], v[52:55]
	v_mfma_f32_16x16x32_bf16 v[52:55], v[170:173], v[188:191], v[52:55]
	v_mfma_f32_16x16x32_bf16 v[48:51], v[176:179], v[184:187], v[48:51]
	v_mfma_f32_16x16x32_bf16 v[48:51], v[180:183], v[188:191], v[48:51]
	v_mfma_f32_16x16x32_bf16 v[36:39], v[166:169], v[192:195], v[36:39]
	v_mfma_f32_16x16x32_bf16 v[36:39], v[170:173], v[196:199], v[36:39]
	v_mfma_f32_16x16x32_bf16 v[32:35], v[176:179], v[192:195], v[32:35]
	v_mfma_f32_16x16x32_bf16 v[32:35], v[180:183], v[196:199], v[32:35]
	v_mfma_f32_16x16x32_bf16 v[20:23], v[166:169], v[200:203], v[20:23]
	v_mfma_f32_16x16x32_bf16 v[20:23], v[170:173], v[204:207], v[20:23]
	v_mfma_f32_16x16x32_bf16 v[16:19], v[176:179], v[200:203], v[16:19]
	v_mfma_f32_16x16x32_bf16 v[16:19], v[180:183], v[204:207], v[16:19]
	v_mfma_f32_16x16x32_bf16 v[4:7], v[166:169], v[208:211], v[4:7]
	v_mfma_f32_16x16x32_bf16 v[4:7], v[170:173], v[212:215], v[4:7]
	v_mfma_f32_16x16x32_bf16 v[0:3], v[176:179], v[208:211], v[0:3]
	v_mfma_f32_16x16x32_bf16 v[0:3], v[180:183], v[212:215], v[0:3]
	s_setprio 0
	s_barrier
	s_add_i32 s77, 0, 0x18000
	v_add_u32_e32 v136, s77, v158
	s_add_i32 s78, 0, 0x1c000
	ds_read_b128 v[142:145], v136
	ds_read_b128 v[146:149], v136 offset:1024
	ds_read_b128 v[150:153], v136 offset:2048
	ds_read_b128 v[154:157], v136 offset:3072
	v_add_u32_e32 v136, s78, v158
	ds_read_b128 v[166:169], v136
	ds_read_b128 v[170:173], v136 offset:1024
	ds_read_b128 v[176:179], v136 offset:2048
	ds_read_b128 v[180:183], v136 offset:3072
	s_add_u32 s60, s60, 0x80000
	s_addc_u32 s61, s61, 0
	s_mov_b32 m0, s11
	ds_read_b128 v[184:187], v161 offset:32768
	ds_read_b128 v[188:191], v161 offset:33792
	ds_read_b128 v[192:195], v161 offset:34816
	ds_read_b128 v[196:199], v161 offset:35840
	ds_read_b128 v[200:203], v161 offset:36864
	ds_read_b128 v[204:207], v161 offset:37888
	ds_read_b128 v[208:211], v161 offset:38912
	ds_read_b128 v[212:215], v161 offset:39936
	global_load_lds_dwordx4 v128, s[60:61]
	s_mov_b32 m0, s14
	s_nop 0
	global_load_lds_dwordx4 v132, s[60:61]
	s_waitcnt vmcnt(8)
	s_waitcnt lgkmcnt(0)
	s_barrier
	s_setprio 1
	s_waitcnt lgkmcnt(0)
	v_mfma_f32_16x16x32_bf16 v[124:127], v[142:145], v[184:187], v[124:127]
	v_mfma_f32_16x16x32_bf16 v[124:127], v[146:149], v[188:191], v[124:127]
	v_mfma_f32_16x16x32_bf16 v[120:123], v[150:153], v[184:187], v[120:123]
	v_mfma_f32_16x16x32_bf16 v[120:123], v[154:157], v[188:191], v[120:123]
	v_mfma_f32_16x16x32_bf16 v[108:111], v[142:145], v[192:195], v[108:111]
	v_mfma_f32_16x16x32_bf16 v[108:111], v[146:149], v[196:199], v[108:111]
	v_mfma_f32_16x16x32_bf16 v[104:107], v[150:153], v[192:195], v[104:107]
	v_mfma_f32_16x16x32_bf16 v[104:107], v[154:157], v[196:199], v[104:107]
	v_mfma_f32_16x16x32_bf16 v[92:95], v[142:145], v[200:203], v[92:95]
	v_mfma_f32_16x16x32_bf16 v[92:95], v[146:149], v[204:207], v[92:95]
	v_mfma_f32_16x16x32_bf16 v[88:91], v[150:153], v[200:203], v[88:91]
	v_mfma_f32_16x16x32_bf16 v[88:91], v[154:157], v[204:207], v[88:91]
	v_mfma_f32_16x16x32_bf16 v[76:79], v[142:145], v[208:211], v[76:79]
	v_mfma_f32_16x16x32_bf16 v[76:79], v[146:149], v[212:215], v[76:79]
	v_mfma_f32_16x16x32_bf16 v[72:75], v[150:153], v[208:211], v[72:75]
	v_mfma_f32_16x16x32_bf16 v[72:75], v[154:157], v[212:215], v[72:75]
	s_setprio 0
	s_setprio 1
	v_mfma_f32_16x16x32_bf16 v[116:119], v[166:169], v[184:187], v[116:119]
	v_mfma_f32_16x16x32_bf16 v[116:119], v[170:173], v[188:191], v[116:119]
	v_mfma_f32_16x16x32_bf16 v[112:115], v[176:179], v[184:187], v[112:115]
	v_mfma_f32_16x16x32_bf16 v[112:115], v[180:183], v[188:191], v[112:115]
	v_mfma_f32_16x16x32_bf16 v[100:103], v[166:169], v[192:195], v[100:103]
	v_mfma_f32_16x16x32_bf16 v[100:103], v[170:173], v[196:199], v[100:103]
	v_mfma_f32_16x16x32_bf16 v[96:99], v[176:179], v[192:195], v[96:99]
	v_mfma_f32_16x16x32_bf16 v[96:99], v[180:183], v[196:199], v[96:99]
	v_mfma_f32_16x16x32_bf16 v[84:87], v[166:169], v[200:203], v[84:87]
	v_mfma_f32_16x16x32_bf16 v[84:87], v[170:173], v[204:207], v[84:87]
	v_mfma_f32_16x16x32_bf16 v[80:83], v[176:179], v[200:203], v[80:83]
	v_mfma_f32_16x16x32_bf16 v[80:83], v[180:183], v[204:207], v[80:83]
	v_mfma_f32_16x16x32_bf16 v[68:71], v[166:169], v[208:211], v[68:71]
	v_mfma_f32_16x16x32_bf16 v[68:71], v[170:173], v[212:215], v[68:71]
	v_mfma_f32_16x16x32_bf16 v[64:67], v[176:179], v[208:211], v[64:67]
	v_mfma_f32_16x16x32_bf16 v[64:67], v[180:183], v[212:215], v[64:67]
	s_setprio 0
	s_barrier
	s_add_i32 s60, s77, s0
	s_mov_b32 m0, s60
	ds_read_b128 v[184:187], v161 offset:49152
	ds_read_b128 v[188:191], v161 offset:50176
	ds_read_b128 v[192:195], v161 offset:51200
	ds_read_b128 v[196:199], v161 offset:52224
	ds_read_b128 v[200:203], v161 offset:53248
	ds_read_b128 v[204:207], v161 offset:54272
	ds_read_b128 v[208:211], v161 offset:55296
	ds_read_b128 v[212:215], v161 offset:56320
	global_load_lds_dwordx4 v130, s[98:99]
	s_add_i32 m0, s60, 0x2000
	s_add_u32 s50, s50, 0x80080
	s_addc_u32 s51, s51, 0
	s_add_i32 s60, s78, s0
	global_load_lds_dwordx4 v134, s[98:99]
	s_mov_b32 m0, s60
	s_nop 0
	global_load_lds_dwordx4 v130, s[50:51]
	s_add_i32 m0, s60, 0x2000
	s_nop 0
	global_load_lds_dwordx4 v134, s[50:51]
	s_mov_b32 m0, s15
	s_nop 0
	global_load_lds_dwordx4 v128, s[100:101]
	s_mov_b32 m0, s33
	s_nop 0
	global_load_lds_dwordx4 v132, s[100:101]
	s_waitcnt vmcnt(8)
	s_waitcnt lgkmcnt(0)
	s_barrier
	s_setprio 1
	s_waitcnt lgkmcnt(0)
	v_mfma_f32_16x16x32_bf16 v[60:63], v[142:145], v[184:187], v[60:63]
	v_mfma_f32_16x16x32_bf16 v[60:63], v[146:149], v[188:191], v[60:63]
	v_mfma_f32_16x16x32_bf16 v[56:59], v[150:153], v[184:187], v[56:59]
	v_mfma_f32_16x16x32_bf16 v[56:59], v[154:157], v[188:191], v[56:59]
	v_mfma_f32_16x16x32_bf16 v[44:47], v[142:145], v[192:195], v[44:47]
	v_mfma_f32_16x16x32_bf16 v[44:47], v[146:149], v[196:199], v[44:47]
	v_mfma_f32_16x16x32_bf16 v[40:43], v[150:153], v[192:195], v[40:43]
	v_mfma_f32_16x16x32_bf16 v[40:43], v[154:157], v[196:199], v[40:43]
	v_mfma_f32_16x16x32_bf16 v[28:31], v[142:145], v[200:203], v[28:31]
	v_mfma_f32_16x16x32_bf16 v[28:31], v[146:149], v[204:207], v[28:31]
	v_mfma_f32_16x16x32_bf16 v[24:27], v[150:153], v[200:203], v[24:27]
	v_mfma_f32_16x16x32_bf16 v[24:27], v[154:157], v[204:207], v[24:27]
	v_mfma_f32_16x16x32_bf16 v[12:15], v[142:145], v[208:211], v[12:15]
	v_mfma_f32_16x16x32_bf16 v[12:15], v[146:149], v[212:215], v[12:15]
	v_mfma_f32_16x16x32_bf16 v[8:11], v[150:153], v[208:211], v[8:11]
	v_mfma_f32_16x16x32_bf16 v[8:11], v[154:157], v[212:215], v[8:11]
	s_setprio 0
	s_setprio 1
	v_mfma_f32_16x16x32_bf16 v[52:55], v[166:169], v[184:187], v[52:55]
	v_mfma_f32_16x16x32_bf16 v[52:55], v[170:173], v[188:191], v[52:55]
	v_mfma_f32_16x16x32_bf16 v[48:51], v[176:179], v[184:187], v[48:51]
	v_mfma_f32_16x16x32_bf16 v[48:51], v[180:183], v[188:191], v[48:51]
	v_mfma_f32_16x16x32_bf16 v[36:39], v[166:169], v[192:195], v[36:39]
	v_mfma_f32_16x16x32_bf16 v[36:39], v[170:173], v[196:199], v[36:39]
	v_mfma_f32_16x16x32_bf16 v[32:35], v[176:179], v[192:195], v[32:35]
	v_mfma_f32_16x16x32_bf16 v[32:35], v[180:183], v[196:199], v[32:35]
	v_mfma_f32_16x16x32_bf16 v[20:23], v[166:169], v[200:203], v[20:23]
	v_mfma_f32_16x16x32_bf16 v[20:23], v[170:173], v[204:207], v[20:23]
	v_mfma_f32_16x16x32_bf16 v[16:19], v[176:179], v[200:203], v[16:19]
	v_mfma_f32_16x16x32_bf16 v[16:19], v[180:183], v[204:207], v[16:19]
	v_mfma_f32_16x16x32_bf16 v[4:7], v[166:169], v[208:211], v[4:7]
	v_mfma_f32_16x16x32_bf16 v[4:7], v[170:173], v[212:215], v[4:7]
	v_mfma_f32_16x16x32_bf16 v[0:3], v[176:179], v[208:211], v[0:3]
	v_mfma_f32_16x16x32_bf16 v[0:3], v[180:183], v[212:215], v[0:3]
	s_setprio 0
	s_add_i32 s76, s76, 2
	s_add_u32 s48, s48, 0x100
	s_addc_u32 s49, s49, 0
	s_add_u32 s74, s74, 0x100
	s_addc_u32 s75, s75, 0
	s_cmp_gt_u32 s76, 29
	s_barrier
	s_cbranch_scc0 .LBB0_596
	s_and_b64 vcc, exec, s[36:37]
	s_cbranch_vccz .LBB0_599
	s_barrier

.LBB0_707:
	ds_read_b128 v[128:131], v188
	ds_read_b128 v[132:135], v188 offset:1024
	ds_read_b128 v[136:139], v188 offset:2048
	ds_read_b128 v[140:143], v188 offset:3072
	ds_read_b128 v[144:147], v189
	ds_read_b128 v[148:151], v189 offset:1024
	ds_read_b128 v[164:167], v189 offset:2048
	ds_read_b128 v[192:195], v189 offset:3072
	s_add_u32 s60, s50, 0xfffc0080
	s_addc_u32 s61, s51, -1
	s_cmp_eq_u32 s73, 12
	s_cselect_b32 s63, s27, s61
	s_cselect_b32 s62, s41, s60
	s_cselect_b32 s61, s49, s72
	s_cselect_b32 s60, s70, s71
	s_add_i32 m0, s1, 0xc000
	ds_read_b128 v[196:199], v190
	ds_read_b128 v[200:203], v190 offset:1024
	ds_read_b128 v[204:207], v190 offset:2048
	ds_read_b128 v[208:211], v190 offset:3072
	ds_read_b128 v[212:215], v190 offset:4096
	ds_read_b128 v[216:219], v190 offset:5120
	ds_read_b128 v[220:223], v190 offset:6144
	ds_read_b128 v[224:227], v190 offset:7168
	global_load_lds_dwordx4 v160, s[50:51]
	s_add_i32 m0, s1, 0xe000
	s_nop 0
	global_load_lds_dwordx4 v162, s[50:51]
	s_waitcnt vmcnt(8)
	s_waitcnt lgkmcnt(0)
	s_barrier
	s_setprio 1
	s_waitcnt lgkmcnt(0)
	v_mfma_f32_16x16x32_bf16 v[124:127], v[128:131], v[196:199], v[124:127]
	v_mfma_f32_16x16x32_bf16 v[124:127], v[132:135], v[200:203], v[124:127]
	v_mfma_f32_16x16x32_bf16 v[120:123], v[136:139], v[196:199], v[120:123]
	v_mfma_f32_16x16x32_bf16 v[120:123], v[140:143], v[200:203], v[120:123]
	v_mfma_f32_16x16x32_bf16 v[108:111], v[128:131], v[204:207], v[108:111]
	v_mfma_f32_16x16x32_bf16 v[108:111], v[132:135], v[208:211], v[108:111]
	v_mfma_f32_16x16x32_bf16 v[104:107], v[136:139], v[204:207], v[104:107]
	v_mfma_f32_16x16x32_bf16 v[104:107], v[140:143], v[208:211], v[104:107]
	v_mfma_f32_16x16x32_bf16 v[92:95], v[128:131], v[212:215], v[92:95]
	v_mfma_f32_16x16x32_bf16 v[92:95], v[132:135], v[216:219], v[92:95]
	v_mfma_f32_16x16x32_bf16 v[88:91], v[136:139], v[212:215], v[88:91]
	v_mfma_f32_16x16x32_bf16 v[88:91], v[140:143], v[216:219], v[88:91]
	v_mfma_f32_16x16x32_bf16 v[76:79], v[128:131], v[220:223], v[76:79]
	v_mfma_f32_16x16x32_bf16 v[76:79], v[132:135], v[224:227], v[76:79]
	v_mfma_f32_16x16x32_bf16 v[72:75], v[136:139], v[220:223], v[72:75]
	v_mfma_f32_16x16x32_bf16 v[72:75], v[140:143], v[224:227], v[72:75]
	s_setprio 0
	s_setprio 1
	v_mfma_f32_16x16x32_bf16 v[116:119], v[144:147], v[196:199], v[116:119]
	v_mfma_f32_16x16x32_bf16 v[116:119], v[148:151], v[200:203], v[116:119]
	v_mfma_f32_16x16x32_bf16 v[112:115], v[164:167], v[196:199], v[112:115]
	v_mfma_f32_16x16x32_bf16 v[112:115], v[192:195], v[200:203], v[112:115]
	v_mfma_f32_16x16x32_bf16 v[100:103], v[144:147], v[204:207], v[100:103]
	v_mfma_f32_16x16x32_bf16 v[100:103], v[148:151], v[208:211], v[100:103]
	v_mfma_f32_16x16x32_bf16 v[96:99], v[164:167], v[204:207], v[96:99]
	v_mfma_f32_16x16x32_bf16 v[96:99], v[192:195], v[208:211], v[96:99]
	v_mfma_f32_16x16x32_bf16 v[84:87], v[144:147], v[212:215], v[84:87]
	v_mfma_f32_16x16x32_bf16 v[84:87], v[148:151], v[216:219], v[84:87]
	v_mfma_f32_16x16x32_bf16 v[80:83], v[164:167], v[212:215], v[80:83]
	v_mfma_f32_16x16x32_bf16 v[80:83], v[192:195], v[216:219], v[80:83]
	v_mfma_f32_16x16x32_bf16 v[68:71], v[144:147], v[220:223], v[68:71]
	v_mfma_f32_16x16x32_bf16 v[68:71], v[148:151], v[224:227], v[68:71]
	v_mfma_f32_16x16x32_bf16 v[64:67], v[164:167], v[220:223], v[64:67]
	v_mfma_f32_16x16x32_bf16 v[64:67], v[192:195], v[224:227], v[64:67]
	s_setprio 0
	s_barrier
	s_add_i32 s74, s66, s0
	s_add_u32 s98, s60, s36
	s_addc_u32 s99, s61, s37
	s_mov_b32 m0, s74
	ds_read_b128 v[196:199], v190 offset:16384
	ds_read_b128 v[200:203], v190 offset:17408
	ds_read_b128 v[204:207], v190 offset:18432
	ds_read_b128 v[208:211], v190 offset:19456
	ds_read_b128 v[212:215], v190 offset:20480
	ds_read_b128 v[216:219], v190 offset:21504
	ds_read_b128 v[220:223], v190 offset:22528
	ds_read_b128 v[224:227], v190 offset:23552
	global_load_lds_dwordx4 v154, s[60:61]
	s_add_i32 m0, s74, 0x2000
	s_add_u32 s74, s60, 0x40000
	s_addc_u32 s75, s61, 0
	s_add_i32 s76, s67, s0
	global_load_lds_dwordx4 v158, s[60:61]
	s_mov_b32 m0, s76
	s_nop 0
	global_load_lds_dwordx4 v154, s[74:75]
	s_add_i32 m0, s76, 0x2000
	s_nop 0
	global_load_lds_dwordx4 v158, s[74:75]
	s_add_u32 s100, s62, s36
	s_addc_u32 s101, s63, s37
	s_mov_b32 m0, s1
	s_nop 0
	global_load_lds_dwordx4 v152, s[62:63]
	s_mov_b32 m0, s10
	s_nop 0
	global_load_lds_dwordx4 v156, s[62:63]
	s_waitcnt vmcnt(8)
	s_waitcnt lgkmcnt(0)
	s_barrier
	s_setprio 1
	s_waitcnt lgkmcnt(0)
	v_mfma_f32_16x16x32_bf16 v[60:63], v[128:131], v[196:199], v[60:63]
	v_mfma_f32_16x16x32_bf16 v[60:63], v[132:135], v[200:203], v[60:63]
	v_mfma_f32_16x16x32_bf16 v[56:59], v[136:139], v[196:199], v[56:59]
	v_mfma_f32_16x16x32_bf16 v[56:59], v[140:143], v[200:203], v[56:59]
	v_mfma_f32_16x16x32_bf16 v[44:47], v[128:131], v[204:207], v[44:47]
	v_mfma_f32_16x16x32_bf16 v[44:47], v[132:135], v[208:211], v[44:47]
	v_mfma_f32_16x16x32_bf16 v[40:43], v[136:139], v[204:207], v[40:43]
	v_mfma_f32_16x16x32_bf16 v[40:43], v[140:143], v[208:211], v[40:43]
	v_mfma_f32_16x16x32_bf16 v[28:31], v[128:131], v[212:215], v[28:31]
	v_mfma_f32_16x16x32_bf16 v[28:31], v[132:135], v[216:219], v[28:31]
	v_mfma_f32_16x16x32_bf16 v[24:27], v[136:139], v[212:215], v[24:27]
	v_mfma_f32_16x16x32_bf16 v[24:27], v[140:143], v[216:219], v[24:27]
	v_mfma_f32_16x16x32_bf16 v[12:15], v[128:131], v[220:223], v[12:15]
	v_mfma_f32_16x16x32_bf16 v[12:15], v[132:135], v[224:227], v[12:15]
	v_mfma_f32_16x16x32_bf16 v[8:11], v[136:139], v[220:223], v[8:11]
	v_mfma_f32_16x16x32_bf16 v[8:11], v[140:143], v[224:227], v[8:11]
	s_setprio 0
	s_setprio 1
	v_mfma_f32_16x16x32_bf16 v[52:55], v[144:147], v[196:199], v[52:55]
	v_mfma_f32_16x16x32_bf16 v[52:55], v[148:151], v[200:203], v[52:55]
	v_mfma_f32_16x16x32_bf16 v[48:51], v[164:167], v[196:199], v[48:51]
	v_mfma_f32_16x16x32_bf16 v[48:51], v[192:195], v[200:203], v[48:51]
	v_mfma_f32_16x16x32_bf16 v[36:39], v[144:147], v[204:207], v[36:39]
	v_mfma_f32_16x16x32_bf16 v[36:39], v[148:151], v[208:211], v[36:39]
	v_mfma_f32_16x16x32_bf16 v[32:35], v[164:167], v[204:207], v[32:35]
	v_mfma_f32_16x16x32_bf16 v[32:35], v[192:195], v[208:211], v[32:35]
	v_mfma_f32_16x16x32_bf16 v[20:23], v[144:147], v[212:215], v[20:23]
	v_mfma_f32_16x16x32_bf16 v[20:23], v[148:151], v[216:219], v[20:23]
	v_mfma_f32_16x16x32_bf16 v[16:19], v[164:167], v[212:215], v[16:19]
	v_mfma_f32_16x16x32_bf16 v[16:19], v[192:195], v[216:219], v[16:19]
	v_mfma_f32_16x16x32_bf16 v[4:7], v[144:147], v[220:223], v[4:7]
	v_mfma_f32_16x16x32_bf16 v[4:7], v[148:151], v[224:227], v[4:7]
	v_mfma_f32_16x16x32_bf16 v[0:3], v[164:167], v[220:223], v[0:3]
	v_mfma_f32_16x16x32_bf16 v[0:3], v[192:195], v[224:227], v[0:3]
	s_setprio 0
	s_barrier
	s_add_i32 s74, 0, 0x18000
	s_add_i32 s75, 0, 0x1c000
	v_add_u32_e32 v140, s74, v171
	v_add_u32_e32 v192, s75, v171
	ds_read_b128 v[128:131], v140
	ds_read_b128 v[132:135], v140 offset:1024
	ds_read_b128 v[136:139], v140 offset:2048
	ds_read_b128 v[140:143], v140 offset:3072
	ds_read_b128 v[144:147], v192
	ds_read_b128 v[148:151], v192 offset:1024
	ds_read_b128 v[164:167], v192 offset:2048
	ds_read_b128 v[192:195], v192 offset:3072
	s_add_u32 s62, s62, 0x40000
	s_addc_u32 s63, s63, 0
	s_mov_b32 m0, s11
	ds_read_b128 v[196:199], v190 offset:32768
	ds_read_b128 v[200:203], v190 offset:33792
	ds_read_b128 v[204:207], v190 offset:34816
	ds_read_b128 v[208:211], v190 offset:35840
	ds_read_b128 v[212:215], v190 offset:36864
	ds_read_b128 v[216:219], v190 offset:37888
	ds_read_b128 v[220:223], v190 offset:38912
	ds_read_b128 v[224:227], v190 offset:39936
	global_load_lds_dwordx4 v152, s[62:63]
	s_mov_b32 m0, s14
	s_nop 0
	global_load_lds_dwordx4 v156, s[62:63]
	s_waitcnt vmcnt(8)
	s_waitcnt lgkmcnt(0)
	s_barrier
	s_setprio 1
	s_waitcnt lgkmcnt(0)
	v_mfma_f32_16x16x32_bf16 v[124:127], v[128:131], v[196:199], v[124:127]
	v_mfma_f32_16x16x32_bf16 v[124:127], v[132:135], v[200:203], v[124:127]
	v_mfma_f32_16x16x32_bf16 v[120:123], v[136:139], v[196:199], v[120:123]
	v_mfma_f32_16x16x32_bf16 v[120:123], v[140:143], v[200:203], v[120:123]
	v_mfma_f32_16x16x32_bf16 v[108:111], v[128:131], v[204:207], v[108:111]
	v_mfma_f32_16x16x32_bf16 v[108:111], v[132:135], v[208:211], v[108:111]
	v_mfma_f32_16x16x32_bf16 v[104:107], v[136:139], v[204:207], v[104:107]
	v_mfma_f32_16x16x32_bf16 v[104:107], v[140:143], v[208:211], v[104:107]
	v_mfma_f32_16x16x32_bf16 v[92:95], v[128:131], v[212:215], v[92:95]
	v_mfma_f32_16x16x32_bf16 v[92:95], v[132:135], v[216:219], v[92:95]
	v_mfma_f32_16x16x32_bf16 v[88:91], v[136:139], v[212:215], v[88:91]
	v_mfma_f32_16x16x32_bf16 v[88:91], v[140:143], v[216:219], v[88:91]
	v_mfma_f32_16x16x32_bf16 v[76:79], v[128:131], v[220:223], v[76:79]
	v_mfma_f32_16x16x32_bf16 v[76:79], v[132:135], v[224:227], v[76:79]
	v_mfma_f32_16x16x32_bf16 v[72:75], v[136:139], v[220:223], v[72:75]
	v_mfma_f32_16x16x32_bf16 v[72:75], v[140:143], v[224:227], v[72:75]
	s_setprio 0
	s_setprio 1
	v_mfma_f32_16x16x32_bf16 v[116:119], v[144:147], v[196:199], v[116:119]
	v_mfma_f32_16x16x32_bf16 v[116:119], v[148:151], v[200:203], v[116:119]
	v_mfma_f32_16x16x32_bf16 v[112:115], v[164:167], v[196:199], v[112:115]
	v_mfma_f32_16x16x32_bf16 v[112:115], v[192:195], v[200:203], v[112:115]
	v_mfma_f32_16x16x32_bf16 v[100:103], v[144:147], v[204:207], v[100:103]
	v_mfma_f32_16x16x32_bf16 v[100:103], v[148:151], v[208:211], v[100:103]
	v_mfma_f32_16x16x32_bf16 v[96:99], v[164:167], v[204:207], v[96:99]
	v_mfma_f32_16x16x32_bf16 v[96:99], v[192:195], v[208:211], v[96:99]
	v_mfma_f32_16x16x32_bf16 v[84:87], v[144:147], v[212:215], v[84:87]
	v_mfma_f32_16x16x32_bf16 v[84:87], v[148:151], v[216:219], v[84:87]
	v_mfma_f32_16x16x32_bf16 v[80:83], v[164:167], v[212:215], v[80:83]
	v_mfma_f32_16x16x32_bf16 v[80:83], v[192:195], v[216:219], v[80:83]
	v_mfma_f32_16x16x32_bf16 v[68:71], v[144:147], v[220:223], v[68:71]
	v_mfma_f32_16x16x32_bf16 v[68:71], v[148:151], v[224:227], v[68:71]
	v_mfma_f32_16x16x32_bf16 v[64:67], v[164:167], v[220:223], v[64:67]
	v_mfma_f32_16x16x32_bf16 v[64:67], v[192:195], v[224:227], v[64:67]
	s_setprio 0
	s_barrier
	s_add_i32 s62, s74, s0
	s_mov_b32 m0, s62
	ds_read_b128 v[196:199], v190 offset:49152
	ds_read_b128 v[200:203], v190 offset:50176
	ds_read_b128 v[204:207], v190 offset:51200
	ds_read_b128 v[208:211], v190 offset:52224
	ds_read_b128 v[212:215], v190 offset:53248
	ds_read_b128 v[216:219], v190 offset:54272
	ds_read_b128 v[220:223], v190 offset:55296
	ds_read_b128 v[224:227], v190 offset:56320
	global_load_lds_dwordx4 v154, s[98:99]
	s_add_i32 m0, s62, 0x2000
	s_add_u32 s60, s60, 0x40080
	s_addc_u32 s61, s61, 0
	s_add_i32 s62, s75, s0
	global_load_lds_dwordx4 v158, s[98:99]
	s_mov_b32 m0, s62
	s_nop 0
	global_load_lds_dwordx4 v154, s[60:61]
	s_add_i32 m0, s62, 0x2000
	s_nop 0
	global_load_lds_dwordx4 v158, s[60:61]
	s_mov_b32 m0, s15
	s_nop 0
	global_load_lds_dwordx4 v152, s[100:101]
	s_mov_b32 m0, s33
	s_nop 0
	global_load_lds_dwordx4 v156, s[100:101]
	s_waitcnt vmcnt(8)
	s_waitcnt lgkmcnt(0)
	s_barrier
	s_setprio 1
	s_waitcnt lgkmcnt(0)
	v_mfma_f32_16x16x32_bf16 v[60:63], v[128:131], v[196:199], v[60:63]
	v_mfma_f32_16x16x32_bf16 v[60:63], v[132:135], v[200:203], v[60:63]
	v_mfma_f32_16x16x32_bf16 v[56:59], v[136:139], v[196:199], v[56:59]
	v_mfma_f32_16x16x32_bf16 v[56:59], v[140:143], v[200:203], v[56:59]
	v_mfma_f32_16x16x32_bf16 v[44:47], v[128:131], v[204:207], v[44:47]
	v_mfma_f32_16x16x32_bf16 v[44:47], v[132:135], v[208:211], v[44:47]
	v_mfma_f32_16x16x32_bf16 v[40:43], v[136:139], v[204:207], v[40:43]
	v_mfma_f32_16x16x32_bf16 v[40:43], v[140:143], v[208:211], v[40:43]
	v_mfma_f32_16x16x32_bf16 v[28:31], v[128:131], v[212:215], v[28:31]
	v_mfma_f32_16x16x32_bf16 v[28:31], v[132:135], v[216:219], v[28:31]
	v_mfma_f32_16x16x32_bf16 v[24:27], v[136:139], v[212:215], v[24:27]
	v_mfma_f32_16x16x32_bf16 v[24:27], v[140:143], v[216:219], v[24:27]
	v_mfma_f32_16x16x32_bf16 v[12:15], v[128:131], v[220:223], v[12:15]
	v_mfma_f32_16x16x32_bf16 v[12:15], v[132:135], v[224:227], v[12:15]
	v_mfma_f32_16x16x32_bf16 v[8:11], v[136:139], v[220:223], v[8:11]
	v_mfma_f32_16x16x32_bf16 v[8:11], v[140:143], v[224:227], v[8:11]
	s_setprio 0
	s_setprio 1
	v_mfma_f32_16x16x32_bf16 v[52:55], v[144:147], v[196:199], v[52:55]
	v_mfma_f32_16x16x32_bf16 v[52:55], v[148:151], v[200:203], v[52:55]
	v_mfma_f32_16x16x32_bf16 v[48:51], v[164:167], v[196:199], v[48:51]
	v_mfma_f32_16x16x32_bf16 v[48:51], v[192:195], v[200:203], v[48:51]
	v_mfma_f32_16x16x32_bf16 v[36:39], v[144:147], v[204:207], v[36:39]
	v_mfma_f32_16x16x32_bf16 v[36:39], v[148:151], v[208:211], v[36:39]
	v_mfma_f32_16x16x32_bf16 v[32:35], v[164:167], v[204:207], v[32:35]
	v_mfma_f32_16x16x32_bf16 v[32:35], v[192:195], v[208:211], v[32:35]
	v_mfma_f32_16x16x32_bf16 v[20:23], v[144:147], v[212:215], v[20:23]
	v_mfma_f32_16x16x32_bf16 v[20:23], v[148:151], v[216:219], v[20:23]
	v_mfma_f32_16x16x32_bf16 v[16:19], v[164:167], v[212:215], v[16:19]
	v_mfma_f32_16x16x32_bf16 v[16:19], v[192:195], v[216:219], v[16:19]
	v_mfma_f32_16x16x32_bf16 v[4:7], v[144:147], v[220:223], v[4:7]
	v_mfma_f32_16x16x32_bf16 v[4:7], v[148:151], v[224:227], v[4:7]
	v_mfma_f32_16x16x32_bf16 v[0:3], v[164:167], v[220:223], v[0:3]
	v_mfma_f32_16x16x32_bf16 v[0:3], v[192:195], v[224:227], v[0:3]
	s_setprio 0
	s_add_i32 s73, s73, 2
	s_add_u32 s50, s50, 0x100
	s_addc_u32 s51, s51, 0
	s_add_u32 s71, s71, 0x100
	s_addc_u32 s72, s72, 0
	s_cmp_gt_u32 s73, 13
	s_barrier
	s_cbranch_scc0 .LBB0_707
	s_and_b64 vcc, exec, s[38:39]
	s_cbranch_vccz .LBB0_710
	s_barrier

.LBB0_793:
	ds_read_b128 v[144:147], v153
	ds_read_b128 v[158:161], v153 offset:1024
	ds_read_b128 v[162:165], v153 offset:2048
	ds_read_b128 v[166:169], v153 offset:3072
	ds_read_b128 v[170:173], v154
	ds_read_b128 v[176:179], v154 offset:1024
	ds_read_b128 v[180:183], v154 offset:2048
	ds_read_b128 v[184:187], v154 offset:3072
	s_add_u32 s44, s42, 0xfff80080
	s_addc_u32 s45, s43, -1
	s_cmp_eq_u32 s65, 28
	s_cselect_b32 s47, s35, s45
	s_cselect_b32 s46, s61, s44
	s_cselect_b32 s45, s27, s64
	s_cselect_b32 s44, s62, s63
	s_add_u32 s100, s46, 0x80
	s_addc_u32 s101, s47, 0
	s_add_i32 m0, s10, 0xc000
	ds_read_b128 v[188:191], v155
	ds_read_b128 v[192:195], v155 offset:1024
	ds_read_b128 v[196:199], v155 offset:2048
	ds_read_b128 v[200:203], v155 offset:3072
	ds_read_b128 v[204:207], v155 offset:4096
	ds_read_b128 v[208:211], v155 offset:5120
	ds_read_b128 v[212:215], v155 offset:6144
	ds_read_b128 v[216:219], v155 offset:7168
	global_load_lds_dwordx4 v136, s[42:43]
	s_add_i32 m0, s10, 0xe000
	s_nop 0
	global_load_lds_dwordx4 v138, s[42:43]
	s_waitcnt vmcnt(8)
	s_waitcnt lgkmcnt(0)
	s_setprio 1
	s_waitcnt lgkmcnt(0)
	v_mfma_f32_16x16x32_bf16 v[124:127], v[144:147], v[188:191], v[124:127]
	v_mfma_f32_16x16x32_bf16 v[124:127], v[158:161], v[192:195], v[124:127]
	v_mfma_f32_16x16x32_bf16 v[120:123], v[166:169], v[192:195], v[120:123]
	v_mfma_f32_16x16x32_bf16 v[120:123], v[162:165], v[188:191], v[120:123]
	v_mfma_f32_16x16x32_bf16 v[104:107], v[162:165], v[196:199], v[104:107]
	v_mfma_f32_16x16x32_bf16 v[104:107], v[166:169], v[200:203], v[104:107]
	v_mfma_f32_16x16x32_bf16 v[108:111], v[158:161], v[200:203], v[108:111]
	v_mfma_f32_16x16x32_bf16 v[108:111], v[144:147], v[196:199], v[108:111]
	v_mfma_f32_16x16x32_bf16 v[92:95], v[144:147], v[204:207], v[92:95]
	v_mfma_f32_16x16x32_bf16 v[92:95], v[158:161], v[208:211], v[92:95]
	v_mfma_f32_16x16x32_bf16 v[88:91], v[166:169], v[208:211], v[88:91]
	v_mfma_f32_16x16x32_bf16 v[88:91], v[162:165], v[204:207], v[88:91]
	v_mfma_f32_16x16x32_bf16 v[72:75], v[162:165], v[212:215], v[72:75]
	v_mfma_f32_16x16x32_bf16 v[72:75], v[166:169], v[216:219], v[72:75]
	v_mfma_f32_16x16x32_bf16 v[76:79], v[158:161], v[216:219], v[76:79]
	v_mfma_f32_16x16x32_bf16 v[76:79], v[144:147], v[212:215], v[76:79]
	s_setprio 0
	s_setprio 1
	v_mfma_f32_16x16x32_bf16 v[116:119], v[170:173], v[188:191], v[116:119]
	v_mfma_f32_16x16x32_bf16 v[116:119], v[176:179], v[192:195], v[116:119]
	v_mfma_f32_16x16x32_bf16 v[112:115], v[184:187], v[192:195], v[112:115]
	v_mfma_f32_16x16x32_bf16 v[112:115], v[180:183], v[188:191], v[112:115]
	v_mfma_f32_16x16x32_bf16 v[96:99], v[180:183], v[196:199], v[96:99]
	v_mfma_f32_16x16x32_bf16 v[96:99], v[184:187], v[200:203], v[96:99]
	v_mfma_f32_16x16x32_bf16 v[100:103], v[176:179], v[200:203], v[100:103]
	v_mfma_f32_16x16x32_bf16 v[100:103], v[170:173], v[196:199], v[100:103]
	v_mfma_f32_16x16x32_bf16 v[84:87], v[170:173], v[204:207], v[84:87]
	v_mfma_f32_16x16x32_bf16 v[84:87], v[176:179], v[208:211], v[84:87]
	v_mfma_f32_16x16x32_bf16 v[80:83], v[184:187], v[208:211], v[80:83]
	v_mfma_f32_16x16x32_bf16 v[80:83], v[180:183], v[204:207], v[80:83]
	v_mfma_f32_16x16x32_bf16 v[64:67], v[180:183], v[212:215], v[64:67]
	v_mfma_f32_16x16x32_bf16 v[64:67], v[184:187], v[216:219], v[64:67]
	v_mfma_f32_16x16x32_bf16 v[68:71], v[176:179], v[216:219], v[68:71]
	v_mfma_f32_16x16x32_bf16 v[68:71], v[170:173], v[212:215], v[68:71]
	s_setprio 0
	s_barrier
	s_add_i32 s66, s49, s0
	s_mov_b32 m0, s66
	ds_read_b128 v[188:191], v155 offset:16384
	ds_read_b128 v[192:195], v155 offset:17408
	ds_read_b128 v[196:199], v155 offset:18432
	ds_read_b128 v[200:203], v155 offset:19456
	ds_read_b128 v[204:207], v155 offset:20480
	ds_read_b128 v[208:211], v155 offset:21504
	ds_read_b128 v[212:215], v155 offset:22528
	ds_read_b128 v[216:219], v155 offset:23552
	global_load_lds_dwordx4 v132, s[44:45]
	s_add_i32 m0, s66, 0x2000
	s_add_u32 s66, s44, 0x80000
	s_addc_u32 s67, s45, 0
	s_add_i32 s68, s50, s0
	global_load_lds_dwordx4 v128, s[44:45]
	s_mov_b32 m0, s68
	s_nop 0
	global_load_lds_dwordx4 v132, s[66:67]
	s_add_i32 m0, s68, 0x2000
	s_nop 0
	global_load_lds_dwordx4 v128, s[66:67]
	s_mov_b32 m0, s10
	s_nop 0
	global_load_lds_dwordx4 v134, s[46:47]
	s_mov_b32 m0, s11
	s_nop 0
	global_load_lds_dwordx4 v130, s[46:47]
	s_waitcnt vmcnt(8)
	s_waitcnt lgkmcnt(0)
	s_setprio 1
	s_waitcnt lgkmcnt(0)
	v_mfma_f32_16x16x32_bf16 v[60:63], v[144:147], v[188:191], v[60:63]
	v_mfma_f32_16x16x32_bf16 v[60:63], v[158:161], v[192:195], v[60:63]
	v_mfma_f32_16x16x32_bf16 v[56:59], v[166:169], v[192:195], v[56:59]
	v_mfma_f32_16x16x32_bf16 v[56:59], v[162:165], v[188:191], v[56:59]
	v_mfma_f32_16x16x32_bf16 v[40:43], v[162:165], v[196:199], v[40:43]
	v_mfma_f32_16x16x32_bf16 v[40:43], v[166:169], v[200:203], v[40:43]
	v_mfma_f32_16x16x32_bf16 v[44:47], v[158:161], v[200:203], v[44:47]
	v_mfma_f32_16x16x32_bf16 v[44:47], v[144:147], v[196:199], v[44:47]
	v_mfma_f32_16x16x32_bf16 v[28:31], v[144:147], v[204:207], v[28:31]
	v_mfma_f32_16x16x32_bf16 v[28:31], v[158:161], v[208:211], v[28:31]
	v_mfma_f32_16x16x32_bf16 v[24:27], v[166:169], v[208:211], v[24:27]
	v_mfma_f32_16x16x32_bf16 v[24:27], v[162:165], v[204:207], v[24:27]
	v_mfma_f32_16x16x32_bf16 v[8:11], v[162:165], v[212:215], v[8:11]
	v_mfma_f32_16x16x32_bf16 v[8:11], v[166:169], v[216:219], v[8:11]
	v_mfma_f32_16x16x32_bf16 v[12:15], v[158:161], v[216:219], v[12:15]
	v_mfma_f32_16x16x32_bf16 v[12:15], v[144:147], v[212:215], v[12:15]
	s_setprio 0
	s_setprio 1
	v_mfma_f32_16x16x32_bf16 v[52:55], v[170:173], v[188:191], v[52:55]
	v_mfma_f32_16x16x32_bf16 v[52:55], v[176:179], v[192:195], v[52:55]
	v_mfma_f32_16x16x32_bf16 v[48:51], v[184:187], v[192:195], v[48:51]
	v_mfma_f32_16x16x32_bf16 v[48:51], v[180:183], v[188:191], v[48:51]
	v_mfma_f32_16x16x32_bf16 v[32:35], v[180:183], v[196:199], v[32:35]
	v_mfma_f32_16x16x32_bf16 v[32:35], v[184:187], v[200:203], v[32:35]
	v_mfma_f32_16x16x32_bf16 v[36:39], v[176:179], v[200:203], v[36:39]
	v_mfma_f32_16x16x32_bf16 v[36:39], v[170:173], v[196:199], v[36:39]
	v_mfma_f32_16x16x32_bf16 v[20:23], v[170:173], v[204:207], v[20:23]
	v_mfma_f32_16x16x32_bf16 v[20:23], v[176:179], v[208:211], v[20:23]
	v_mfma_f32_16x16x32_bf16 v[16:19], v[184:187], v[208:211], v[16:19]
	v_mfma_f32_16x16x32_bf16 v[16:19], v[180:183], v[204:207], v[16:19]
	v_mfma_f32_16x16x32_bf16 v[0:3], v[180:183], v[212:215], v[0:3]
	v_mfma_f32_16x16x32_bf16 v[0:3], v[184:187], v[216:219], v[0:3]
	v_mfma_f32_16x16x32_bf16 v[4:7], v[176:179], v[216:219], v[4:7]
	v_mfma_f32_16x16x32_bf16 v[4:7], v[170:173], v[212:215], v[4:7]
	s_setprio 0
	s_barrier
	s_add_i32 s66, 0, 0x18000
	v_add_u32_e32 v157, s66, v151
	s_add_i32 s67, 0, 0x1c000
	ds_read_b128 v[144:147], v157
	ds_read_b128 v[158:161], v157 offset:1024
	ds_read_b128 v[162:165], v157 offset:2048
	ds_read_b128 v[166:169], v157 offset:3072
	v_add_u32_e32 v157, s67, v151
	ds_read_b128 v[170:173], v157
	ds_read_b128 v[176:179], v157 offset:1024
	ds_read_b128 v[180:183], v157 offset:2048
	ds_read_b128 v[184:187], v157 offset:3072
	s_add_u32 s46, s46, 0x80000
	s_addc_u32 s47, s47, 0
	s_mov_b32 m0, s14
	ds_read_b128 v[188:191], v155 offset:32768
	ds_read_b128 v[192:195], v155 offset:33792
	ds_read_b128 v[196:199], v155 offset:34816
	ds_read_b128 v[200:203], v155 offset:35840
	ds_read_b128 v[204:207], v155 offset:36864
	ds_read_b128 v[208:211], v155 offset:37888
	ds_read_b128 v[212:215], v155 offset:38912
	ds_read_b128 v[216:219], v155 offset:39936
	global_load_lds_dwordx4 v134, s[46:47]
	s_mov_b32 m0, s15
	s_nop 0
	global_load_lds_dwordx4 v130, s[46:47]
	s_waitcnt vmcnt(8)
	s_waitcnt lgkmcnt(0)
	s_setprio 1
	s_waitcnt lgkmcnt(0)
	v_mfma_f32_16x16x32_bf16 v[124:127], v[144:147], v[188:191], v[124:127]
	v_mfma_f32_16x16x32_bf16 v[124:127], v[158:161], v[192:195], v[124:127]
	v_mfma_f32_16x16x32_bf16 v[120:123], v[166:169], v[192:195], v[120:123]
	v_mfma_f32_16x16x32_bf16 v[120:123], v[162:165], v[188:191], v[120:123]
	v_mfma_f32_16x16x32_bf16 v[104:107], v[162:165], v[196:199], v[104:107]
	v_mfma_f32_16x16x32_bf16 v[104:107], v[166:169], v[200:203], v[104:107]
	v_mfma_f32_16x16x32_bf16 v[108:111], v[158:161], v[200:203], v[108:111]
	v_mfma_f32_16x16x32_bf16 v[108:111], v[144:147], v[196:199], v[108:111]
	v_mfma_f32_16x16x32_bf16 v[92:95], v[144:147], v[204:207], v[92:95]
	v_mfma_f32_16x16x32_bf16 v[92:95], v[158:161], v[208:211], v[92:95]
	v_mfma_f32_16x16x32_bf16 v[88:91], v[166:169], v[208:211], v[88:91]
	v_mfma_f32_16x16x32_bf16 v[88:91], v[162:165], v[204:207], v[88:91]
	v_mfma_f32_16x16x32_bf16 v[72:75], v[162:165], v[212:215], v[72:75]
	v_mfma_f32_16x16x32_bf16 v[72:75], v[166:169], v[216:219], v[72:75]
	v_mfma_f32_16x16x32_bf16 v[76:79], v[158:161], v[216:219], v[76:79]
	v_mfma_f32_16x16x32_bf16 v[76:79], v[144:147], v[212:215], v[76:79]
	s_setprio 0
	s_setprio 1
	v_mfma_f32_16x16x32_bf16 v[116:119], v[170:173], v[188:191], v[116:119]
	v_mfma_f32_16x16x32_bf16 v[116:119], v[176:179], v[192:195], v[116:119]
	v_mfma_f32_16x16x32_bf16 v[112:115], v[184:187], v[192:195], v[112:115]
	v_mfma_f32_16x16x32_bf16 v[112:115], v[180:183], v[188:191], v[112:115]
	v_mfma_f32_16x16x32_bf16 v[96:99], v[180:183], v[196:199], v[96:99]
	v_mfma_f32_16x16x32_bf16 v[96:99], v[184:187], v[200:203], v[96:99]
	v_mfma_f32_16x16x32_bf16 v[100:103], v[176:179], v[200:203], v[100:103]
	v_mfma_f32_16x16x32_bf16 v[100:103], v[170:173], v[196:199], v[100:103]
	v_mfma_f32_16x16x32_bf16 v[84:87], v[170:173], v[204:207], v[84:87]
	v_mfma_f32_16x16x32_bf16 v[84:87], v[176:179], v[208:211], v[84:87]
	v_mfma_f32_16x16x32_bf16 v[80:83], v[184:187], v[208:211], v[80:83]
	v_mfma_f32_16x16x32_bf16 v[80:83], v[180:183], v[204:207], v[80:83]
	v_mfma_f32_16x16x32_bf16 v[64:67], v[180:183], v[212:215], v[64:67]
	v_mfma_f32_16x16x32_bf16 v[64:67], v[184:187], v[216:219], v[64:67]
	v_mfma_f32_16x16x32_bf16 v[68:71], v[176:179], v[216:219], v[68:71]
	v_mfma_f32_16x16x32_bf16 v[68:71], v[170:173], v[212:215], v[68:71]
	s_setprio 0
	s_barrier
	s_add_i32 s46, s66, s0
	s_add_u32 s98, s44, 0x80
	s_addc_u32 s99, s45, 0
	s_mov_b32 m0, s46
	ds_read_b128 v[188:191], v155 offset:49152
	ds_read_b128 v[192:195], v155 offset:50176
	ds_read_b128 v[196:199], v155 offset:51200
	ds_read_b128 v[200:203], v155 offset:52224
	ds_read_b128 v[204:207], v155 offset:53248
	ds_read_b128 v[208:211], v155 offset:54272
	ds_read_b128 v[212:215], v155 offset:55296
	ds_read_b128 v[216:219], v155 offset:56320
	global_load_lds_dwordx4 v132, s[98:99]
	s_add_i32 m0, s46, 0x2000
	s_add_u32 s44, s44, 0x80080
	s_addc_u32 s45, s45, 0
	s_add_i32 s46, s67, s0
	global_load_lds_dwordx4 v128, s[98:99]
	s_mov_b32 m0, s46
	s_nop 0
	global_load_lds_dwordx4 v132, s[44:45]
	s_add_i32 m0, s46, 0x2000
	s_nop 0
	global_load_lds_dwordx4 v128, s[44:45]
	s_mov_b32 m0, s41
	s_nop 0
	global_load_lds_dwordx4 v134, s[100:101]
	s_mov_b32 m0, s48
	s_nop 0
	global_load_lds_dwordx4 v130, s[100:101]
	s_waitcnt vmcnt(8)
	s_waitcnt lgkmcnt(0)
	s_setprio 1
	s_waitcnt lgkmcnt(0)
	v_mfma_f32_16x16x32_bf16 v[60:63], v[144:147], v[188:191], v[60:63]
	v_mfma_f32_16x16x32_bf16 v[60:63], v[158:161], v[192:195], v[60:63]
	v_mfma_f32_16x16x32_bf16 v[56:59], v[166:169], v[192:195], v[56:59]
	v_mfma_f32_16x16x32_bf16 v[56:59], v[162:165], v[188:191], v[56:59]
	v_mfma_f32_16x16x32_bf16 v[40:43], v[162:165], v[196:199], v[40:43]
	v_mfma_f32_16x16x32_bf16 v[40:43], v[166:169], v[200:203], v[40:43]
	v_mfma_f32_16x16x32_bf16 v[44:47], v[158:161], v[200:203], v[44:47]
	v_mfma_f32_16x16x32_bf16 v[44:47], v[144:147], v[196:199], v[44:47]
	v_mfma_f32_16x16x32_bf16 v[28:31], v[144:147], v[204:207], v[28:31]
	v_mfma_f32_16x16x32_bf16 v[28:31], v[158:161], v[208:211], v[28:31]
	v_mfma_f32_16x16x32_bf16 v[24:27], v[166:169], v[208:211], v[24:27]
	v_mfma_f32_16x16x32_bf16 v[24:27], v[162:165], v[204:207], v[24:27]
	v_mfma_f32_16x16x32_bf16 v[8:11], v[162:165], v[212:215], v[8:11]
	v_mfma_f32_16x16x32_bf16 v[8:11], v[166:169], v[216:219], v[8:11]
	v_mfma_f32_16x16x32_bf16 v[12:15], v[158:161], v[216:219], v[12:15]
	v_mfma_f32_16x16x32_bf16 v[12:15], v[144:147], v[212:215], v[12:15]
	s_setprio 0
	s_setprio 1
	v_mfma_f32_16x16x32_bf16 v[52:55], v[170:173], v[188:191], v[52:55]
	v_mfma_f32_16x16x32_bf16 v[52:55], v[176:179], v[192:195], v[52:55]
	v_mfma_f32_16x16x32_bf16 v[48:51], v[184:187], v[192:195], v[48:51]
	v_mfma_f32_16x16x32_bf16 v[48:51], v[180:183], v[188:191], v[48:51]
	v_mfma_f32_16x16x32_bf16 v[32:35], v[180:183], v[196:199], v[32:35]
	v_mfma_f32_16x16x32_bf16 v[32:35], v[184:187], v[200:203], v[32:35]
	v_mfma_f32_16x16x32_bf16 v[36:39], v[176:179], v[200:203], v[36:39]
	v_mfma_f32_16x16x32_bf16 v[36:39], v[170:173], v[196:199], v[36:39]
	v_mfma_f32_16x16x32_bf16 v[20:23], v[170:173], v[204:207], v[20:23]
	v_mfma_f32_16x16x32_bf16 v[20:23], v[176:179], v[208:211], v[20:23]
	v_mfma_f32_16x16x32_bf16 v[16:19], v[184:187], v[208:211], v[16:19]
	v_mfma_f32_16x16x32_bf16 v[16:19], v[180:183], v[204:207], v[16:19]
	v_mfma_f32_16x16x32_bf16 v[0:3], v[180:183], v[212:215], v[0:3]
	v_mfma_f32_16x16x32_bf16 v[0:3], v[184:187], v[216:219], v[0:3]
	v_mfma_f32_16x16x32_bf16 v[4:7], v[176:179], v[216:219], v[4:7]
	v_mfma_f32_16x16x32_bf16 v[4:7], v[170:173], v[212:215], v[4:7]
	s_setprio 0
	s_add_i32 s65, s65, 2
	s_add_u32 s42, s42, 0x100
	s_addc_u32 s43, s43, 0
	s_add_u32 s63, s63, 0x100
	s_addc_u32 s64, s64, 0
	s_cmp_gt_u32 s65, 29
	s_barrier
	s_cbranch_scc0 .LBB0_793
	s_branch .Lp7_kloop_done

.LBB0_873:
	ds_read_b128 v[128:131], v192
	ds_read_b128 v[132:135], v192 offset:1024
	ds_read_b128 v[136:139], v192 offset:2048
	ds_read_b128 v[140:143], v192 offset:3072
	ds_read_b128 v[144:147], v193
	ds_read_b128 v[148:151], v193 offset:1024
	ds_read_b128 v[168:171], v193 offset:2048
	ds_read_b128 v[196:199], v193 offset:3072
	s_add_u32 s34, s26, 0x100
	s_addc_u32 s35, s27, 0
	s_cmpk_eq_i32 s51, 0x54
	s_cselect_b32 s39, s1, s35
	s_cselect_b32 s38, s0, s34
	s_cselect_b32 s37, s25, s50
	s_cselect_b32 s36, s24, s49
	v_lshl_add_u64 v[172:173], s[26:27], 0, v[160:161]
	s_add_i32 m0, s11, 0xc000
	ds_read_b128 v[200:203], v194
	ds_read_b128 v[204:207], v194 offset:1024
	ds_read_b128 v[208:211], v194 offset:2048
	ds_read_b128 v[212:215], v194 offset:3072
	ds_read_b128 v[216:219], v194 offset:4096
	ds_read_b128 v[220:223], v194 offset:5120
	ds_read_b128 v[224:227], v194 offset:6144
	ds_read_b128 v[228:231], v194 offset:7168
	global_load_lds_dwordx4 v[172:173], off
	v_lshl_add_u64 v[172:173], s[26:27], 0, v[162:163]
	s_add_i32 m0, s11, 0xe000
	s_nop 0
	global_load_lds_dwordx4 v[172:173], off
	s_waitcnt vmcnt(8)
	s_waitcnt lgkmcnt(0)
	s_barrier
	s_setprio 1
	s_waitcnt lgkmcnt(0)
	v_mfma_f32_16x16x32_bf16 v[124:127], v[128:131], v[200:203], v[124:127]
	v_mfma_f32_16x16x32_bf16 v[124:127], v[132:135], v[204:207], v[124:127]
	v_mfma_f32_16x16x32_bf16 v[120:123], v[136:139], v[200:203], v[120:123]
	v_mfma_f32_16x16x32_bf16 v[120:123], v[140:143], v[204:207], v[120:123]
	v_mfma_f32_16x16x32_bf16 v[108:111], v[128:131], v[208:211], v[108:111]
	v_mfma_f32_16x16x32_bf16 v[108:111], v[132:135], v[212:215], v[108:111]
	v_mfma_f32_16x16x32_bf16 v[104:107], v[136:139], v[208:211], v[104:107]
	v_mfma_f32_16x16x32_bf16 v[104:107], v[140:143], v[212:215], v[104:107]
	v_mfma_f32_16x16x32_bf16 v[92:95], v[128:131], v[216:219], v[92:95]
	v_mfma_f32_16x16x32_bf16 v[92:95], v[132:135], v[220:223], v[92:95]
	v_mfma_f32_16x16x32_bf16 v[88:91], v[136:139], v[216:219], v[88:91]
	v_mfma_f32_16x16x32_bf16 v[88:91], v[140:143], v[220:223], v[88:91]
	v_mfma_f32_16x16x32_bf16 v[76:79], v[128:131], v[224:227], v[76:79]
	v_mfma_f32_16x16x32_bf16 v[76:79], v[132:135], v[228:231], v[76:79]
	v_mfma_f32_16x16x32_bf16 v[72:75], v[136:139], v[224:227], v[72:75]
	v_mfma_f32_16x16x32_bf16 v[72:75], v[140:143], v[228:231], v[72:75]
	s_setprio 0
	s_setprio 1
	v_mfma_f32_16x16x32_bf16 v[116:119], v[144:147], v[200:203], v[116:119]
	v_mfma_f32_16x16x32_bf16 v[116:119], v[148:151], v[204:207], v[116:119]
	v_mfma_f32_16x16x32_bf16 v[112:115], v[168:171], v[200:203], v[112:115]
	v_mfma_f32_16x16x32_bf16 v[112:115], v[196:199], v[204:207], v[112:115]
	v_mfma_f32_16x16x32_bf16 v[100:103], v[144:147], v[208:211], v[100:103]
	v_mfma_f32_16x16x32_bf16 v[100:103], v[148:151], v[212:215], v[100:103]
	v_mfma_f32_16x16x32_bf16 v[96:99], v[168:171], v[208:211], v[96:99]
	v_mfma_f32_16x16x32_bf16 v[96:99], v[196:199], v[212:215], v[96:99]
	v_mfma_f32_16x16x32_bf16 v[84:87], v[144:147], v[216:219], v[84:87]
	v_mfma_f32_16x16x32_bf16 v[84:87], v[148:151], v[220:223], v[84:87]
	v_mfma_f32_16x16x32_bf16 v[80:83], v[168:171], v[216:219], v[80:83]
	v_mfma_f32_16x16x32_bf16 v[80:83], v[196:199], v[220:223], v[80:83]
	v_mfma_f32_16x16x32_bf16 v[68:71], v[144:147], v[224:227], v[68:71]
	v_mfma_f32_16x16x32_bf16 v[68:71], v[148:151], v[228:231], v[68:71]
	v_mfma_f32_16x16x32_bf16 v[64:67], v[168:171], v[224:227], v[64:67]
	v_mfma_f32_16x16x32_bf16 v[64:67], v[196:199], v[228:231], v[64:67]
	s_setprio 0
	s_barrier
	s_add_i32 s26, s45, s10
	v_lshl_add_u64 v[172:173], s[36:37], 0, v[154:155]
	s_mov_b32 m0, s26
	ds_read_b128 v[200:203], v194 offset:16384
	ds_read_b128 v[204:207], v194 offset:17408
	ds_read_b128 v[208:211], v194 offset:18432
	ds_read_b128 v[212:215], v194 offset:19456
	ds_read_b128 v[216:219], v194 offset:20480
	ds_read_b128 v[220:223], v194 offset:21504
	ds_read_b128 v[224:227], v194 offset:22528
	ds_read_b128 v[228:231], v194 offset:23552
	global_load_lds_dwordx4 v[172:173], off
	s_add_i32 m0, s26, 0x2000
	s_add_u32 s26, s36, 0x160000
	v_lshl_add_u64 v[232:233], s[36:37], 0, v[158:159]
	s_addc_u32 s27, s37, 0
	s_add_i32 s60, s46, s10
	global_load_lds_dwordx4 v[232:233], off
	v_lshl_add_u64 v[234:235], s[26:27], 0, v[154:155]
	s_mov_b32 m0, s60
	v_lshl_add_u64 v[236:237], s[38:39], 0, v[156:157]
	global_load_lds_dwordx4 v[234:235], off
	v_lshl_add_u64 v[234:235], s[26:27], 0, v[158:159]
	s_add_i32 m0, s60, 0x2000
	s_nop 0
	global_load_lds_dwordx4 v[234:235], off
	v_lshl_add_u64 v[234:235], s[38:39], 0, v[152:153]
	s_mov_b32 m0, s11
	s_nop 0
	global_load_lds_dwordx4 v[234:235], off
	s_mov_b32 m0, s33
	s_nop 0
	global_load_lds_dwordx4 v[236:237], off
	s_waitcnt vmcnt(8)
	s_waitcnt lgkmcnt(0)
	s_barrier
	s_setprio 1
	s_waitcnt lgkmcnt(0)
	v_mfma_f32_16x16x32_bf16 v[60:63], v[128:131], v[200:203], v[60:63]
	v_mfma_f32_16x16x32_bf16 v[60:63], v[132:135], v[204:207], v[60:63]
	v_mfma_f32_16x16x32_bf16 v[56:59], v[136:139], v[200:203], v[56:59]
	v_mfma_f32_16x16x32_bf16 v[56:59], v[140:143], v[204:207], v[56:59]
	v_mfma_f32_16x16x32_bf16 v[44:47], v[128:131], v[208:211], v[44:47]
	v_mfma_f32_16x16x32_bf16 v[44:47], v[132:135], v[212:215], v[44:47]
	v_mfma_f32_16x16x32_bf16 v[40:43], v[136:139], v[208:211], v[40:43]
	v_mfma_f32_16x16x32_bf16 v[40:43], v[140:143], v[212:215], v[40:43]
	v_mfma_f32_16x16x32_bf16 v[28:31], v[128:131], v[216:219], v[28:31]
	v_mfma_f32_16x16x32_bf16 v[28:31], v[132:135], v[220:223], v[28:31]
	v_mfma_f32_16x16x32_bf16 v[24:27], v[136:139], v[216:219], v[24:27]
	v_mfma_f32_16x16x32_bf16 v[24:27], v[140:143], v[220:223], v[24:27]
	v_mfma_f32_16x16x32_bf16 v[12:15], v[128:131], v[224:227], v[12:15]
	v_mfma_f32_16x16x32_bf16 v[12:15], v[132:135], v[228:231], v[12:15]
	v_mfma_f32_16x16x32_bf16 v[8:11], v[136:139], v[224:227], v[8:11]
	v_mfma_f32_16x16x32_bf16 v[8:11], v[140:143], v[228:231], v[8:11]
	s_setprio 0
	s_setprio 1
	v_mfma_f32_16x16x32_bf16 v[52:55], v[144:147], v[200:203], v[52:55]
	v_mfma_f32_16x16x32_bf16 v[52:55], v[148:151], v[204:207], v[52:55]
	v_mfma_f32_16x16x32_bf16 v[48:51], v[168:171], v[200:203], v[48:51]
	v_mfma_f32_16x16x32_bf16 v[48:51], v[196:199], v[204:207], v[48:51]
	v_mfma_f32_16x16x32_bf16 v[36:39], v[144:147], v[208:211], v[36:39]
	v_mfma_f32_16x16x32_bf16 v[36:39], v[148:151], v[212:215], v[36:39]
	v_mfma_f32_16x16x32_bf16 v[32:35], v[168:171], v[208:211], v[32:35]
	v_mfma_f32_16x16x32_bf16 v[32:35], v[196:199], v[212:215], v[32:35]
	v_mfma_f32_16x16x32_bf16 v[20:23], v[144:147], v[216:219], v[20:23]
	v_mfma_f32_16x16x32_bf16 v[20:23], v[148:151], v[220:223], v[20:23]
	v_mfma_f32_16x16x32_bf16 v[16:19], v[168:171], v[216:219], v[16:19]
	v_mfma_f32_16x16x32_bf16 v[16:19], v[196:199], v[220:223], v[16:19]
	v_mfma_f32_16x16x32_bf16 v[4:7], v[144:147], v[224:227], v[4:7]
	v_mfma_f32_16x16x32_bf16 v[4:7], v[148:151], v[228:231], v[4:7]
	v_mfma_f32_16x16x32_bf16 v[0:3], v[168:171], v[224:227], v[0:3]
	v_mfma_f32_16x16x32_bf16 v[0:3], v[196:199], v[228:231], v[0:3]
	s_setprio 0
	s_barrier
	s_add_i32 s60, 0, 0x18000
	s_add_i32 s61, 0, 0x1c000
	v_add_u32_e32 v140, s60, v177
	v_add_u32_e32 v196, s61, v177
	ds_read_b128 v[128:131], v140
	ds_read_b128 v[132:135], v140 offset:1024
	ds_read_b128 v[136:139], v140 offset:2048
	ds_read_b128 v[140:143], v140 offset:3072
	ds_read_b128 v[144:147], v196
	ds_read_b128 v[148:151], v196 offset:1024
	ds_read_b128 v[168:171], v196 offset:2048
	ds_read_b128 v[196:199], v196 offset:3072
	s_add_u32 s26, s38, 0x160000
	s_addc_u32 s27, s39, 0
	s_mov_b32 m0, s40
	v_lshl_add_u64 v[238:239], s[26:27], 0, v[152:153]
	ds_read_b128 v[200:203], v194 offset:32768
	ds_read_b128 v[204:207], v194 offset:33792
	ds_read_b128 v[208:211], v194 offset:34816
	ds_read_b128 v[212:215], v194 offset:35840
	ds_read_b128 v[216:219], v194 offset:36864
	ds_read_b128 v[220:223], v194 offset:37888
	ds_read_b128 v[224:227], v194 offset:38912
	ds_read_b128 v[228:231], v194 offset:39936
	global_load_lds_dwordx4 v[238:239], off
	v_lshl_add_u64 v[238:239], s[26:27], 0, v[156:157]
	s_mov_b32 m0, s41
	s_nop 0
	global_load_lds_dwordx4 v[238:239], off
	s_waitcnt vmcnt(8)
	s_waitcnt lgkmcnt(0)
	s_barrier
	s_setprio 1
	s_waitcnt lgkmcnt(0)
	v_mfma_f32_16x16x32_bf16 v[124:127], v[128:131], v[200:203], v[124:127]
	v_mfma_f32_16x16x32_bf16 v[124:127], v[132:135], v[204:207], v[124:127]
	v_mfma_f32_16x16x32_bf16 v[120:123], v[136:139], v[200:203], v[120:123]
	v_mfma_f32_16x16x32_bf16 v[120:123], v[140:143], v[204:207], v[120:123]
	v_mfma_f32_16x16x32_bf16 v[108:111], v[128:131], v[208:211], v[108:111]
	v_mfma_f32_16x16x32_bf16 v[108:111], v[132:135], v[212:215], v[108:111]
	v_mfma_f32_16x16x32_bf16 v[104:107], v[136:139], v[208:211], v[104:107]
	v_mfma_f32_16x16x32_bf16 v[104:107], v[140:143], v[212:215], v[104:107]
	v_mfma_f32_16x16x32_bf16 v[92:95], v[128:131], v[216:219], v[92:95]
	v_mfma_f32_16x16x32_bf16 v[92:95], v[132:135], v[220:223], v[92:95]
	v_mfma_f32_16x16x32_bf16 v[88:91], v[136:139], v[216:219], v[88:91]
	v_mfma_f32_16x16x32_bf16 v[88:91], v[140:143], v[220:223], v[88:91]
	v_mfma_f32_16x16x32_bf16 v[76:79], v[128:131], v[224:227], v[76:79]
	v_mfma_f32_16x16x32_bf16 v[76:79], v[132:135], v[228:231], v[76:79]
	v_mfma_f32_16x16x32_bf16 v[72:75], v[136:139], v[224:227], v[72:75]
	v_mfma_f32_16x16x32_bf16 v[72:75], v[140:143], v[228:231], v[72:75]
	s_setprio 0
	s_setprio 1
	v_mfma_f32_16x16x32_bf16 v[116:119], v[144:147], v[200:203], v[116:119]
	v_mfma_f32_16x16x32_bf16 v[116:119], v[148:151], v[204:207], v[116:119]
	v_mfma_f32_16x16x32_bf16 v[112:115], v[168:171], v[200:203], v[112:115]
	v_mfma_f32_16x16x32_bf16 v[112:115], v[196:199], v[204:207], v[112:115]
	v_mfma_f32_16x16x32_bf16 v[100:103], v[144:147], v[208:211], v[100:103]
	v_mfma_f32_16x16x32_bf16 v[100:103], v[148:151], v[212:215], v[100:103]
	v_mfma_f32_16x16x32_bf16 v[96:99], v[168:171], v[208:211], v[96:99]
	v_mfma_f32_16x16x32_bf16 v[96:99], v[196:199], v[212:215], v[96:99]
	v_mfma_f32_16x16x32_bf16 v[84:87], v[144:147], v[216:219], v[84:87]
	v_mfma_f32_16x16x32_bf16 v[84:87], v[148:151], v[220:223], v[84:87]
	v_mfma_f32_16x16x32_bf16 v[80:83], v[168:171], v[216:219], v[80:83]
	v_mfma_f32_16x16x32_bf16 v[80:83], v[196:199], v[220:223], v[80:83]
	v_mfma_f32_16x16x32_bf16 v[68:71], v[144:147], v[224:227], v[68:71]
	v_mfma_f32_16x16x32_bf16 v[68:71], v[148:151], v[228:231], v[68:71]
	v_mfma_f32_16x16x32_bf16 v[64:67], v[168:171], v[224:227], v[64:67]
	v_mfma_f32_16x16x32_bf16 v[64:67], v[196:199], v[228:231], v[64:67]
	s_setprio 0
	s_barrier
	s_add_i32 s26, s60, s10
	v_lshl_add_u64 v[172:173], v[172:173], 0, s[20:21]
	s_mov_b32 m0, s26
	ds_read_b128 v[200:203], v194 offset:49152
	ds_read_b128 v[204:207], v194 offset:50176
	ds_read_b128 v[208:211], v194 offset:51200
	ds_read_b128 v[212:215], v194 offset:52224
	ds_read_b128 v[216:219], v194 offset:53248
	ds_read_b128 v[220:223], v194 offset:54272
	ds_read_b128 v[224:227], v194 offset:55296
	ds_read_b128 v[228:231], v194 offset:56320
	global_load_lds_dwordx4 v[172:173], off
	s_add_i32 m0, s26, 0x2000
	s_add_u32 s26, s36, 0x160080
	v_lshl_add_u64 v[172:173], v[232:233], 0, s[20:21]
	s_addc_u32 s27, s37, 0
	s_add_i32 s36, s61, s10
	global_load_lds_dwordx4 v[172:173], off
	v_lshl_add_u64 v[172:173], s[26:27], 0, v[154:155]
	s_mov_b32 m0, s36
	s_nop 0
	global_load_lds_dwordx4 v[172:173], off
	v_lshl_add_u64 v[172:173], s[26:27], 0, v[158:159]
	s_add_i32 m0, s36, 0x2000
	s_nop 0
	global_load_lds_dwordx4 v[172:173], off
	v_lshl_add_u64 v[172:173], v[234:235], 0, s[20:21]
	s_mov_b32 m0, s43
	s_nop 0
	global_load_lds_dwordx4 v[172:173], off
	v_lshl_add_u64 v[172:173], v[236:237], 0, s[20:21]
	s_mov_b32 m0, s44
	s_nop 0
	global_load_lds_dwordx4 v[172:173], off
	s_waitcnt vmcnt(8)
	s_waitcnt lgkmcnt(0)
	s_barrier
	s_setprio 1
	s_waitcnt lgkmcnt(0)
	v_mfma_f32_16x16x32_bf16 v[60:63], v[128:131], v[200:203], v[60:63]
	v_mfma_f32_16x16x32_bf16 v[60:63], v[132:135], v[204:207], v[60:63]
	v_mfma_f32_16x16x32_bf16 v[56:59], v[136:139], v[200:203], v[56:59]
	v_mfma_f32_16x16x32_bf16 v[56:59], v[140:143], v[204:207], v[56:59]
	v_mfma_f32_16x16x32_bf16 v[44:47], v[128:131], v[208:211], v[44:47]
	v_mfma_f32_16x16x32_bf16 v[44:47], v[132:135], v[212:215], v[44:47]
	v_mfma_f32_16x16x32_bf16 v[40:43], v[136:139], v[208:211], v[40:43]
	v_mfma_f32_16x16x32_bf16 v[40:43], v[140:143], v[212:215], v[40:43]
	v_mfma_f32_16x16x32_bf16 v[28:31], v[128:131], v[216:219], v[28:31]
	v_mfma_f32_16x16x32_bf16 v[28:31], v[132:135], v[220:223], v[28:31]
	v_mfma_f32_16x16x32_bf16 v[24:27], v[136:139], v[216:219], v[24:27]
	v_mfma_f32_16x16x32_bf16 v[24:27], v[140:143], v[220:223], v[24:27]
	v_mfma_f32_16x16x32_bf16 v[12:15], v[128:131], v[224:227], v[12:15]
	v_mfma_f32_16x16x32_bf16 v[12:15], v[132:135], v[228:231], v[12:15]
	v_mfma_f32_16x16x32_bf16 v[8:11], v[136:139], v[224:227], v[8:11]
	v_mfma_f32_16x16x32_bf16 v[8:11], v[140:143], v[228:231], v[8:11]
	s_setprio 0
	s_setprio 1
	v_mfma_f32_16x16x32_bf16 v[52:55], v[144:147], v[200:203], v[52:55]
	v_mfma_f32_16x16x32_bf16 v[52:55], v[148:151], v[204:207], v[52:55]
	v_mfma_f32_16x16x32_bf16 v[48:51], v[168:171], v[200:203], v[48:51]
	v_mfma_f32_16x16x32_bf16 v[48:51], v[196:199], v[204:207], v[48:51]
	v_mfma_f32_16x16x32_bf16 v[36:39], v[144:147], v[208:211], v[36:39]
	v_mfma_f32_16x16x32_bf16 v[36:39], v[148:151], v[212:215], v[36:39]
	v_mfma_f32_16x16x32_bf16 v[32:35], v[168:171], v[208:211], v[32:35]
	v_mfma_f32_16x16x32_bf16 v[32:35], v[196:199], v[212:215], v[32:35]
	v_mfma_f32_16x16x32_bf16 v[20:23], v[144:147], v[216:219], v[20:23]
	v_mfma_f32_16x16x32_bf16 v[20:23], v[148:151], v[220:223], v[20:23]
	v_mfma_f32_16x16x32_bf16 v[16:19], v[168:171], v[216:219], v[16:19]
	v_mfma_f32_16x16x32_bf16 v[16:19], v[196:199], v[220:223], v[16:19]
	v_mfma_f32_16x16x32_bf16 v[4:7], v[144:147], v[224:227], v[4:7]
	v_mfma_f32_16x16x32_bf16 v[4:7], v[148:151], v[228:231], v[4:7]
	v_mfma_f32_16x16x32_bf16 v[0:3], v[168:171], v[224:227], v[0:3]
	v_mfma_f32_16x16x32_bf16 v[0:3], v[196:199], v[228:231], v[0:3]
	s_setprio 0
	s_add_i32 s51, s51, 2
	s_add_u32 s49, s49, 0x100
	s_addc_u32 s50, s50, 0
	s_cmpk_gt_u32 s51, 0x55
	s_mov_b64 s[26:27], s[34:35]
	s_barrier
	s_cbranch_scc0 .LBB0_873
	s_and_b64 vcc, exec, s[22:23]
	s_cbranch_vccz .LBB0_876
	s_barrier

.LBB0_975:
	ds_read_b128 v[132:135], v179
	ds_read_b128 v[136:139], v179 offset:1024
	ds_read_b128 v[140:143], v179 offset:2048
	ds_read_b128 v[144:147], v179 offset:3072
	ds_read_b128 v[148:151], v180
	ds_read_b128 v[166:169], v180 offset:1024
	ds_read_b128 v[170:173], v180 offset:2048
	ds_read_b128 v[174:177], v180 offset:3072
	s_add_u32 s22, s20, 0x100
	s_addc_u32 s23, s21, 0
	s_add_u32 s24, s62, s20
	s_addc_u32 s25, s63, s21
	s_cmpk_eq_i32 s64, 0x54
	s_cselect_b32 s26, s16, s24
	s_cselect_b32 s24, 0, s22
	s_cselect_b32 s27, s17, s25
	s_cselect_b32 s25, 0, s23
	s_add_u32 s24, s2, s24
	s_addc_u32 s25, s3, s25
	s_mov_b32 m0, s57
	v_lshl_add_u64 v[218:219], v[128:129], 0, s[20:21]
	ds_read_b128 v[186:189], v181
	ds_read_b128 v[190:193], v181 offset:1024
	ds_read_b128 v[194:197], v181 offset:2048
	ds_read_b128 v[198:201], v181 offset:3072
	ds_read_b128 v[202:205], v181 offset:4096
	ds_read_b128 v[206:209], v181 offset:5120
	ds_read_b128 v[210:213], v181 offset:6144
	ds_read_b128 v[214:217], v181 offset:7168
	global_load_lds_dwordx4 v[218:219], off
	v_lshl_add_u64 v[218:219], v[130:131], 0, s[20:21]
	s_mov_b32 m0, s58
	s_nop 0
	global_load_lds_dwordx4 v[218:219], off
	s_waitcnt vmcnt(8)
	s_waitcnt lgkmcnt(0)
	s_barrier
	s_setprio 1
	s_waitcnt lgkmcnt(0)
	v_mfma_f32_16x16x32_bf16 v[124:127], v[132:135], v[186:189], v[124:127]
	v_mfma_f32_16x16x32_bf16 v[124:127], v[136:139], v[190:193], v[124:127]
	v_mfma_f32_16x16x32_bf16 v[120:123], v[140:143], v[186:189], v[120:123]
	v_mfma_f32_16x16x32_bf16 v[120:123], v[144:147], v[190:193], v[120:123]
	v_mfma_f32_16x16x32_bf16 v[108:111], v[132:135], v[194:197], v[108:111]
	v_mfma_f32_16x16x32_bf16 v[108:111], v[136:139], v[198:201], v[108:111]
	v_mfma_f32_16x16x32_bf16 v[104:107], v[140:143], v[194:197], v[104:107]
	v_mfma_f32_16x16x32_bf16 v[104:107], v[144:147], v[198:201], v[104:107]
	v_mfma_f32_16x16x32_bf16 v[92:95], v[132:135], v[202:205], v[92:95]
	v_mfma_f32_16x16x32_bf16 v[92:95], v[136:139], v[206:209], v[92:95]
	v_mfma_f32_16x16x32_bf16 v[88:91], v[140:143], v[202:205], v[88:91]
	v_mfma_f32_16x16x32_bf16 v[88:91], v[144:147], v[206:209], v[88:91]
	v_mfma_f32_16x16x32_bf16 v[76:79], v[132:135], v[210:213], v[76:79]
	v_mfma_f32_16x16x32_bf16 v[76:79], v[136:139], v[214:217], v[76:79]
	v_mfma_f32_16x16x32_bf16 v[72:75], v[140:143], v[210:213], v[72:75]
	v_mfma_f32_16x16x32_bf16 v[72:75], v[144:147], v[214:217], v[72:75]
	s_setprio 0
	s_setprio 1
	v_mfma_f32_16x16x32_bf16 v[116:119], v[148:151], v[186:189], v[116:119]
	v_mfma_f32_16x16x32_bf16 v[116:119], v[166:169], v[190:193], v[116:119]
	v_mfma_f32_16x16x32_bf16 v[112:115], v[170:173], v[186:189], v[112:115]
	v_mfma_f32_16x16x32_bf16 v[112:115], v[174:177], v[190:193], v[112:115]
	v_mfma_f32_16x16x32_bf16 v[100:103], v[148:151], v[194:197], v[100:103]
	v_mfma_f32_16x16x32_bf16 v[100:103], v[166:169], v[198:201], v[100:103]
	v_mfma_f32_16x16x32_bf16 v[96:99], v[170:173], v[194:197], v[96:99]
	v_mfma_f32_16x16x32_bf16 v[96:99], v[174:177], v[198:201], v[96:99]
	v_mfma_f32_16x16x32_bf16 v[84:87], v[148:151], v[202:205], v[84:87]
	v_mfma_f32_16x16x32_bf16 v[84:87], v[166:169], v[206:209], v[84:87]
	v_mfma_f32_16x16x32_bf16 v[80:83], v[170:173], v[202:205], v[80:83]
	v_mfma_f32_16x16x32_bf16 v[80:83], v[174:177], v[206:209], v[80:83]
	v_mfma_f32_16x16x32_bf16 v[68:71], v[148:151], v[210:213], v[68:71]
	v_mfma_f32_16x16x32_bf16 v[68:71], v[166:169], v[214:217], v[68:71]
	v_mfma_f32_16x16x32_bf16 v[64:67], v[170:173], v[210:213], v[64:67]
	v_mfma_f32_16x16x32_bf16 v[64:67], v[174:177], v[214:217], v[64:67]
	s_setprio 0
	s_barrier
	s_mov_b32 m0, s59
	s_add_u32 s98, s24, s6
	s_addc_u32 s99, s25, s7
	ds_read_b128 v[186:189], v181 offset:16384
	ds_read_b128 v[190:193], v181 offset:17408
	ds_read_b128 v[194:197], v181 offset:18432
	ds_read_b128 v[198:201], v181 offset:19456
	ds_read_b128 v[202:205], v181 offset:20480
	ds_read_b128 v[206:209], v181 offset:21504
	ds_read_b128 v[210:213], v181 offset:22528
	ds_read_b128 v[214:217], v181 offset:23552
	global_load_lds_dwordx4 v154, s[24:25]
	s_add_i32 m0, s59, 0x2000
	s_add_u32 s20, s24, 0x160000
	s_addc_u32 s21, s25, 0
	s_add_i32 s65, s56, s31
	global_load_lds_dwordx4 v158, s[24:25]
	s_mov_b32 m0, s65
	s_nop 0
	global_load_lds_dwordx4 v154, s[20:21]
	s_add_i32 m0, s65, 0x2000
	s_nop 0
	global_load_lds_dwordx4 v158, s[20:21]
	s_add_u32 s100, s26, s6
	s_addc_u32 s101, s27, s7
	s_mov_b32 m0, s33
	s_nop 0
	global_load_lds_dwordx4 v152, s[26:27]
	s_mov_b32 m0, s34
	s_nop 0
	global_load_lds_dwordx4 v156, s[26:27]
	s_waitcnt vmcnt(8)
	s_waitcnt lgkmcnt(0)
	s_barrier
	s_setprio 1
	s_waitcnt lgkmcnt(0)
	v_mfma_f32_16x16x32_bf16 v[60:63], v[132:135], v[186:189], v[60:63]
	v_mfma_f32_16x16x32_bf16 v[60:63], v[136:139], v[190:193], v[60:63]
	v_mfma_f32_16x16x32_bf16 v[56:59], v[140:143], v[186:189], v[56:59]
	v_mfma_f32_16x16x32_bf16 v[56:59], v[144:147], v[190:193], v[56:59]
	v_mfma_f32_16x16x32_bf16 v[44:47], v[132:135], v[194:197], v[44:47]
	v_mfma_f32_16x16x32_bf16 v[44:47], v[136:139], v[198:201], v[44:47]
	v_mfma_f32_16x16x32_bf16 v[40:43], v[140:143], v[194:197], v[40:43]
	v_mfma_f32_16x16x32_bf16 v[40:43], v[144:147], v[198:201], v[40:43]
	v_mfma_f32_16x16x32_bf16 v[28:31], v[132:135], v[202:205], v[28:31]
	v_mfma_f32_16x16x32_bf16 v[28:31], v[136:139], v[206:209], v[28:31]
	v_mfma_f32_16x16x32_bf16 v[24:27], v[140:143], v[202:205], v[24:27]
	v_mfma_f32_16x16x32_bf16 v[24:27], v[144:147], v[206:209], v[24:27]
	v_mfma_f32_16x16x32_bf16 v[12:15], v[132:135], v[210:213], v[12:15]
	v_mfma_f32_16x16x32_bf16 v[12:15], v[136:139], v[214:217], v[12:15]
	v_mfma_f32_16x16x32_bf16 v[8:11], v[140:143], v[210:213], v[8:11]
	v_mfma_f32_16x16x32_bf16 v[8:11], v[144:147], v[214:217], v[8:11]
	s_setprio 0
	s_setprio 1
	v_mfma_f32_16x16x32_bf16 v[52:55], v[148:151], v[186:189], v[52:55]
	v_mfma_f32_16x16x32_bf16 v[52:55], v[166:169], v[190:193], v[52:55]
	v_mfma_f32_16x16x32_bf16 v[48:51], v[170:173], v[186:189], v[48:51]
	v_mfma_f32_16x16x32_bf16 v[48:51], v[174:177], v[190:193], v[48:51]
	v_mfma_f32_16x16x32_bf16 v[36:39], v[148:151], v[194:197], v[36:39]
	v_mfma_f32_16x16x32_bf16 v[36:39], v[166:169], v[198:201], v[36:39]
	v_mfma_f32_16x16x32_bf16 v[32:35], v[170:173], v[194:197], v[32:35]
	v_mfma_f32_16x16x32_bf16 v[32:35], v[174:177], v[198:201], v[32:35]
	v_mfma_f32_16x16x32_bf16 v[20:23], v[148:151], v[202:205], v[20:23]
	v_mfma_f32_16x16x32_bf16 v[20:23], v[166:169], v[206:209], v[20:23]
	v_mfma_f32_16x16x32_bf16 v[16:19], v[170:173], v[202:205], v[16:19]
	v_mfma_f32_16x16x32_bf16 v[16:19], v[174:177], v[206:209], v[16:19]
	v_mfma_f32_16x16x32_bf16 v[4:7], v[148:151], v[210:213], v[4:7]
	v_mfma_f32_16x16x32_bf16 v[4:7], v[166:169], v[214:217], v[4:7]
	v_mfma_f32_16x16x32_bf16 v[0:3], v[170:173], v[210:213], v[0:3]
	v_mfma_f32_16x16x32_bf16 v[0:3], v[174:177], v[214:217], v[0:3]
	s_setprio 0
	s_barrier
	s_add_i32 s65, 0, 0x18000
	s_add_i32 s66, 0, 0x1c000
	v_add_u32_e32 v144, s65, v178
	v_add_u32_e32 v160, s66, v178
	ds_read_b128 v[132:135], v144
	ds_read_b128 v[136:139], v144 offset:1024
	ds_read_b128 v[140:143], v144 offset:2048
	ds_read_b128 v[144:147], v144 offset:3072
	ds_read_b128 v[148:151], v160
	ds_read_b128 v[166:169], v160 offset:1024
	ds_read_b128 v[170:173], v160 offset:2048
	ds_read_b128 v[174:177], v160 offset:3072
	s_add_u32 s20, s26, 0x160000
	s_addc_u32 s21, s27, 0
	s_mov_b32 m0, s35
	ds_read_b128 v[186:189], v181 offset:32768
	ds_read_b128 v[190:193], v181 offset:33792
	ds_read_b128 v[194:197], v181 offset:34816
	ds_read_b128 v[198:201], v181 offset:35840
	ds_read_b128 v[202:205], v181 offset:36864
	ds_read_b128 v[206:209], v181 offset:37888
	ds_read_b128 v[210:213], v181 offset:38912
	ds_read_b128 v[214:217], v181 offset:39936
	global_load_lds_dwordx4 v152, s[20:21]
	s_mov_b32 m0, s36
	s_nop 0
	global_load_lds_dwordx4 v156, s[20:21]
	s_waitcnt vmcnt(8)
	s_waitcnt lgkmcnt(0)
	s_barrier
	s_setprio 1
	s_waitcnt lgkmcnt(0)
	v_mfma_f32_16x16x32_bf16 v[124:127], v[132:135], v[186:189], v[124:127]
	v_mfma_f32_16x16x32_bf16 v[124:127], v[136:139], v[190:193], v[124:127]
	v_mfma_f32_16x16x32_bf16 v[120:123], v[140:143], v[186:189], v[120:123]
	v_mfma_f32_16x16x32_bf16 v[120:123], v[144:147], v[190:193], v[120:123]
	v_mfma_f32_16x16x32_bf16 v[108:111], v[132:135], v[194:197], v[108:111]
	v_mfma_f32_16x16x32_bf16 v[108:111], v[136:139], v[198:201], v[108:111]
	v_mfma_f32_16x16x32_bf16 v[104:107], v[140:143], v[194:197], v[104:107]
	v_mfma_f32_16x16x32_bf16 v[104:107], v[144:147], v[198:201], v[104:107]
	v_mfma_f32_16x16x32_bf16 v[92:95], v[132:135], v[202:205], v[92:95]
	v_mfma_f32_16x16x32_bf16 v[92:95], v[136:139], v[206:209], v[92:95]
	v_mfma_f32_16x16x32_bf16 v[88:91], v[140:143], v[202:205], v[88:91]
	v_mfma_f32_16x16x32_bf16 v[88:91], v[144:147], v[206:209], v[88:91]
	v_mfma_f32_16x16x32_bf16 v[76:79], v[132:135], v[210:213], v[76:79]
	v_mfma_f32_16x16x32_bf16 v[76:79], v[136:139], v[214:217], v[76:79]
	v_mfma_f32_16x16x32_bf16 v[72:75], v[140:143], v[210:213], v[72:75]
	v_mfma_f32_16x16x32_bf16 v[72:75], v[144:147], v[214:217], v[72:75]
	s_setprio 0
	s_setprio 1
	v_mfma_f32_16x16x32_bf16 v[116:119], v[148:151], v[186:189], v[116:119]
	v_mfma_f32_16x16x32_bf16 v[116:119], v[166:169], v[190:193], v[116:119]
	v_mfma_f32_16x16x32_bf16 v[112:115], v[170:173], v[186:189], v[112:115]
	v_mfma_f32_16x16x32_bf16 v[112:115], v[174:177], v[190:193], v[112:115]
	v_mfma_f32_16x16x32_bf16 v[100:103], v[148:151], v[194:197], v[100:103]
	v_mfma_f32_16x16x32_bf16 v[100:103], v[166:169], v[198:201], v[100:103]
	v_mfma_f32_16x16x32_bf16 v[96:99], v[170:173], v[194:197], v[96:99]
	v_mfma_f32_16x16x32_bf16 v[96:99], v[174:177], v[198:201], v[96:99]
	v_mfma_f32_16x16x32_bf16 v[84:87], v[148:151], v[202:205], v[84:87]
	v_mfma_f32_16x16x32_bf16 v[84:87], v[166:169], v[206:209], v[84:87]
	v_mfma_f32_16x16x32_bf16 v[80:83], v[170:173], v[202:205], v[80:83]
	v_mfma_f32_16x16x32_bf16 v[80:83], v[174:177], v[206:209], v[80:83]
	v_mfma_f32_16x16x32_bf16 v[68:71], v[148:151], v[210:213], v[68:71]
	v_mfma_f32_16x16x32_bf16 v[68:71], v[166:169], v[214:217], v[68:71]
	v_mfma_f32_16x16x32_bf16 v[64:67], v[170:173], v[210:213], v[64:67]
	v_mfma_f32_16x16x32_bf16 v[64:67], v[174:177], v[214:217], v[64:67]
	s_setprio 0
	s_barrier
	s_add_i32 s20, s65, s31
	s_mov_b32 m0, s20
	ds_read_b128 v[186:189], v181 offset:49152
	ds_read_b128 v[190:193], v181 offset:50176
	ds_read_b128 v[194:197], v181 offset:51200
	ds_read_b128 v[198:201], v181 offset:52224
	ds_read_b128 v[202:205], v181 offset:53248
	ds_read_b128 v[206:209], v181 offset:54272
	ds_read_b128 v[210:213], v181 offset:55296
	ds_read_b128 v[214:217], v181 offset:56320
	global_load_lds_dwordx4 v154, s[98:99]
	s_add_i32 m0, s20, 0x2000
	s_add_u32 s20, s24, 0x160080
	s_addc_u32 s21, s25, 0
	s_add_i32 s24, s66, s31
	global_load_lds_dwordx4 v158, s[98:99]
	s_mov_b32 m0, s24
	s_nop 0
	global_load_lds_dwordx4 v154, s[20:21]
	s_add_i32 m0, s24, 0x2000
	s_nop 0
	global_load_lds_dwordx4 v158, s[20:21]
	s_mov_b32 m0, s39
	s_nop 0
	global_load_lds_dwordx4 v152, s[100:101]
	s_mov_b32 m0, s40
	s_nop 0
	global_load_lds_dwordx4 v156, s[100:101]
	s_waitcnt vmcnt(8)
	s_waitcnt lgkmcnt(0)
	s_barrier
	s_setprio 1
	s_waitcnt lgkmcnt(0)
	v_mfma_f32_16x16x32_bf16 v[60:63], v[132:135], v[186:189], v[60:63]
	v_mfma_f32_16x16x32_bf16 v[60:63], v[136:139], v[190:193], v[60:63]
	v_mfma_f32_16x16x32_bf16 v[56:59], v[140:143], v[186:189], v[56:59]
	v_mfma_f32_16x16x32_bf16 v[56:59], v[144:147], v[190:193], v[56:59]
	v_mfma_f32_16x16x32_bf16 v[44:47], v[132:135], v[194:197], v[44:47]
	v_mfma_f32_16x16x32_bf16 v[44:47], v[136:139], v[198:201], v[44:47]
	v_mfma_f32_16x16x32_bf16 v[40:43], v[140:143], v[194:197], v[40:43]
	v_mfma_f32_16x16x32_bf16 v[40:43], v[144:147], v[198:201], v[40:43]
	v_mfma_f32_16x16x32_bf16 v[28:31], v[132:135], v[202:205], v[28:31]
	v_mfma_f32_16x16x32_bf16 v[28:31], v[136:139], v[206:209], v[28:31]
	v_mfma_f32_16x16x32_bf16 v[24:27], v[140:143], v[202:205], v[24:27]
	v_mfma_f32_16x16x32_bf16 v[24:27], v[144:147], v[206:209], v[24:27]
	v_mfma_f32_16x16x32_bf16 v[12:15], v[132:135], v[210:213], v[12:15]
	v_mfma_f32_16x16x32_bf16 v[12:15], v[136:139], v[214:217], v[12:15]
	v_mfma_f32_16x16x32_bf16 v[8:11], v[140:143], v[210:213], v[8:11]
	v_mfma_f32_16x16x32_bf16 v[8:11], v[144:147], v[214:217], v[8:11]
	s_setprio 0
	s_setprio 1
	v_mfma_f32_16x16x32_bf16 v[52:55], v[148:151], v[186:189], v[52:55]
	v_mfma_f32_16x16x32_bf16 v[52:55], v[166:169], v[190:193], v[52:55]
	v_mfma_f32_16x16x32_bf16 v[48:51], v[170:173], v[186:189], v[48:51]
	v_mfma_f32_16x16x32_bf16 v[48:51], v[174:177], v[190:193], v[48:51]
	v_mfma_f32_16x16x32_bf16 v[36:39], v[148:151], v[194:197], v[36:39]
	v_mfma_f32_16x16x32_bf16 v[36:39], v[166:169], v[198:201], v[36:39]
	v_mfma_f32_16x16x32_bf16 v[32:35], v[170:173], v[194:197], v[32:35]
	v_mfma_f32_16x16x32_bf16 v[32:35], v[174:177], v[198:201], v[32:35]
	v_mfma_f32_16x16x32_bf16 v[20:23], v[148:151], v[202:205], v[20:23]
	v_mfma_f32_16x16x32_bf16 v[20:23], v[166:169], v[206:209], v[20:23]
	v_mfma_f32_16x16x32_bf16 v[16:19], v[170:173], v[202:205], v[16:19]
	v_mfma_f32_16x16x32_bf16 v[16:19], v[174:177], v[206:209], v[16:19]
	v_mfma_f32_16x16x32_bf16 v[4:7], v[148:151], v[210:213], v[4:7]
	v_mfma_f32_16x16x32_bf16 v[4:7], v[166:169], v[214:217], v[4:7]
	v_mfma_f32_16x16x32_bf16 v[0:3], v[170:173], v[210:213], v[0:3]
	v_mfma_f32_16x16x32_bf16 v[0:3], v[174:177], v[214:217], v[0:3]
	s_setprio 0
	s_add_i32 s64, s64, 2
	s_cmpk_gt_u32 s64, 0x55
	s_mov_b64 s[20:21], s[22:23]
	s_barrier
	s_cbranch_scc0 .LBB0_975
	s_and_b64 vcc, exec, s[8:9]
	s_cbranch_vccz .LBB0_978
	s_barrier
